# batched-load rewrite of the gated-merge GEMM epilogues (EpiGate pass 1/2) and of the attention epilogue tail on top of the hand-scheduled attention loop (6-slot fragment ring)
# speedup vs baseline: 1.0145x; 1.0145x over previous
.LBB0_629:
	s_lshl_b32 s30, s46, 4
	s_add_i32 s38, s1, s30
	v_readlane_b32 s30, v253, 52
	s_ashr_i32 s39, s2, 4
	v_readlane_b32 s31, v253, 53
	s_and_b64 s[30:31], s[30:31], exec
	s_cselect_b32 s39, s38, s39
	s_cselect_b32 s2, s4, s2
	s_ashr_i32 s40, s39, 3
	s_and_b32 s38, s2, 15
	s_ashr_i32 s41, s40, 31
	s_lshl_b64 s[42:43], s[40:41], 11
	v_lshl_or_b32 v0, s38, 7, v178
	v_or_b32_e32 v168, s42, v0
	v_mov_b64_e32 v[0:1], s[6:7]
	s_movk_i32 s47, 0x1100
	s_lshl_b32 s2, s39, 7
	v_mad_u64_u32 v[2:3], s[30:31], v168, s47, v[0:1]
	s_and_b32 s2, s2, 0x380
	v_mad_i32_i24 v3, s43, v242, v3
	s_lshl_b32 s30, s2, 1
	s_mov_b32 s31, s3
	v_lshl_add_u64 v[2:3], v[2:3], 0, s[30:31]
	v_lshl_add_u64 v[2:3], s[14:15], 1, v[2:3]
	v_lshl_add_u64 v[2:3], v[2:3], 0, v[192:193]
	global_load_dwordx4 v[128:131], v[2:3], off
	global_load_dwordx4 v[132:135], v[2:3], off offset:32
	global_load_dwordx4 v[136:139], v[2:3], off offset:64
	global_load_dwordx4 v[140:143], v[2:3], off offset:96
	v_lshl_add_u64 v[2:3], s[42:43], 0, v[160:161]
	v_mov_b32_e32 v169, s43
	v_mad_u64_u32 v[0:1], s[42:43], v2, s47, v[0:1]
	v_mad_i32_i24 v1, v3, s47, v1
	v_lshl_add_u64 v[0:1], v[0:1], 0, s[30:31]
	v_mov_b32_e32 v165, v193
	v_lshl_add_u64 v[170:171], v[0:1], 0, v[164:165]
	v_add_u32_e32 v2, s2, v160
	v_mov_b64_e32 v[0:1], s[10:11]
	v_mad_i64_i32 v[0:1], s[42:43], v2, s73, v[0:1]
	s_lshl_b64 s[40:41], s[40:41], 12
	v_lshl_add_u64 v[0:1], v[0:1], 0, s[40:41]
	s_mul_i32 s2, s38, 0x88000
	v_lshl_add_u64 v[172:173], v[0:1], 0, v[164:165]
	s_lshl_b32 s31, s38, 1
	s_not_b64 s[38:39], s[16:17]
	v_and_b32_e32 v34, 64, v240
	v_xor_b32_e32 v33, 32, v240
	v_add_u32_e32 v34, 64, v34
	v_cmp_lt_i32_e32 vcc, v33, v34
	s_nop 1
	v_cndmask_b32_e32 v33, v240, v33, vcc
	v_lshlrev_b32_e32 v165, 2, v33
	s_mov_b32 s42, s31
	s_add_i32 s2, s42, 0
	s_and_b32 s2, s2, 31
	s_mul_i32 s2, s2, 0x44000
	s_add_i32 m0, s5, 0
	v_lshl_add_u64 v[232:233], v[170:171], 0, s[2:3]
	v_lshl_add_u64 v[234:235], v[232:233], 0, s[18:19]
	global_load_lds_dwordx4 v[234:235], off
	s_add_i32 m0, s5, 8192
	v_lshl_add_u64 v[232:233], v[232:233], 0, s[20:21]
	global_load_lds_dwordx4 v[232:233], off
	s_add_i32 s2, s42, 1
	s_and_b32 s2, s2, 31
	s_mul_i32 s2, s2, 0x44000
	s_add_i32 m0, s5, 16384
	v_lshl_add_u64 v[232:233], v[170:171], 0, s[2:3]
	v_lshl_add_u64 v[234:235], v[232:233], 0, s[18:19]
	global_load_lds_dwordx4 v[234:235], off
	s_add_i32 m0, s5, 24576
	v_lshl_add_u64 v[232:233], v[232:233], 0, s[20:21]
	global_load_lds_dwordx4 v[232:233], off
	s_add_i32 s2, s42, 0
	s_and_b32 s2, s2, 31
	s_lshl_b32 s2, s2, 7
	s_add_i32 m0, s5, 65536
	v_lshl_add_u64 v[232:233], v[172:173], 0, s[2:3]
	global_load_lds_dwordx4 v[232:233], off
	s_add_i32 m0, s5, 73728
	v_lshl_add_u64 v[234:235], v[232:233], 0, s[22:23]
	global_load_lds_dwordx4 v[234:235], off
	s_add_i32 s2, s42, 2
	s_and_b32 s2, s2, 31
	s_mul_i32 s2, s2, 0x44000
	s_add_i32 m0, s5, 32768
	v_lshl_add_u64 v[232:233], v[170:171], 0, s[2:3]
	v_lshl_add_u64 v[234:235], v[232:233], 0, s[18:19]
	global_load_lds_dwordx4 v[234:235], off
	s_add_i32 m0, s5, 40960
	v_lshl_add_u64 v[232:233], v[232:233], 0, s[20:21]
	global_load_lds_dwordx4 v[232:233], off
	s_add_i32 s2, s42, 1
	s_and_b32 s2, s2, 31
	s_lshl_b32 s2, s2, 7
	s_add_i32 m0, s5, 81920
	v_lshl_add_u64 v[232:233], v[172:173], 0, s[2:3]
	global_load_lds_dwordx4 v[232:233], off
	s_add_i32 m0, s5, 90112
	v_lshl_add_u64 v[234:235], v[232:233], 0, s[22:23]
	global_load_lds_dwordx4 v[234:235], off
	v_mov_b32_e32 v0, 0
	v_mov_b32_e32 v1, 0
	v_mov_b32_e32 v2, 0
	v_mov_b32_e32 v3, 0
	v_mov_b32_e32 v4, 0
	v_mov_b32_e32 v5, 0
	v_mov_b32_e32 v6, 0
	v_mov_b32_e32 v7, 0
	v_mov_b32_e32 v8, 0
	v_mov_b32_e32 v9, 0
	v_mov_b32_e32 v10, 0
	v_mov_b32_e32 v11, 0
	v_mov_b32_e32 v12, 0
	v_mov_b32_e32 v13, 0
	v_mov_b32_e32 v14, 0
	v_mov_b32_e32 v15, 0
	v_mov_b32_e32 v16, 0
	v_mov_b32_e32 v17, 0
	v_mov_b32_e32 v18, 0
	v_mov_b32_e32 v19, 0
	v_mov_b32_e32 v20, 0
	v_mov_b32_e32 v21, 0
	v_mov_b32_e32 v22, 0
	v_mov_b32_e32 v23, 0
	v_mov_b32_e32 v24, 0
	v_mov_b32_e32 v25, 0
	v_mov_b32_e32 v26, 0
	v_mov_b32_e32 v27, 0
	v_mov_b32_e32 v28, 0
	v_mov_b32_e32 v29, 0
	v_mov_b32_e32 v30, 0
	v_mov_b32_e32 v31, 0
	v_mov_b32_e32 v32, 0
	v_mov_b32_e32 v33, 0
	v_mov_b32_e32 v34, 0
	v_mov_b32_e32 v35, 0
	v_mov_b32_e32 v36, 0
	v_mov_b32_e32 v37, 0
	v_mov_b32_e32 v38, 0
	v_mov_b32_e32 v39, 0
	v_mov_b32_e32 v40, 0
	v_mov_b32_e32 v41, 0
	v_mov_b32_e32 v42, 0
	v_mov_b32_e32 v43, 0
	v_mov_b32_e32 v44, 0
	v_mov_b32_e32 v45, 0
	v_mov_b32_e32 v46, 0
	v_mov_b32_e32 v47, 0
	v_mov_b32_e32 v48, 0
	v_mov_b32_e32 v49, 0
	v_mov_b32_e32 v50, 0
	v_mov_b32_e32 v51, 0
	v_mov_b32_e32 v52, 0
	v_mov_b32_e32 v53, 0
	v_mov_b32_e32 v54, 0
	v_mov_b32_e32 v55, 0
	v_mov_b32_e32 v56, 0
	v_mov_b32_e32 v57, 0
	v_mov_b32_e32 v58, 0
	v_mov_b32_e32 v59, 0
	v_mov_b32_e32 v60, 0
	v_mov_b32_e32 v61, 0
	v_mov_b32_e32 v62, 0
	v_mov_b32_e32 v63, 0
	v_mov_b32_e32 v167, 0
	v_mov_b32_e32 v175, v243
	s_waitcnt vmcnt(8)
	s_barrier
	ds_read_b128 v[96:99], v182 offset:0
	ds_read_b128 v[100:103], v182 offset:4096
	ds_read_b128 v[104:107], v183 offset:0
	ds_read_b128 v[108:111], v183 offset:4096
	ds_read_b128 v[112:115], v184 offset:0
	ds_read_b128 v[116:119], v184 offset:4096
	ds_read_b128 v[120:123], v185 offset:0
	ds_read_b128 v[124:127], v185 offset:4096
	s_waitcnt lgkmcnt(0)
	v_mfma_f32_32x32x16_bf16 v[64:79], v[96:99], v[128:131], 0
	v_mfma_f32_32x32x16_bf16 v[80:95], v[100:103], v[128:131], 0
	v_mfma_f32_32x32x16_bf16 v[64:79], v[104:107], v[132:135], v[64:79]
	v_mfma_f32_32x32x16_bf16 v[80:95], v[108:111], v[132:135], v[80:95]
	v_mfma_f32_32x32x16_bf16 v[64:79], v[112:115], v[136:139], v[64:79]
	v_mfma_f32_32x32x16_bf16 v[80:95], v[116:119], v[136:139], v[80:95]
	v_mfma_f32_32x32x16_bf16 v[64:79], v[120:123], v[140:143], v[64:79]
	v_mfma_f32_32x32x16_bf16 v[80:95], v[124:127], v[140:143], v[80:95]
	s_waitcnt vmcnt(4)
	s_barrier
	ds_read_b128 v[208:211], v182 offset:16384
	ds_read_b128 v[212:215], v182 offset:20480
	ds_read_b128 v[216:219], v183 offset:16384
	ds_read_b128 v[220:223], v183 offset:20480
	ds_read_b128 v[224:227], v184 offset:16384
	ds_read_b128 v[228:231], v184 offset:20480
	s_nop 7
	s_waitcnt lgkmcnt(5)
	v_mfma_f32_32x32x16_bf16 v[96:111], v[208:211], v[128:131], 0
	ds_read_b128 v[208:211], v185 offset:16384
	s_add_i32 s2, s42, 3
	v_max3_f32 v254, v64, v65, v66
	s_and_b32 s2, s2, 31
	v_max3_f32 v255, v80, v81, v82
	s_mul_i32 s2, s2, 0x44000
	v_max3_f32 v254, v254, v67, v68
	s_add_i32 m0, s5, 49152
	v_max3_f32 v255, v255, v83, v84
	v_lshl_add_u64 v[232:233], v[170:171], 0, s[2:3]
	v_max3_f32 v254, v254, v69, v70
	v_lshl_add_u64 v[234:235], v[232:233], 0, s[18:19]
	v_max3_f32 v255, v255, v85, v86
	global_load_lds_dwordx4 v[234:235], off
	v_max3_f32 v254, v254, v71, v72
	s_add_i32 m0, s5, 57344
	v_max3_f32 v255, v255, v87, v88
	v_lshl_add_u64 v[232:233], v[232:233], 0, s[20:21]
	v_max3_f32 v254, v254, v73, v74
	global_load_lds_dwordx4 v[232:233], off
	v_max3_f32 v255, v255, v89, v90
	s_waitcnt lgkmcnt(5)
	v_mfma_f32_32x32x16_bf16 v[112:127], v[212:215], v[128:131], 0
	ds_read_b128 v[212:215], v185 offset:20480
	s_add_i32 s2, s42, 2
	v_max3_f32 v254, v254, v75, v76
	s_and_b32 s2, s2, 31
	v_max3_f32 v255, v255, v91, v92
	s_lshl_b32 s2, s2, 7
	v_max3_f32 v254, v254, v77, v78
	s_add_i32 m0, s5, 98304
	v_max3_f32 v255, v255, v93, v94
	v_lshl_add_u64 v[232:233], v[172:173], 0, s[2:3]
	v_max3_f32 v254, v254, v79, v95
	global_load_lds_dwordx4 v[232:233], off
	v_max_f32_e32 v254, v254, v255
	s_add_i32 m0, s5, 106496
	v_mov_b32_e32 v255, v254
	v_lshl_add_u64 v[234:235], v[232:233], 0, s[22:23]
	s_nop 1
	global_load_lds_dwordx4 v[234:235], off
	v_permlane32_swap_b32_e32 v254, v255
	v_max_f32_e32 v254, v254, v255
	v_add_f32_e32 v180, 0x42800000, v175
	s_waitcnt lgkmcnt(5)
	v_mfma_f32_32x32x16_bf16 v[96:111], v[216:219], v[132:135], v[96:111]
	ds_read_b128 v[216:219], v187 offset:0
	v_cmp_gt_f32_e32 vcc, v254, v180
	s_nop 1
	v_cndmask_b32_e32 v180, v175, v254, vcc
	v_sub_f32_e32 v255, v175, v180
	v_mul_f32_e32 v255, 0x3e38aa3b, v255
	v_exp_f32_e32 v174, v255
	v_mov_b32_e32 v175, v180
	v_mul_f32_e32 v179, 0x3e38aa3b, v180
	s_waitcnt lgkmcnt(5)
	v_mfma_f32_32x32x16_bf16 v[112:127], v[220:223], v[132:135], v[112:127]
	ds_read_b128 v[220:223], v187 offset:4096
	v_fma_f32 v64, v64, s24, -v179
	v_fma_f32 v65, v65, s24, -v179
	v_fma_f32 v66, v66, s24, -v179
	v_fma_f32 v67, v67, s24, -v179
	v_fma_f32 v68, v68, s24, -v179
	v_fma_f32 v69, v69, s24, -v179
	v_fma_f32 v70, v70, s24, -v179
	v_fma_f32 v71, v71, s24, -v179
	v_exp_f32_e32 v64, v64
	v_exp_f32_e32 v65, v65
	v_exp_f32_e32 v66, v66
	v_exp_f32_e32 v67, v67
	v_exp_f32_e32 v68, v68
	v_exp_f32_e32 v69, v69
	v_exp_f32_e32 v70, v70
	v_exp_f32_e32 v71, v71
	v_add_f32_e32 v190, v64, v65
	v_add_f32_e32 v191, v66, v67
	v_add_f32_e32 v190, v190, v68
	v_add_f32_e32 v191, v191, v69
	v_add_f32_e32 v190, v190, v70
	v_add_f32_e32 v191, v191, v71
	v_cvt_pk_bf16_f32 v144, v64, v65
	s_waitcnt lgkmcnt(5)
	v_mfma_f32_32x32x16_bf16 v[96:111], v[224:227], v[136:139], v[96:111]
	ds_read_b128 v[224:227], v187 offset:8192
	v_cvt_pk_bf16_f32 v145, v66, v67
	v_cvt_pk_bf16_f32 v146, v68, v69
	v_cvt_pk_bf16_f32 v147, v70, v71
	s_waitcnt lgkmcnt(5)
	v_mfma_f32_32x32x16_bf16 v[112:127], v[228:231], v[136:139], v[112:127]
	ds_read_b128 v[228:231], v187 offset:12288
	s_waitcnt lgkmcnt(5)
	v_mfma_f32_32x32x16_bf16 v[96:111], v[208:211], v[140:143], v[96:111]
	ds_read_b128 v[208:211], v188 offset:0
	s_waitcnt lgkmcnt(5)
	v_mfma_f32_32x32x16_bf16 v[112:127], v[212:215], v[140:143], v[112:127]
	ds_read_b128 v[212:215], v188 offset:4096
	v_fma_f32 v72, v72, s24, -v179
	v_fma_f32 v73, v73, s24, -v179
	v_fma_f32 v74, v74, s24, -v179
	v_fma_f32 v75, v75, s24, -v179
	v_fma_f32 v76, v76, s24, -v179
	v_fma_f32 v77, v77, s24, -v179
	v_fma_f32 v78, v78, s24, -v179
	v_fma_f32 v79, v79, s24, -v179
	v_exp_f32_e32 v72, v72
	v_exp_f32_e32 v73, v73
	v_exp_f32_e32 v74, v74
	v_exp_f32_e32 v75, v75
	v_exp_f32_e32 v76, v76
	v_exp_f32_e32 v77, v77
	v_exp_f32_e32 v78, v78
	v_exp_f32_e32 v79, v79
	v_add_f32_e32 v190, v190, v72
	v_add_f32_e32 v191, v191, v73
	v_add_f32_e32 v190, v190, v74
	v_add_f32_e32 v191, v191, v75
	v_add_f32_e32 v190, v190, v76
	v_add_f32_e32 v191, v191, v77
	v_add_f32_e32 v190, v190, v78
	v_add_f32_e32 v191, v191, v79
	v_cvt_pk_bf16_f32 v148, v72, v73
	v_cvt_pk_bf16_f32 v149, v74, v75
	v_cvt_pk_bf16_f32 v150, v76, v77
	v_cvt_pk_bf16_f32 v151, v78, v79
	v_fma_f32 v80, v80, s24, -v179
	v_fma_f32 v81, v81, s24, -v179
	v_fma_f32 v82, v82, s24, -v179
	v_fma_f32 v83, v83, s24, -v179
	v_fma_f32 v84, v84, s24, -v179
	v_fma_f32 v85, v85, s24, -v179
	v_fma_f32 v86, v86, s24, -v179
	v_fma_f32 v87, v87, s24, -v179
	v_exp_f32_e32 v80, v80
	v_exp_f32_e32 v81, v81
	v_exp_f32_e32 v82, v82
	v_exp_f32_e32 v83, v83
	v_exp_f32_e32 v84, v84
	v_exp_f32_e32 v85, v85
	v_exp_f32_e32 v86, v86
	v_exp_f32_e32 v87, v87
	v_add_f32_e32 v190, v190, v80
	v_add_f32_e32 v191, v191, v81
	v_add_f32_e32 v190, v190, v82
	v_add_f32_e32 v191, v191, v83
	v_add_f32_e32 v190, v190, v84
	v_add_f32_e32 v191, v191, v85
	v_add_f32_e32 v190, v190, v86
	v_add_f32_e32 v191, v191, v87
	v_cvt_pk_bf16_f32 v152, v80, v81
	v_cvt_pk_bf16_f32 v153, v82, v83
	v_cvt_pk_bf16_f32 v154, v84, v85
	v_cvt_pk_bf16_f32 v155, v86, v87
	v_fma_f32 v88, v88, s24, -v179
	v_fma_f32 v89, v89, s24, -v179
	v_fma_f32 v90, v90, s24, -v179
	v_fma_f32 v91, v91, s24, -v179
	v_fma_f32 v92, v92, s24, -v179
	v_fma_f32 v93, v93, s24, -v179
	v_fma_f32 v94, v94, s24, -v179
	v_fma_f32 v95, v95, s24, -v179
	v_exp_f32_e32 v88, v88
	v_exp_f32_e32 v89, v89
	v_exp_f32_e32 v90, v90
	v_exp_f32_e32 v91, v91
	v_exp_f32_e32 v92, v92
	v_exp_f32_e32 v93, v93
	v_exp_f32_e32 v94, v94
	v_exp_f32_e32 v95, v95
	v_add_f32_e32 v190, v190, v88
	v_add_f32_e32 v191, v191, v89
	v_add_f32_e32 v190, v190, v90
	v_add_f32_e32 v191, v191, v91
	v_add_f32_e32 v190, v190, v92
	v_add_f32_e32 v191, v191, v93
	v_add_f32_e32 v190, v190, v94
	v_add_f32_e32 v191, v191, v95
	v_cvt_pk_bf16_f32 v156, v88, v89
	v_cvt_pk_bf16_f32 v157, v90, v91
	v_cvt_pk_bf16_f32 v158, v92, v93
	v_cvt_pk_bf16_f32 v159, v94, v95
	v_add_f32_e32 v190, v190, v191
	v_fma_f32 v167, v167, v174, v190
	s_add_i32 s42, s31, 1
	s_movk_i32 s47, 7
.Lattn_loop:
	s_waitcnt vmcnt(4)
	s_barrier
	s_waitcnt lgkmcnt(5)
	v_mfma_f32_32x32x16_bf16 v[48:63], v[216:219], v[144:147], v[48:63]
	ds_read_b128 v[216:219], v188 offset:8192
	s_add_i32 s2, s42, 3
	v_max3_f32 v254, v96, v97, v98
	s_and_b32 s2, s2, 31
	v_max3_f32 v255, v112, v113, v114
	s_mul_i32 s2, s2, 0x44000
	v_max3_f32 v254, v254, v99, v100
	s_add_i32 m0, s5, 0
	s_waitcnt lgkmcnt(5)
	v_mfma_f32_32x32x16_bf16 v[32:47], v[220:223], v[144:147], v[32:47]
	ds_read_b128 v[220:223], v188 offset:12288
	v_max3_f32 v255, v255, v115, v116
	v_lshl_add_u64 v[232:233], v[170:171], 0, s[2:3]
	v_max3_f32 v254, v254, v101, v102
	v_lshl_add_u64 v[234:235], v[232:233], 0, s[18:19]
	v_max3_f32 v255, v255, v117, v118
	global_load_lds_dwordx4 v[234:235], off
	v_max3_f32 v254, v254, v103, v104
	s_waitcnt lgkmcnt(5)
	v_mfma_f32_32x32x16_bf16 v[16:31], v[224:227], v[144:147], v[16:31]
	ds_read_b128 v[224:227], v186 offset:0
	s_add_i32 m0, s5, 8192
	v_max3_f32 v255, v255, v119, v120
	v_lshl_add_u64 v[232:233], v[232:233], 0, s[20:21]
	v_max3_f32 v254, v254, v105, v106
	global_load_lds_dwordx4 v[232:233], off
	v_max3_f32 v255, v255, v121, v122
	s_add_i32 s2, s42, 2
	s_waitcnt lgkmcnt(5)
	v_mfma_f32_32x32x16_bf16 v[0:15], v[228:231], v[144:147], v[0:15]
	ds_read_b128 v[228:231], v186 offset:4096
	v_max3_f32 v254, v254, v107, v108
	s_and_b32 s2, s2, 31
	v_max3_f32 v255, v255, v123, v124
	s_lshl_b32 s2, s2, 7
	v_max3_f32 v254, v254, v109, v110
	s_add_i32 m0, s5, 114688
	v_max3_f32 v255, v255, v125, v126
	s_waitcnt lgkmcnt(5)
	v_mfma_f32_32x32x16_bf16 v[48:63], v[208:211], v[148:151], v[48:63]
	ds_read_b128 v[208:211], v186 offset:8192
	v_lshl_add_u64 v[232:233], v[172:173], 0, s[2:3]
	v_max3_f32 v254, v254, v111, v127
	global_load_lds_dwordx4 v[232:233], off
	v_max_f32_e32 v254, v254, v255
	s_add_i32 m0, s5, 122880
	v_mov_b32_e32 v255, v254
	v_lshl_add_u64 v[234:235], v[232:233], 0, s[22:23]
	s_waitcnt lgkmcnt(5)
	v_mfma_f32_32x32x16_bf16 v[32:47], v[212:215], v[148:151], v[32:47]
	ds_read_b128 v[212:215], v186 offset:12288
	s_nop 1
	global_load_lds_dwordx4 v[234:235], off
	v_permlane32_swap_b32_e32 v254, v255
	v_max_f32_e32 v254, v254, v255
	v_add_f32_e32 v180, 0x42800000, v175
	v_cmp_gt_f32_e32 vcc, v254, v180
	s_nop 1
	s_waitcnt lgkmcnt(5)
	v_mfma_f32_32x32x16_bf16 v[16:31], v[216:219], v[148:151], v[16:31]
	ds_read_b128 v[216:219], v189 offset:0
	v_cndmask_b32_e32 v180, v175, v254, vcc
	v_sub_f32_e32 v255, v175, v180
	v_mul_f32_e32 v255, 0x3e38aa3b, v255
	v_exp_f32_e32 v174, v255
	v_mov_b32_e32 v175, v180
	v_mul_f32_e32 v179, 0x3e38aa3b, v180
	v_fma_f32 v96, v96, s24, -v179
	s_waitcnt lgkmcnt(5)
	v_mfma_f32_32x32x16_bf16 v[0:15], v[220:223], v[148:151], v[0:15]
	ds_read_b128 v[220:223], v189 offset:4096
	v_fma_f32 v97, v97, s24, -v179
	v_fma_f32 v98, v98, s24, -v179
	v_fma_f32 v99, v99, s24, -v179
	v_fma_f32 v100, v100, s24, -v179
	v_fma_f32 v101, v101, s24, -v179
	v_fma_f32 v102, v102, s24, -v179
	v_fma_f32 v103, v103, s24, -v179
	s_waitcnt lgkmcnt(5)
	v_mfma_f32_32x32x16_bf16 v[48:63], v[224:227], v[152:155], v[48:63]
	ds_read_b128 v[224:227], v189 offset:8192
	v_exp_f32_e32 v96, v96
	v_exp_f32_e32 v97, v97
	v_exp_f32_e32 v98, v98
	v_exp_f32_e32 v99, v99
	v_exp_f32_e32 v100, v100
	v_exp_f32_e32 v101, v101
	v_exp_f32_e32 v102, v102
	s_waitcnt lgkmcnt(5)
	v_mfma_f32_32x32x16_bf16 v[32:47], v[228:231], v[152:155], v[32:47]
	ds_read_b128 v[228:231], v189 offset:12288
	v_exp_f32_e32 v103, v103
	v_add_f32_e32 v190, v96, v97
	v_add_f32_e32 v191, v98, v99
	v_add_f32_e32 v190, v190, v100
	v_add_f32_e32 v191, v191, v101
	v_add_f32_e32 v190, v190, v102
	v_add_f32_e32 v191, v191, v103
	s_waitcnt lgkmcnt(5)
	v_mfma_f32_32x32x16_bf16 v[16:31], v[208:211], v[152:155], v[16:31]
	ds_read_b128 v[208:211], v182 offset:32768
	v_cvt_pk_bf16_f32 v144, v96, v97
	v_cvt_pk_bf16_f32 v145, v98, v99
	v_cvt_pk_bf16_f32 v146, v100, v101
	v_cvt_pk_bf16_f32 v147, v102, v103
	v_fma_f32 v104, v104, s24, -v179
	v_fma_f32 v105, v105, s24, -v179
	v_fma_f32 v106, v106, s24, -v179
	s_waitcnt lgkmcnt(5)
	v_mfma_f32_32x32x16_bf16 v[0:15], v[212:215], v[152:155], v[0:15]
	ds_read_b128 v[212:215], v182 offset:36864
	v_fma_f32 v107, v107, s24, -v179
	v_fma_f32 v108, v108, s24, -v179
	v_fma_f32 v109, v109, s24, -v179
	v_fma_f32 v110, v110, s24, -v179
	v_fma_f32 v111, v111, s24, -v179
	v_exp_f32_e32 v104, v104
	v_exp_f32_e32 v105, v105
	s_waitcnt lgkmcnt(5)
	v_mfma_f32_32x32x16_bf16 v[48:63], v[216:219], v[156:159], v[48:63]
	ds_read_b128 v[216:219], v183 offset:32768
	v_exp_f32_e32 v106, v106
	v_exp_f32_e32 v107, v107
	v_exp_f32_e32 v108, v108
	v_exp_f32_e32 v109, v109
	v_exp_f32_e32 v110, v110
	v_exp_f32_e32 v111, v111
	v_add_f32_e32 v190, v190, v104
	s_waitcnt lgkmcnt(5)
	v_mfma_f32_32x32x16_bf16 v[32:47], v[220:223], v[156:159], v[32:47]
	ds_read_b128 v[220:223], v183 offset:36864
	v_add_f32_e32 v191, v191, v105
	v_add_f32_e32 v190, v190, v106
	v_add_f32_e32 v191, v191, v107
	v_add_f32_e32 v190, v190, v108
	v_add_f32_e32 v191, v191, v109
	v_add_f32_e32 v190, v190, v110
	v_add_f32_e32 v191, v191, v111
	s_waitcnt lgkmcnt(5)
	v_mfma_f32_32x32x16_bf16 v[16:31], v[224:227], v[156:159], v[16:31]
	ds_read_b128 v[224:227], v184 offset:32768
	v_cvt_pk_bf16_f32 v148, v104, v105
	v_cvt_pk_bf16_f32 v149, v106, v107
	v_cvt_pk_bf16_f32 v150, v108, v109
	v_cvt_pk_bf16_f32 v151, v110, v111
	v_fma_f32 v112, v112, s24, -v179
	v_fma_f32 v113, v113, s24, -v179
	v_fma_f32 v114, v114, s24, -v179
	s_waitcnt lgkmcnt(5)
	v_mfma_f32_32x32x16_bf16 v[0:15], v[228:231], v[156:159], v[0:15]
	ds_read_b128 v[228:231], v184 offset:36864
	v_fma_f32 v115, v115, s24, -v179
	v_fma_f32 v116, v116, s24, -v179
	v_fma_f32 v117, v117, s24, -v179
	v_fma_f32 v118, v118, s24, -v179
	v_fma_f32 v119, v119, s24, -v179
	v_exp_f32_e32 v112, v112
	v_exp_f32_e32 v113, v113
	s_waitcnt lgkmcnt(5)
	v_mfma_f32_32x32x16_bf16 v[64:79], v[208:211], v[128:131], 0
	ds_read_b128 v[208:211], v185 offset:32768
	v_exp_f32_e32 v114, v114
	v_exp_f32_e32 v115, v115
	v_exp_f32_e32 v116, v116
	v_exp_f32_e32 v117, v117
	v_exp_f32_e32 v118, v118
	v_exp_f32_e32 v119, v119
	s_waitcnt lgkmcnt(5)
	v_mfma_f32_32x32x16_bf16 v[80:95], v[212:215], v[128:131], 0
	ds_read_b128 v[212:215], v185 offset:36864
	v_add_f32_e32 v190, v190, v112
	v_add_f32_e32 v191, v191, v113
	v_add_f32_e32 v190, v190, v114
	v_add_f32_e32 v191, v191, v115
	v_add_f32_e32 v190, v190, v116
	v_add_f32_e32 v191, v191, v117
	s_waitcnt lgkmcnt(5)
	v_mfma_f32_32x32x16_bf16 v[64:79], v[216:219], v[132:135], v[64:79]
	ds_read_b128 v[216:219], v187 offset:16384
	v_add_f32_e32 v190, v190, v118
	v_add_f32_e32 v191, v191, v119
	v_cvt_pk_bf16_f32 v152, v112, v113
	v_cvt_pk_bf16_f32 v153, v114, v115
	v_cvt_pk_bf16_f32 v154, v116, v117
	v_cvt_pk_bf16_f32 v155, v118, v119
	s_waitcnt lgkmcnt(5)
	v_mfma_f32_32x32x16_bf16 v[80:95], v[220:223], v[132:135], v[80:95]
	ds_read_b128 v[220:223], v187 offset:20480
	v_fma_f32 v120, v120, s24, -v179
	v_fma_f32 v121, v121, s24, -v179
	v_fma_f32 v122, v122, s24, -v179
	v_fma_f32 v123, v123, s24, -v179
	v_fma_f32 v124, v124, s24, -v179
	v_fma_f32 v125, v125, s24, -v179
	s_waitcnt lgkmcnt(5)
	v_mfma_f32_32x32x16_bf16 v[64:79], v[224:227], v[136:139], v[64:79]
	ds_read_b128 v[224:227], v187 offset:24576
	v_fma_f32 v126, v126, s24, -v179
	v_fma_f32 v127, v127, s24, -v179
	v_exp_f32_e32 v120, v120
	v_exp_f32_e32 v121, v121
	v_exp_f32_e32 v122, v122
	v_exp_f32_e32 v123, v123
	s_waitcnt lgkmcnt(5)
	v_mfma_f32_32x32x16_bf16 v[80:95], v[228:231], v[136:139], v[80:95]
	ds_read_b128 v[228:231], v187 offset:28672
	v_exp_f32_e32 v124, v124
	v_exp_f32_e32 v125, v125
	v_exp_f32_e32 v126, v126
	v_exp_f32_e32 v127, v127
	v_add_f32_e32 v190, v190, v120
	v_add_f32_e32 v191, v191, v121
	s_waitcnt lgkmcnt(5)
	v_mfma_f32_32x32x16_bf16 v[64:79], v[208:211], v[140:143], v[64:79]
	ds_read_b128 v[208:211], v188 offset:16384
	v_add_f32_e32 v190, v190, v122
	v_add_f32_e32 v191, v191, v123
	v_add_f32_e32 v190, v190, v124
	v_add_f32_e32 v191, v191, v125
	v_add_f32_e32 v190, v190, v126
	v_add_f32_e32 v191, v191, v127
	s_waitcnt lgkmcnt(5)
	v_mfma_f32_32x32x16_bf16 v[80:95], v[212:215], v[140:143], v[80:95]
	ds_read_b128 v[212:215], v188 offset:20480
	v_cvt_pk_bf16_f32 v156, v120, v121
	v_cvt_pk_bf16_f32 v157, v122, v123
	v_cvt_pk_bf16_f32 v158, v124, v125
	v_cvt_pk_bf16_f32 v159, v126, v127
	v_add_f32_e32 v190, v190, v191
	v_fma_f32 v167, v167, v174, v190
	s_cbranch_vccz .Lattn_noresc_L0
	s_nop 7
	s_nop 7
	v_pk_mul_f32 v[0:1], v[0:1], v[174:175] op_sel_hi:[1,0]
	v_pk_mul_f32 v[2:3], v[2:3], v[174:175] op_sel_hi:[1,0]
	v_pk_mul_f32 v[4:5], v[4:5], v[174:175] op_sel_hi:[1,0]
	v_pk_mul_f32 v[6:7], v[6:7], v[174:175] op_sel_hi:[1,0]
	v_pk_mul_f32 v[8:9], v[8:9], v[174:175] op_sel_hi:[1,0]
	v_pk_mul_f32 v[10:11], v[10:11], v[174:175] op_sel_hi:[1,0]
	v_pk_mul_f32 v[12:13], v[12:13], v[174:175] op_sel_hi:[1,0]
	v_pk_mul_f32 v[14:15], v[14:15], v[174:175] op_sel_hi:[1,0]
	v_pk_mul_f32 v[16:17], v[16:17], v[174:175] op_sel_hi:[1,0]
	v_pk_mul_f32 v[18:19], v[18:19], v[174:175] op_sel_hi:[1,0]
	v_pk_mul_f32 v[20:21], v[20:21], v[174:175] op_sel_hi:[1,0]
	v_pk_mul_f32 v[22:23], v[22:23], v[174:175] op_sel_hi:[1,0]
	v_pk_mul_f32 v[24:25], v[24:25], v[174:175] op_sel_hi:[1,0]
	v_pk_mul_f32 v[26:27], v[26:27], v[174:175] op_sel_hi:[1,0]
	v_pk_mul_f32 v[28:29], v[28:29], v[174:175] op_sel_hi:[1,0]
	v_pk_mul_f32 v[30:31], v[30:31], v[174:175] op_sel_hi:[1,0]
	v_pk_mul_f32 v[32:33], v[32:33], v[174:175] op_sel_hi:[1,0]
	v_pk_mul_f32 v[34:35], v[34:35], v[174:175] op_sel_hi:[1,0]
	v_pk_mul_f32 v[36:37], v[36:37], v[174:175] op_sel_hi:[1,0]
	v_pk_mul_f32 v[38:39], v[38:39], v[174:175] op_sel_hi:[1,0]
	v_pk_mul_f32 v[40:41], v[40:41], v[174:175] op_sel_hi:[1,0]
	v_pk_mul_f32 v[42:43], v[42:43], v[174:175] op_sel_hi:[1,0]
	v_pk_mul_f32 v[44:45], v[44:45], v[174:175] op_sel_hi:[1,0]
	v_pk_mul_f32 v[46:47], v[46:47], v[174:175] op_sel_hi:[1,0]
	v_pk_mul_f32 v[48:49], v[48:49], v[174:175] op_sel_hi:[1,0]
	v_pk_mul_f32 v[50:51], v[50:51], v[174:175] op_sel_hi:[1,0]
	v_pk_mul_f32 v[52:53], v[52:53], v[174:175] op_sel_hi:[1,0]
	v_pk_mul_f32 v[54:55], v[54:55], v[174:175] op_sel_hi:[1,0]
	v_pk_mul_f32 v[56:57], v[56:57], v[174:175] op_sel_hi:[1,0]
	v_pk_mul_f32 v[58:59], v[58:59], v[174:175] op_sel_hi:[1,0]
	v_pk_mul_f32 v[60:61], v[60:61], v[174:175] op_sel_hi:[1,0]
	v_pk_mul_f32 v[62:63], v[62:63], v[174:175] op_sel_hi:[1,0]
	s_nop 1
.Lattn_noresc_L0:
	s_waitcnt vmcnt(4)
	s_barrier
	s_waitcnt lgkmcnt(5)
	v_mfma_f32_32x32x16_bf16 v[48:63], v[216:219], v[144:147], v[48:63]
	ds_read_b128 v[216:219], v188 offset:24576
	s_add_i32 s2, s42, 4
	v_max3_f32 v254, v64, v65, v66
	s_and_b32 s2, s2, 31
	v_max3_f32 v255, v80, v81, v82
	s_mul_i32 s2, s2, 0x44000
	v_max3_f32 v254, v254, v67, v68
	s_add_i32 m0, s5, 16384
	s_waitcnt lgkmcnt(5)
	v_mfma_f32_32x32x16_bf16 v[32:47], v[220:223], v[144:147], v[32:47]
	ds_read_b128 v[220:223], v188 offset:28672
	v_max3_f32 v255, v255, v83, v84
	v_lshl_add_u64 v[232:233], v[170:171], 0, s[2:3]
	v_max3_f32 v254, v254, v69, v70
	v_lshl_add_u64 v[234:235], v[232:233], 0, s[18:19]
	v_max3_f32 v255, v255, v85, v86
	global_load_lds_dwordx4 v[234:235], off
	v_max3_f32 v254, v254, v71, v72
	s_waitcnt lgkmcnt(5)
	v_mfma_f32_32x32x16_bf16 v[16:31], v[224:227], v[144:147], v[16:31]
	ds_read_b128 v[224:227], v186 offset:16384
	s_add_i32 m0, s5, 24576
	v_max3_f32 v255, v255, v87, v88
	v_lshl_add_u64 v[232:233], v[232:233], 0, s[20:21]
	v_max3_f32 v254, v254, v73, v74
	global_load_lds_dwordx4 v[232:233], off
	v_max3_f32 v255, v255, v89, v90
	s_add_i32 s2, s42, 3
	s_waitcnt lgkmcnt(5)
	v_mfma_f32_32x32x16_bf16 v[0:15], v[228:231], v[144:147], v[0:15]
	ds_read_b128 v[228:231], v186 offset:20480
	v_max3_f32 v254, v254, v75, v76
	s_and_b32 s2, s2, 31
	v_max3_f32 v255, v255, v91, v92
	s_lshl_b32 s2, s2, 7
	v_max3_f32 v254, v254, v77, v78
	s_add_i32 m0, s5, 65536
	v_max3_f32 v255, v255, v93, v94
	s_waitcnt lgkmcnt(5)
	v_mfma_f32_32x32x16_bf16 v[48:63], v[208:211], v[148:151], v[48:63]
	ds_read_b128 v[208:211], v186 offset:24576
	v_lshl_add_u64 v[232:233], v[172:173], 0, s[2:3]
	v_max3_f32 v254, v254, v79, v95
	global_load_lds_dwordx4 v[232:233], off
	v_max_f32_e32 v254, v254, v255
	s_add_i32 m0, s5, 73728
	v_mov_b32_e32 v255, v254
	v_lshl_add_u64 v[234:235], v[232:233], 0, s[22:23]
	s_waitcnt lgkmcnt(5)
	v_mfma_f32_32x32x16_bf16 v[32:47], v[212:215], v[148:151], v[32:47]
	ds_read_b128 v[212:215], v186 offset:28672
	s_nop 1
	global_load_lds_dwordx4 v[234:235], off
	v_permlane32_swap_b32_e32 v254, v255
	v_max_f32_e32 v254, v254, v255
	v_add_f32_e32 v180, 0x42800000, v175
	v_cmp_gt_f32_e32 vcc, v254, v180
	s_nop 1
	s_waitcnt lgkmcnt(5)
	v_mfma_f32_32x32x16_bf16 v[16:31], v[216:219], v[148:151], v[16:31]
	ds_read_b128 v[216:219], v189 offset:16384
	v_cndmask_b32_e32 v180, v175, v254, vcc
	v_sub_f32_e32 v255, v175, v180
	v_mul_f32_e32 v255, 0x3e38aa3b, v255
	v_exp_f32_e32 v174, v255
	v_mov_b32_e32 v175, v180
	v_mul_f32_e32 v179, 0x3e38aa3b, v180
	v_fma_f32 v64, v64, s24, -v179
	s_waitcnt lgkmcnt(5)
	v_mfma_f32_32x32x16_bf16 v[0:15], v[220:223], v[148:151], v[0:15]
	ds_read_b128 v[220:223], v189 offset:20480
	v_fma_f32 v65, v65, s24, -v179
	v_fma_f32 v66, v66, s24, -v179
	v_fma_f32 v67, v67, s24, -v179
	v_fma_f32 v68, v68, s24, -v179
	v_fma_f32 v69, v69, s24, -v179
	v_fma_f32 v70, v70, s24, -v179
	v_fma_f32 v71, v71, s24, -v179
	s_waitcnt lgkmcnt(5)
	v_mfma_f32_32x32x16_bf16 v[48:63], v[224:227], v[152:155], v[48:63]
	ds_read_b128 v[224:227], v189 offset:24576
	v_exp_f32_e32 v64, v64
	v_exp_f32_e32 v65, v65
	v_exp_f32_e32 v66, v66
	v_exp_f32_e32 v67, v67
	v_exp_f32_e32 v68, v68
	v_exp_f32_e32 v69, v69
	v_exp_f32_e32 v70, v70
	s_waitcnt lgkmcnt(5)
	v_mfma_f32_32x32x16_bf16 v[32:47], v[228:231], v[152:155], v[32:47]
	ds_read_b128 v[228:231], v189 offset:28672
	v_exp_f32_e32 v71, v71
	v_add_f32_e32 v190, v64, v65
	v_add_f32_e32 v191, v66, v67
	v_add_f32_e32 v190, v190, v68
	v_add_f32_e32 v191, v191, v69
	v_add_f32_e32 v190, v190, v70
	v_add_f32_e32 v191, v191, v71
	s_waitcnt lgkmcnt(5)
	v_mfma_f32_32x32x16_bf16 v[16:31], v[208:211], v[152:155], v[16:31]
	ds_read_b128 v[208:211], v182 offset:49152
	v_cvt_pk_bf16_f32 v144, v64, v65
	v_cvt_pk_bf16_f32 v145, v66, v67
	v_cvt_pk_bf16_f32 v146, v68, v69
	v_cvt_pk_bf16_f32 v147, v70, v71
	v_fma_f32 v72, v72, s24, -v179
	v_fma_f32 v73, v73, s24, -v179
	v_fma_f32 v74, v74, s24, -v179
	s_waitcnt lgkmcnt(5)
	v_mfma_f32_32x32x16_bf16 v[0:15], v[212:215], v[152:155], v[0:15]
	ds_read_b128 v[212:215], v182 offset:53248
	v_fma_f32 v75, v75, s24, -v179
	v_fma_f32 v76, v76, s24, -v179
	v_fma_f32 v77, v77, s24, -v179
	v_fma_f32 v78, v78, s24, -v179
	v_fma_f32 v79, v79, s24, -v179
	v_exp_f32_e32 v72, v72
	v_exp_f32_e32 v73, v73
	s_waitcnt lgkmcnt(5)
	v_mfma_f32_32x32x16_bf16 v[48:63], v[216:219], v[156:159], v[48:63]
	ds_read_b128 v[216:219], v183 offset:49152
	v_exp_f32_e32 v74, v74
	v_exp_f32_e32 v75, v75
	v_exp_f32_e32 v76, v76
	v_exp_f32_e32 v77, v77
	v_exp_f32_e32 v78, v78
	v_exp_f32_e32 v79, v79
	v_add_f32_e32 v190, v190, v72
	s_waitcnt lgkmcnt(5)
	v_mfma_f32_32x32x16_bf16 v[32:47], v[220:223], v[156:159], v[32:47]
	ds_read_b128 v[220:223], v183 offset:53248
	v_add_f32_e32 v191, v191, v73
	v_add_f32_e32 v190, v190, v74
	v_add_f32_e32 v191, v191, v75
	v_add_f32_e32 v190, v190, v76
	v_add_f32_e32 v191, v191, v77
	v_add_f32_e32 v190, v190, v78
	v_add_f32_e32 v191, v191, v79
	s_waitcnt lgkmcnt(5)
	v_mfma_f32_32x32x16_bf16 v[16:31], v[224:227], v[156:159], v[16:31]
	ds_read_b128 v[224:227], v184 offset:49152
	v_cvt_pk_bf16_f32 v148, v72, v73
	v_cvt_pk_bf16_f32 v149, v74, v75
	v_cvt_pk_bf16_f32 v150, v76, v77
	v_cvt_pk_bf16_f32 v151, v78, v79
	v_fma_f32 v80, v80, s24, -v179
	v_fma_f32 v81, v81, s24, -v179
	v_fma_f32 v82, v82, s24, -v179
	s_waitcnt lgkmcnt(5)
	v_mfma_f32_32x32x16_bf16 v[0:15], v[228:231], v[156:159], v[0:15]
	ds_read_b128 v[228:231], v184 offset:53248
	v_fma_f32 v83, v83, s24, -v179
	v_fma_f32 v84, v84, s24, -v179
	v_fma_f32 v85, v85, s24, -v179
	v_fma_f32 v86, v86, s24, -v179
	v_fma_f32 v87, v87, s24, -v179
	v_exp_f32_e32 v80, v80
	v_exp_f32_e32 v81, v81
	s_waitcnt lgkmcnt(5)
	v_mfma_f32_32x32x16_bf16 v[96:111], v[208:211], v[128:131], 0
	ds_read_b128 v[208:211], v185 offset:49152
	v_exp_f32_e32 v82, v82
	v_exp_f32_e32 v83, v83
	v_exp_f32_e32 v84, v84
	v_exp_f32_e32 v85, v85
	v_exp_f32_e32 v86, v86
	v_exp_f32_e32 v87, v87
	s_waitcnt lgkmcnt(5)
	v_mfma_f32_32x32x16_bf16 v[112:127], v[212:215], v[128:131], 0
	ds_read_b128 v[212:215], v185 offset:53248
	v_add_f32_e32 v190, v190, v80
	v_add_f32_e32 v191, v191, v81
	v_add_f32_e32 v190, v190, v82
	v_add_f32_e32 v191, v191, v83
	v_add_f32_e32 v190, v190, v84
	v_add_f32_e32 v191, v191, v85
	s_waitcnt lgkmcnt(5)
	v_mfma_f32_32x32x16_bf16 v[96:111], v[216:219], v[132:135], v[96:111]
	ds_read_b128 v[216:219], v187 offset:32768
	v_add_f32_e32 v190, v190, v86
	v_add_f32_e32 v191, v191, v87
	v_cvt_pk_bf16_f32 v152, v80, v81
	v_cvt_pk_bf16_f32 v153, v82, v83
	v_cvt_pk_bf16_f32 v154, v84, v85
	v_cvt_pk_bf16_f32 v155, v86, v87
	s_waitcnt lgkmcnt(5)
	v_mfma_f32_32x32x16_bf16 v[112:127], v[220:223], v[132:135], v[112:127]
	ds_read_b128 v[220:223], v187 offset:36864
	v_fma_f32 v88, v88, s24, -v179
	v_fma_f32 v89, v89, s24, -v179
	v_fma_f32 v90, v90, s24, -v179
	v_fma_f32 v91, v91, s24, -v179
	v_fma_f32 v92, v92, s24, -v179
	v_fma_f32 v93, v93, s24, -v179
	s_waitcnt lgkmcnt(5)
	v_mfma_f32_32x32x16_bf16 v[96:111], v[224:227], v[136:139], v[96:111]
	ds_read_b128 v[224:227], v187 offset:40960
	v_fma_f32 v94, v94, s24, -v179
	v_fma_f32 v95, v95, s24, -v179
	v_exp_f32_e32 v88, v88
	v_exp_f32_e32 v89, v89
	v_exp_f32_e32 v90, v90
	v_exp_f32_e32 v91, v91
	s_waitcnt lgkmcnt(5)
	v_mfma_f32_32x32x16_bf16 v[112:127], v[228:231], v[136:139], v[112:127]
	ds_read_b128 v[228:231], v187 offset:45056
	v_exp_f32_e32 v92, v92
	v_exp_f32_e32 v93, v93
	v_exp_f32_e32 v94, v94
	v_exp_f32_e32 v95, v95
	v_add_f32_e32 v190, v190, v88
	v_add_f32_e32 v191, v191, v89
	s_waitcnt lgkmcnt(5)
	v_mfma_f32_32x32x16_bf16 v[96:111], v[208:211], v[140:143], v[96:111]
	ds_read_b128 v[208:211], v188 offset:32768
	v_add_f32_e32 v190, v190, v90
	v_add_f32_e32 v191, v191, v91
	v_add_f32_e32 v190, v190, v92
	v_add_f32_e32 v191, v191, v93
	v_add_f32_e32 v190, v190, v94
	v_add_f32_e32 v191, v191, v95
	s_waitcnt lgkmcnt(5)
	v_mfma_f32_32x32x16_bf16 v[112:127], v[212:215], v[140:143], v[112:127]
	ds_read_b128 v[212:215], v188 offset:36864
	v_cvt_pk_bf16_f32 v156, v88, v89
	v_cvt_pk_bf16_f32 v157, v90, v91
	v_cvt_pk_bf16_f32 v158, v92, v93
	v_cvt_pk_bf16_f32 v159, v94, v95
	v_add_f32_e32 v190, v190, v191
	v_fma_f32 v167, v167, v174, v190
	s_cbranch_vccz .Lattn_noresc_L1
	s_nop 7
	s_nop 7
	v_pk_mul_f32 v[0:1], v[0:1], v[174:175] op_sel_hi:[1,0]
	v_pk_mul_f32 v[2:3], v[2:3], v[174:175] op_sel_hi:[1,0]
	v_pk_mul_f32 v[4:5], v[4:5], v[174:175] op_sel_hi:[1,0]
	v_pk_mul_f32 v[6:7], v[6:7], v[174:175] op_sel_hi:[1,0]
	v_pk_mul_f32 v[8:9], v[8:9], v[174:175] op_sel_hi:[1,0]
	v_pk_mul_f32 v[10:11], v[10:11], v[174:175] op_sel_hi:[1,0]
	v_pk_mul_f32 v[12:13], v[12:13], v[174:175] op_sel_hi:[1,0]
	v_pk_mul_f32 v[14:15], v[14:15], v[174:175] op_sel_hi:[1,0]
	v_pk_mul_f32 v[16:17], v[16:17], v[174:175] op_sel_hi:[1,0]
	v_pk_mul_f32 v[18:19], v[18:19], v[174:175] op_sel_hi:[1,0]
	v_pk_mul_f32 v[20:21], v[20:21], v[174:175] op_sel_hi:[1,0]
	v_pk_mul_f32 v[22:23], v[22:23], v[174:175] op_sel_hi:[1,0]
	v_pk_mul_f32 v[24:25], v[24:25], v[174:175] op_sel_hi:[1,0]
	v_pk_mul_f32 v[26:27], v[26:27], v[174:175] op_sel_hi:[1,0]
	v_pk_mul_f32 v[28:29], v[28:29], v[174:175] op_sel_hi:[1,0]
	v_pk_mul_f32 v[30:31], v[30:31], v[174:175] op_sel_hi:[1,0]
	v_pk_mul_f32 v[32:33], v[32:33], v[174:175] op_sel_hi:[1,0]
	v_pk_mul_f32 v[34:35], v[34:35], v[174:175] op_sel_hi:[1,0]
	v_pk_mul_f32 v[36:37], v[36:37], v[174:175] op_sel_hi:[1,0]
	v_pk_mul_f32 v[38:39], v[38:39], v[174:175] op_sel_hi:[1,0]
	v_pk_mul_f32 v[40:41], v[40:41], v[174:175] op_sel_hi:[1,0]
	v_pk_mul_f32 v[42:43], v[42:43], v[174:175] op_sel_hi:[1,0]
	v_pk_mul_f32 v[44:45], v[44:45], v[174:175] op_sel_hi:[1,0]
	v_pk_mul_f32 v[46:47], v[46:47], v[174:175] op_sel_hi:[1,0]
	v_pk_mul_f32 v[48:49], v[48:49], v[174:175] op_sel_hi:[1,0]
	v_pk_mul_f32 v[50:51], v[50:51], v[174:175] op_sel_hi:[1,0]
	v_pk_mul_f32 v[52:53], v[52:53], v[174:175] op_sel_hi:[1,0]
	v_pk_mul_f32 v[54:55], v[54:55], v[174:175] op_sel_hi:[1,0]
	v_pk_mul_f32 v[56:57], v[56:57], v[174:175] op_sel_hi:[1,0]
	v_pk_mul_f32 v[58:59], v[58:59], v[174:175] op_sel_hi:[1,0]
	v_pk_mul_f32 v[60:61], v[60:61], v[174:175] op_sel_hi:[1,0]
	v_pk_mul_f32 v[62:63], v[62:63], v[174:175] op_sel_hi:[1,0]
	s_nop 1
.Lattn_noresc_L1:
	s_waitcnt vmcnt(4)
	s_barrier
	s_waitcnt lgkmcnt(5)
	v_mfma_f32_32x32x16_bf16 v[48:63], v[216:219], v[144:147], v[48:63]
	ds_read_b128 v[216:219], v188 offset:40960
	s_add_i32 s2, s42, 5
	v_max3_f32 v254, v96, v97, v98
	s_and_b32 s2, s2, 31
	v_max3_f32 v255, v112, v113, v114
	s_mul_i32 s2, s2, 0x44000
	v_max3_f32 v254, v254, v99, v100
	s_add_i32 m0, s5, 32768
	s_waitcnt lgkmcnt(5)
	v_mfma_f32_32x32x16_bf16 v[32:47], v[220:223], v[144:147], v[32:47]
	ds_read_b128 v[220:223], v188 offset:45056
	v_max3_f32 v255, v255, v115, v116
	v_lshl_add_u64 v[232:233], v[170:171], 0, s[2:3]
	v_max3_f32 v254, v254, v101, v102
	v_lshl_add_u64 v[234:235], v[232:233], 0, s[18:19]
	v_max3_f32 v255, v255, v117, v118
	global_load_lds_dwordx4 v[234:235], off
	v_max3_f32 v254, v254, v103, v104
	s_waitcnt lgkmcnt(5)
	v_mfma_f32_32x32x16_bf16 v[16:31], v[224:227], v[144:147], v[16:31]
	ds_read_b128 v[224:227], v186 offset:32768
	s_add_i32 m0, s5, 40960
	v_max3_f32 v255, v255, v119, v120
	v_lshl_add_u64 v[232:233], v[232:233], 0, s[20:21]
	v_max3_f32 v254, v254, v105, v106
	global_load_lds_dwordx4 v[232:233], off
	v_max3_f32 v255, v255, v121, v122
	s_add_i32 s2, s42, 4
	s_waitcnt lgkmcnt(5)
	v_mfma_f32_32x32x16_bf16 v[0:15], v[228:231], v[144:147], v[0:15]
	ds_read_b128 v[228:231], v186 offset:36864
	v_max3_f32 v254, v254, v107, v108
	s_and_b32 s2, s2, 31
	v_max3_f32 v255, v255, v123, v124
	s_lshl_b32 s2, s2, 7
	v_max3_f32 v254, v254, v109, v110
	s_add_i32 m0, s5, 81920
	v_max3_f32 v255, v255, v125, v126
	s_waitcnt lgkmcnt(5)
	v_mfma_f32_32x32x16_bf16 v[48:63], v[208:211], v[148:151], v[48:63]
	ds_read_b128 v[208:211], v186 offset:40960
	v_lshl_add_u64 v[232:233], v[172:173], 0, s[2:3]
	v_max3_f32 v254, v254, v111, v127
	global_load_lds_dwordx4 v[232:233], off
	v_max_f32_e32 v254, v254, v255
	s_add_i32 m0, s5, 90112
	v_mov_b32_e32 v255, v254
	v_lshl_add_u64 v[234:235], v[232:233], 0, s[22:23]
	s_waitcnt lgkmcnt(5)
	v_mfma_f32_32x32x16_bf16 v[32:47], v[212:215], v[148:151], v[32:47]
	ds_read_b128 v[212:215], v186 offset:45056
	s_nop 1
	global_load_lds_dwordx4 v[234:235], off
	v_permlane32_swap_b32_e32 v254, v255
	v_max_f32_e32 v254, v254, v255
	v_add_f32_e32 v180, 0x42800000, v175
	v_cmp_gt_f32_e32 vcc, v254, v180
	s_nop 1
	s_waitcnt lgkmcnt(5)
	v_mfma_f32_32x32x16_bf16 v[16:31], v[216:219], v[148:151], v[16:31]
	ds_read_b128 v[216:219], v189 offset:32768
	v_cndmask_b32_e32 v180, v175, v254, vcc
	v_sub_f32_e32 v255, v175, v180
	v_mul_f32_e32 v255, 0x3e38aa3b, v255
	v_exp_f32_e32 v174, v255
	v_mov_b32_e32 v175, v180
	v_mul_f32_e32 v179, 0x3e38aa3b, v180
	v_fma_f32 v96, v96, s24, -v179
	s_waitcnt lgkmcnt(5)
	v_mfma_f32_32x32x16_bf16 v[0:15], v[220:223], v[148:151], v[0:15]
	ds_read_b128 v[220:223], v189 offset:36864
	v_fma_f32 v97, v97, s24, -v179
	v_fma_f32 v98, v98, s24, -v179
	v_fma_f32 v99, v99, s24, -v179
	v_fma_f32 v100, v100, s24, -v179
	v_fma_f32 v101, v101, s24, -v179
	v_fma_f32 v102, v102, s24, -v179
	v_fma_f32 v103, v103, s24, -v179
	s_waitcnt lgkmcnt(5)
	v_mfma_f32_32x32x16_bf16 v[48:63], v[224:227], v[152:155], v[48:63]
	ds_read_b128 v[224:227], v189 offset:40960
	v_exp_f32_e32 v96, v96
	v_exp_f32_e32 v97, v97
	v_exp_f32_e32 v98, v98
	v_exp_f32_e32 v99, v99
	v_exp_f32_e32 v100, v100
	v_exp_f32_e32 v101, v101
	v_exp_f32_e32 v102, v102
	s_waitcnt lgkmcnt(5)
	v_mfma_f32_32x32x16_bf16 v[32:47], v[228:231], v[152:155], v[32:47]
	ds_read_b128 v[228:231], v189 offset:45056
	v_exp_f32_e32 v103, v103
	v_add_f32_e32 v190, v96, v97
	v_add_f32_e32 v191, v98, v99
	v_add_f32_e32 v190, v190, v100
	v_add_f32_e32 v191, v191, v101
	v_add_f32_e32 v190, v190, v102
	v_add_f32_e32 v191, v191, v103
	s_waitcnt lgkmcnt(5)
	v_mfma_f32_32x32x16_bf16 v[16:31], v[208:211], v[152:155], v[16:31]
	ds_read_b128 v[208:211], v182 offset:0
	v_cvt_pk_bf16_f32 v144, v96, v97
	v_cvt_pk_bf16_f32 v145, v98, v99
	v_cvt_pk_bf16_f32 v146, v100, v101
	v_cvt_pk_bf16_f32 v147, v102, v103
	v_fma_f32 v104, v104, s24, -v179
	v_fma_f32 v105, v105, s24, -v179
	v_fma_f32 v106, v106, s24, -v179
	s_waitcnt lgkmcnt(5)
	v_mfma_f32_32x32x16_bf16 v[0:15], v[212:215], v[152:155], v[0:15]
	ds_read_b128 v[212:215], v182 offset:4096
	v_fma_f32 v107, v107, s24, -v179
	v_fma_f32 v108, v108, s24, -v179
	v_fma_f32 v109, v109, s24, -v179
	v_fma_f32 v110, v110, s24, -v179
	v_fma_f32 v111, v111, s24, -v179
	v_exp_f32_e32 v104, v104
	v_exp_f32_e32 v105, v105
	s_waitcnt lgkmcnt(5)
	v_mfma_f32_32x32x16_bf16 v[48:63], v[216:219], v[156:159], v[48:63]
	ds_read_b128 v[216:219], v183 offset:0
	v_exp_f32_e32 v106, v106
	v_exp_f32_e32 v107, v107
	v_exp_f32_e32 v108, v108
	v_exp_f32_e32 v109, v109
	v_exp_f32_e32 v110, v110
	v_exp_f32_e32 v111, v111
	v_add_f32_e32 v190, v190, v104
	s_waitcnt lgkmcnt(5)
	v_mfma_f32_32x32x16_bf16 v[32:47], v[220:223], v[156:159], v[32:47]
	ds_read_b128 v[220:223], v183 offset:4096
	v_add_f32_e32 v191, v191, v105
	v_add_f32_e32 v190, v190, v106
	v_add_f32_e32 v191, v191, v107
	v_add_f32_e32 v190, v190, v108
	v_add_f32_e32 v191, v191, v109
	v_add_f32_e32 v190, v190, v110
	v_add_f32_e32 v191, v191, v111
	s_waitcnt lgkmcnt(5)
	v_mfma_f32_32x32x16_bf16 v[16:31], v[224:227], v[156:159], v[16:31]
	ds_read_b128 v[224:227], v184 offset:0
	v_cvt_pk_bf16_f32 v148, v104, v105
	v_cvt_pk_bf16_f32 v149, v106, v107
	v_cvt_pk_bf16_f32 v150, v108, v109
	v_cvt_pk_bf16_f32 v151, v110, v111
	v_fma_f32 v112, v112, s24, -v179
	v_fma_f32 v113, v113, s24, -v179
	v_fma_f32 v114, v114, s24, -v179
	s_waitcnt lgkmcnt(5)
	v_mfma_f32_32x32x16_bf16 v[0:15], v[228:231], v[156:159], v[0:15]
	ds_read_b128 v[228:231], v184 offset:4096
	v_fma_f32 v115, v115, s24, -v179
	v_fma_f32 v116, v116, s24, -v179
	v_fma_f32 v117, v117, s24, -v179
	v_fma_f32 v118, v118, s24, -v179
	v_fma_f32 v119, v119, s24, -v179
	v_exp_f32_e32 v112, v112
	v_exp_f32_e32 v113, v113
	s_waitcnt lgkmcnt(5)
	v_mfma_f32_32x32x16_bf16 v[64:79], v[208:211], v[128:131], 0
	ds_read_b128 v[208:211], v185 offset:0
	v_exp_f32_e32 v114, v114
	v_exp_f32_e32 v115, v115
	v_exp_f32_e32 v116, v116
	v_exp_f32_e32 v117, v117
	v_exp_f32_e32 v118, v118
	v_exp_f32_e32 v119, v119
	s_waitcnt lgkmcnt(5)
	v_mfma_f32_32x32x16_bf16 v[80:95], v[212:215], v[128:131], 0
	ds_read_b128 v[212:215], v185 offset:4096
	v_add_f32_e32 v190, v190, v112
	v_add_f32_e32 v191, v191, v113
	v_add_f32_e32 v190, v190, v114
	v_add_f32_e32 v191, v191, v115
	v_add_f32_e32 v190, v190, v116
	v_add_f32_e32 v191, v191, v117
	s_waitcnt lgkmcnt(5)
	v_mfma_f32_32x32x16_bf16 v[64:79], v[216:219], v[132:135], v[64:79]
	ds_read_b128 v[216:219], v187 offset:49152
	v_add_f32_e32 v190, v190, v118
	v_add_f32_e32 v191, v191, v119
	v_cvt_pk_bf16_f32 v152, v112, v113
	v_cvt_pk_bf16_f32 v153, v114, v115
	v_cvt_pk_bf16_f32 v154, v116, v117
	v_cvt_pk_bf16_f32 v155, v118, v119
	s_waitcnt lgkmcnt(5)
	v_mfma_f32_32x32x16_bf16 v[80:95], v[220:223], v[132:135], v[80:95]
	ds_read_b128 v[220:223], v187 offset:53248
	v_fma_f32 v120, v120, s24, -v179
	v_fma_f32 v121, v121, s24, -v179
	v_fma_f32 v122, v122, s24, -v179
	v_fma_f32 v123, v123, s24, -v179
	v_fma_f32 v124, v124, s24, -v179
	v_fma_f32 v125, v125, s24, -v179
	s_waitcnt lgkmcnt(5)
	v_mfma_f32_32x32x16_bf16 v[64:79], v[224:227], v[136:139], v[64:79]
	ds_read_b128 v[224:227], v187 offset:57344
	v_fma_f32 v126, v126, s24, -v179
	v_fma_f32 v127, v127, s24, -v179
	v_exp_f32_e32 v120, v120
	v_exp_f32_e32 v121, v121
	v_exp_f32_e32 v122, v122
	v_exp_f32_e32 v123, v123
	s_waitcnt lgkmcnt(5)
	v_mfma_f32_32x32x16_bf16 v[80:95], v[228:231], v[136:139], v[80:95]
	ds_read_b128 v[228:231], v187 offset:61440
	v_exp_f32_e32 v124, v124
	v_exp_f32_e32 v125, v125
	v_exp_f32_e32 v126, v126
	v_exp_f32_e32 v127, v127
	v_add_f32_e32 v190, v190, v120
	v_add_f32_e32 v191, v191, v121
	s_waitcnt lgkmcnt(5)
	v_mfma_f32_32x32x16_bf16 v[64:79], v[208:211], v[140:143], v[64:79]
	ds_read_b128 v[208:211], v188 offset:49152
	v_add_f32_e32 v190, v190, v122
	v_add_f32_e32 v191, v191, v123
	v_add_f32_e32 v190, v190, v124
	v_add_f32_e32 v191, v191, v125
	v_add_f32_e32 v190, v190, v126
	v_add_f32_e32 v191, v191, v127
	s_waitcnt lgkmcnt(5)
	v_mfma_f32_32x32x16_bf16 v[80:95], v[212:215], v[140:143], v[80:95]
	ds_read_b128 v[212:215], v188 offset:53248
	v_cvt_pk_bf16_f32 v156, v120, v121
	v_cvt_pk_bf16_f32 v157, v122, v123
	v_cvt_pk_bf16_f32 v158, v124, v125
	v_cvt_pk_bf16_f32 v159, v126, v127
	v_add_f32_e32 v190, v190, v191
	v_fma_f32 v167, v167, v174, v190
	s_cbranch_vccz .Lattn_noresc_L2
	s_nop 7
	s_nop 7
	v_pk_mul_f32 v[0:1], v[0:1], v[174:175] op_sel_hi:[1,0]
	v_pk_mul_f32 v[2:3], v[2:3], v[174:175] op_sel_hi:[1,0]
	v_pk_mul_f32 v[4:5], v[4:5], v[174:175] op_sel_hi:[1,0]
	v_pk_mul_f32 v[6:7], v[6:7], v[174:175] op_sel_hi:[1,0]
	v_pk_mul_f32 v[8:9], v[8:9], v[174:175] op_sel_hi:[1,0]
	v_pk_mul_f32 v[10:11], v[10:11], v[174:175] op_sel_hi:[1,0]
	v_pk_mul_f32 v[12:13], v[12:13], v[174:175] op_sel_hi:[1,0]
	v_pk_mul_f32 v[14:15], v[14:15], v[174:175] op_sel_hi:[1,0]
	v_pk_mul_f32 v[16:17], v[16:17], v[174:175] op_sel_hi:[1,0]
	v_pk_mul_f32 v[18:19], v[18:19], v[174:175] op_sel_hi:[1,0]
	v_pk_mul_f32 v[20:21], v[20:21], v[174:175] op_sel_hi:[1,0]
	v_pk_mul_f32 v[22:23], v[22:23], v[174:175] op_sel_hi:[1,0]
	v_pk_mul_f32 v[24:25], v[24:25], v[174:175] op_sel_hi:[1,0]
	v_pk_mul_f32 v[26:27], v[26:27], v[174:175] op_sel_hi:[1,0]
	v_pk_mul_f32 v[28:29], v[28:29], v[174:175] op_sel_hi:[1,0]
	v_pk_mul_f32 v[30:31], v[30:31], v[174:175] op_sel_hi:[1,0]
	v_pk_mul_f32 v[32:33], v[32:33], v[174:175] op_sel_hi:[1,0]
	v_pk_mul_f32 v[34:35], v[34:35], v[174:175] op_sel_hi:[1,0]
	v_pk_mul_f32 v[36:37], v[36:37], v[174:175] op_sel_hi:[1,0]
	v_pk_mul_f32 v[38:39], v[38:39], v[174:175] op_sel_hi:[1,0]
	v_pk_mul_f32 v[40:41], v[40:41], v[174:175] op_sel_hi:[1,0]
	v_pk_mul_f32 v[42:43], v[42:43], v[174:175] op_sel_hi:[1,0]
	v_pk_mul_f32 v[44:45], v[44:45], v[174:175] op_sel_hi:[1,0]
	v_pk_mul_f32 v[46:47], v[46:47], v[174:175] op_sel_hi:[1,0]
	v_pk_mul_f32 v[48:49], v[48:49], v[174:175] op_sel_hi:[1,0]
	v_pk_mul_f32 v[50:51], v[50:51], v[174:175] op_sel_hi:[1,0]
	v_pk_mul_f32 v[52:53], v[52:53], v[174:175] op_sel_hi:[1,0]
	v_pk_mul_f32 v[54:55], v[54:55], v[174:175] op_sel_hi:[1,0]
	v_pk_mul_f32 v[56:57], v[56:57], v[174:175] op_sel_hi:[1,0]
	v_pk_mul_f32 v[58:59], v[58:59], v[174:175] op_sel_hi:[1,0]
	v_pk_mul_f32 v[60:61], v[60:61], v[174:175] op_sel_hi:[1,0]
	v_pk_mul_f32 v[62:63], v[62:63], v[174:175] op_sel_hi:[1,0]
	s_nop 1
.Lattn_noresc_L2:
	s_waitcnt vmcnt(4)
	s_barrier
	s_waitcnt lgkmcnt(5)
	v_mfma_f32_32x32x16_bf16 v[48:63], v[216:219], v[144:147], v[48:63]
	ds_read_b128 v[216:219], v188 offset:57344
	s_add_i32 s2, s42, 6
	v_max3_f32 v254, v64, v65, v66
	s_and_b32 s2, s2, 31
	v_max3_f32 v255, v80, v81, v82
	s_mul_i32 s2, s2, 0x44000
	v_max3_f32 v254, v254, v67, v68
	s_add_i32 m0, s5, 49152
	s_waitcnt lgkmcnt(5)
	v_mfma_f32_32x32x16_bf16 v[32:47], v[220:223], v[144:147], v[32:47]
	ds_read_b128 v[220:223], v188 offset:61440
	v_max3_f32 v255, v255, v83, v84
	v_lshl_add_u64 v[232:233], v[170:171], 0, s[2:3]
	v_max3_f32 v254, v254, v69, v70
	v_lshl_add_u64 v[234:235], v[232:233], 0, s[18:19]
	v_max3_f32 v255, v255, v85, v86
	global_load_lds_dwordx4 v[234:235], off
	v_max3_f32 v254, v254, v71, v72
	s_waitcnt lgkmcnt(5)
	v_mfma_f32_32x32x16_bf16 v[16:31], v[224:227], v[144:147], v[16:31]
	ds_read_b128 v[224:227], v186 offset:49152
	s_add_i32 m0, s5, 57344
	v_max3_f32 v255, v255, v87, v88
	v_lshl_add_u64 v[232:233], v[232:233], 0, s[20:21]
	v_max3_f32 v254, v254, v73, v74
	global_load_lds_dwordx4 v[232:233], off
	v_max3_f32 v255, v255, v89, v90
	s_add_i32 s2, s42, 5
	s_waitcnt lgkmcnt(5)
	v_mfma_f32_32x32x16_bf16 v[0:15], v[228:231], v[144:147], v[0:15]
	ds_read_b128 v[228:231], v186 offset:53248
	v_max3_f32 v254, v254, v75, v76
	s_and_b32 s2, s2, 31
	v_max3_f32 v255, v255, v91, v92
	s_lshl_b32 s2, s2, 7
	v_max3_f32 v254, v254, v77, v78
	s_add_i32 m0, s5, 98304
	v_max3_f32 v255, v255, v93, v94
	s_waitcnt lgkmcnt(5)
	v_mfma_f32_32x32x16_bf16 v[48:63], v[208:211], v[148:151], v[48:63]
	ds_read_b128 v[208:211], v186 offset:57344
	v_lshl_add_u64 v[232:233], v[172:173], 0, s[2:3]
	v_max3_f32 v254, v254, v79, v95
	global_load_lds_dwordx4 v[232:233], off
	v_max_f32_e32 v254, v254, v255
	s_add_i32 m0, s5, 106496
	v_mov_b32_e32 v255, v254
	v_lshl_add_u64 v[234:235], v[232:233], 0, s[22:23]
	s_waitcnt lgkmcnt(5)
	v_mfma_f32_32x32x16_bf16 v[32:47], v[212:215], v[148:151], v[32:47]
	ds_read_b128 v[212:215], v186 offset:61440
	s_nop 1
	global_load_lds_dwordx4 v[234:235], off
	v_permlane32_swap_b32_e32 v254, v255
	v_max_f32_e32 v254, v254, v255
	v_add_f32_e32 v180, 0x42800000, v175
	v_cmp_gt_f32_e32 vcc, v254, v180
	s_nop 1
	s_waitcnt lgkmcnt(5)
	v_mfma_f32_32x32x16_bf16 v[16:31], v[216:219], v[148:151], v[16:31]
	ds_read_b128 v[216:219], v189 offset:49152
	v_cndmask_b32_e32 v180, v175, v254, vcc
	v_sub_f32_e32 v255, v175, v180
	v_mul_f32_e32 v255, 0x3e38aa3b, v255
	v_exp_f32_e32 v174, v255
	v_mov_b32_e32 v175, v180
	v_mul_f32_e32 v179, 0x3e38aa3b, v180
	v_fma_f32 v64, v64, s24, -v179
	s_waitcnt lgkmcnt(5)
	v_mfma_f32_32x32x16_bf16 v[0:15], v[220:223], v[148:151], v[0:15]
	ds_read_b128 v[220:223], v189 offset:53248
	v_fma_f32 v65, v65, s24, -v179
	v_fma_f32 v66, v66, s24, -v179
	v_fma_f32 v67, v67, s24, -v179
	v_fma_f32 v68, v68, s24, -v179
	v_fma_f32 v69, v69, s24, -v179
	v_fma_f32 v70, v70, s24, -v179
	v_fma_f32 v71, v71, s24, -v179
	s_waitcnt lgkmcnt(5)
	v_mfma_f32_32x32x16_bf16 v[48:63], v[224:227], v[152:155], v[48:63]
	ds_read_b128 v[224:227], v189 offset:57344
	v_exp_f32_e32 v64, v64
	v_exp_f32_e32 v65, v65
	v_exp_f32_e32 v66, v66
	v_exp_f32_e32 v67, v67
	v_exp_f32_e32 v68, v68
	v_exp_f32_e32 v69, v69
	v_exp_f32_e32 v70, v70
	s_waitcnt lgkmcnt(5)
	v_mfma_f32_32x32x16_bf16 v[32:47], v[228:231], v[152:155], v[32:47]
	ds_read_b128 v[228:231], v189 offset:61440
	v_exp_f32_e32 v71, v71
	v_add_f32_e32 v190, v64, v65
	v_add_f32_e32 v191, v66, v67
	v_add_f32_e32 v190, v190, v68
	v_add_f32_e32 v191, v191, v69
	v_add_f32_e32 v190, v190, v70
	v_add_f32_e32 v191, v191, v71
	s_waitcnt lgkmcnt(5)
	v_mfma_f32_32x32x16_bf16 v[16:31], v[208:211], v[152:155], v[16:31]
	ds_read_b128 v[208:211], v182 offset:16384
	v_cvt_pk_bf16_f32 v144, v64, v65
	v_cvt_pk_bf16_f32 v145, v66, v67
	v_cvt_pk_bf16_f32 v146, v68, v69
	v_cvt_pk_bf16_f32 v147, v70, v71
	v_fma_f32 v72, v72, s24, -v179
	v_fma_f32 v73, v73, s24, -v179
	v_fma_f32 v74, v74, s24, -v179
	s_waitcnt lgkmcnt(5)
	v_mfma_f32_32x32x16_bf16 v[0:15], v[212:215], v[152:155], v[0:15]
	ds_read_b128 v[212:215], v182 offset:20480
	v_fma_f32 v75, v75, s24, -v179
	v_fma_f32 v76, v76, s24, -v179
	v_fma_f32 v77, v77, s24, -v179
	v_fma_f32 v78, v78, s24, -v179
	v_fma_f32 v79, v79, s24, -v179
	v_exp_f32_e32 v72, v72
	v_exp_f32_e32 v73, v73
	s_waitcnt lgkmcnt(5)
	v_mfma_f32_32x32x16_bf16 v[48:63], v[216:219], v[156:159], v[48:63]
	ds_read_b128 v[216:219], v183 offset:16384
	v_exp_f32_e32 v74, v74
	v_exp_f32_e32 v75, v75
	v_exp_f32_e32 v76, v76
	v_exp_f32_e32 v77, v77
	v_exp_f32_e32 v78, v78
	v_exp_f32_e32 v79, v79
	v_add_f32_e32 v190, v190, v72
	s_waitcnt lgkmcnt(5)
	v_mfma_f32_32x32x16_bf16 v[32:47], v[220:223], v[156:159], v[32:47]
	ds_read_b128 v[220:223], v183 offset:20480
	v_add_f32_e32 v191, v191, v73
	v_add_f32_e32 v190, v190, v74
	v_add_f32_e32 v191, v191, v75
	v_add_f32_e32 v190, v190, v76
	v_add_f32_e32 v191, v191, v77
	v_add_f32_e32 v190, v190, v78
	v_add_f32_e32 v191, v191, v79
	s_waitcnt lgkmcnt(5)
	v_mfma_f32_32x32x16_bf16 v[16:31], v[224:227], v[156:159], v[16:31]
	ds_read_b128 v[224:227], v184 offset:16384
	v_cvt_pk_bf16_f32 v148, v72, v73
	v_cvt_pk_bf16_f32 v149, v74, v75
	v_cvt_pk_bf16_f32 v150, v76, v77
	v_cvt_pk_bf16_f32 v151, v78, v79
	v_fma_f32 v80, v80, s24, -v179
	v_fma_f32 v81, v81, s24, -v179
	v_fma_f32 v82, v82, s24, -v179
	s_waitcnt lgkmcnt(5)
	v_mfma_f32_32x32x16_bf16 v[0:15], v[228:231], v[156:159], v[0:15]
	ds_read_b128 v[228:231], v184 offset:20480
	v_fma_f32 v83, v83, s24, -v179
	v_fma_f32 v84, v84, s24, -v179
	v_fma_f32 v85, v85, s24, -v179
	v_fma_f32 v86, v86, s24, -v179
	v_fma_f32 v87, v87, s24, -v179
	v_exp_f32_e32 v80, v80
	v_exp_f32_e32 v81, v81
	s_waitcnt lgkmcnt(5)
	v_mfma_f32_32x32x16_bf16 v[96:111], v[208:211], v[128:131], 0
	ds_read_b128 v[208:211], v185 offset:16384
	v_exp_f32_e32 v82, v82
	v_exp_f32_e32 v83, v83
	v_exp_f32_e32 v84, v84
	v_exp_f32_e32 v85, v85
	v_exp_f32_e32 v86, v86
	v_exp_f32_e32 v87, v87
	s_waitcnt lgkmcnt(5)
	v_mfma_f32_32x32x16_bf16 v[112:127], v[212:215], v[128:131], 0
	ds_read_b128 v[212:215], v185 offset:20480
	v_add_f32_e32 v190, v190, v80
	v_add_f32_e32 v191, v191, v81
	v_add_f32_e32 v190, v190, v82
	v_add_f32_e32 v191, v191, v83
	v_add_f32_e32 v190, v190, v84
	v_add_f32_e32 v191, v191, v85
	s_waitcnt lgkmcnt(5)
	v_mfma_f32_32x32x16_bf16 v[96:111], v[216:219], v[132:135], v[96:111]
	ds_read_b128 v[216:219], v187 offset:0
	v_add_f32_e32 v190, v190, v86
	v_add_f32_e32 v191, v191, v87
	v_cvt_pk_bf16_f32 v152, v80, v81
	v_cvt_pk_bf16_f32 v153, v82, v83
	v_cvt_pk_bf16_f32 v154, v84, v85
	v_cvt_pk_bf16_f32 v155, v86, v87
	s_waitcnt lgkmcnt(5)
	v_mfma_f32_32x32x16_bf16 v[112:127], v[220:223], v[132:135], v[112:127]
	ds_read_b128 v[220:223], v187 offset:4096
	v_fma_f32 v88, v88, s24, -v179
	v_fma_f32 v89, v89, s24, -v179
	v_fma_f32 v90, v90, s24, -v179
	v_fma_f32 v91, v91, s24, -v179
	v_fma_f32 v92, v92, s24, -v179
	v_fma_f32 v93, v93, s24, -v179
	s_waitcnt lgkmcnt(5)
	v_mfma_f32_32x32x16_bf16 v[96:111], v[224:227], v[136:139], v[96:111]
	ds_read_b128 v[224:227], v187 offset:8192
	v_fma_f32 v94, v94, s24, -v179
	v_fma_f32 v95, v95, s24, -v179
	v_exp_f32_e32 v88, v88
	v_exp_f32_e32 v89, v89
	v_exp_f32_e32 v90, v90
	v_exp_f32_e32 v91, v91
	s_waitcnt lgkmcnt(5)
	v_mfma_f32_32x32x16_bf16 v[112:127], v[228:231], v[136:139], v[112:127]
	ds_read_b128 v[228:231], v187 offset:12288
	v_exp_f32_e32 v92, v92
	v_exp_f32_e32 v93, v93
	v_exp_f32_e32 v94, v94
	v_exp_f32_e32 v95, v95
	v_add_f32_e32 v190, v190, v88
	v_add_f32_e32 v191, v191, v89
	s_waitcnt lgkmcnt(5)
	v_mfma_f32_32x32x16_bf16 v[96:111], v[208:211], v[140:143], v[96:111]
	ds_read_b128 v[208:211], v188 offset:0
	v_add_f32_e32 v190, v190, v90
	v_add_f32_e32 v191, v191, v91
	v_add_f32_e32 v190, v190, v92
	v_add_f32_e32 v191, v191, v93
	v_add_f32_e32 v190, v190, v94
	v_add_f32_e32 v191, v191, v95
	s_waitcnt lgkmcnt(5)
	v_mfma_f32_32x32x16_bf16 v[112:127], v[212:215], v[140:143], v[112:127]
	ds_read_b128 v[212:215], v188 offset:4096
	v_cvt_pk_bf16_f32 v156, v88, v89
	v_cvt_pk_bf16_f32 v157, v90, v91
	v_cvt_pk_bf16_f32 v158, v92, v93
	v_cvt_pk_bf16_f32 v159, v94, v95
	v_add_f32_e32 v190, v190, v191
	v_fma_f32 v167, v167, v174, v190
	s_cbranch_vccz .Lattn_noresc_L3
	s_nop 7
	s_nop 7
	v_pk_mul_f32 v[0:1], v[0:1], v[174:175] op_sel_hi:[1,0]
	v_pk_mul_f32 v[2:3], v[2:3], v[174:175] op_sel_hi:[1,0]
	v_pk_mul_f32 v[4:5], v[4:5], v[174:175] op_sel_hi:[1,0]
	v_pk_mul_f32 v[6:7], v[6:7], v[174:175] op_sel_hi:[1,0]
	v_pk_mul_f32 v[8:9], v[8:9], v[174:175] op_sel_hi:[1,0]
	v_pk_mul_f32 v[10:11], v[10:11], v[174:175] op_sel_hi:[1,0]
	v_pk_mul_f32 v[12:13], v[12:13], v[174:175] op_sel_hi:[1,0]
	v_pk_mul_f32 v[14:15], v[14:15], v[174:175] op_sel_hi:[1,0]
	v_pk_mul_f32 v[16:17], v[16:17], v[174:175] op_sel_hi:[1,0]
	v_pk_mul_f32 v[18:19], v[18:19], v[174:175] op_sel_hi:[1,0]
	v_pk_mul_f32 v[20:21], v[20:21], v[174:175] op_sel_hi:[1,0]
	v_pk_mul_f32 v[22:23], v[22:23], v[174:175] op_sel_hi:[1,0]
	v_pk_mul_f32 v[24:25], v[24:25], v[174:175] op_sel_hi:[1,0]
	v_pk_mul_f32 v[26:27], v[26:27], v[174:175] op_sel_hi:[1,0]
	v_pk_mul_f32 v[28:29], v[28:29], v[174:175] op_sel_hi:[1,0]
	v_pk_mul_f32 v[30:31], v[30:31], v[174:175] op_sel_hi:[1,0]
	v_pk_mul_f32 v[32:33], v[32:33], v[174:175] op_sel_hi:[1,0]
	v_pk_mul_f32 v[34:35], v[34:35], v[174:175] op_sel_hi:[1,0]
	v_pk_mul_f32 v[36:37], v[36:37], v[174:175] op_sel_hi:[1,0]
	v_pk_mul_f32 v[38:39], v[38:39], v[174:175] op_sel_hi:[1,0]
	v_pk_mul_f32 v[40:41], v[40:41], v[174:175] op_sel_hi:[1,0]
	v_pk_mul_f32 v[42:43], v[42:43], v[174:175] op_sel_hi:[1,0]
	v_pk_mul_f32 v[44:45], v[44:45], v[174:175] op_sel_hi:[1,0]
	v_pk_mul_f32 v[46:47], v[46:47], v[174:175] op_sel_hi:[1,0]
	v_pk_mul_f32 v[48:49], v[48:49], v[174:175] op_sel_hi:[1,0]
	v_pk_mul_f32 v[50:51], v[50:51], v[174:175] op_sel_hi:[1,0]
	v_pk_mul_f32 v[52:53], v[52:53], v[174:175] op_sel_hi:[1,0]
	v_pk_mul_f32 v[54:55], v[54:55], v[174:175] op_sel_hi:[1,0]
	v_pk_mul_f32 v[56:57], v[56:57], v[174:175] op_sel_hi:[1,0]
	v_pk_mul_f32 v[58:59], v[58:59], v[174:175] op_sel_hi:[1,0]
	v_pk_mul_f32 v[60:61], v[60:61], v[174:175] op_sel_hi:[1,0]
	v_pk_mul_f32 v[62:63], v[62:63], v[174:175] op_sel_hi:[1,0]
	s_nop 1
.Lattn_noresc_L3:
	s_add_i32 s42, s42, 4
	s_add_i32 s47, s47, -1
	s_cmp_lg_u32 s47, 0
	s_cbranch_scc1 .Lattn_loop
	s_waitcnt vmcnt(4)
	s_barrier
	s_waitcnt lgkmcnt(5)
	v_mfma_f32_32x32x16_bf16 v[48:63], v[216:219], v[144:147], v[48:63]
	ds_read_b128 v[216:219], v188 offset:8192
	s_add_i32 s2, s42, 2
	v_max3_f32 v254, v96, v97, v98
	s_and_b32 s2, s2, 31
	v_max3_f32 v255, v112, v113, v114
	s_lshl_b32 s2, s2, 7
	v_max3_f32 v254, v254, v99, v100
	s_add_i32 m0, s5, 114688
	s_waitcnt lgkmcnt(5)
	v_mfma_f32_32x32x16_bf16 v[32:47], v[220:223], v[144:147], v[32:47]
	ds_read_b128 v[220:223], v188 offset:12288
	v_max3_f32 v255, v255, v115, v116
	v_lshl_add_u64 v[232:233], v[172:173], 0, s[2:3]
	v_max3_f32 v254, v254, v101, v102
	global_load_lds_dwordx4 v[232:233], off
	v_max3_f32 v255, v255, v117, v118
	s_add_i32 m0, s5, 122880
	v_max3_f32 v254, v254, v103, v104
	s_waitcnt lgkmcnt(5)
	v_mfma_f32_32x32x16_bf16 v[16:31], v[224:227], v[144:147], v[16:31]
	ds_read_b128 v[224:227], v186 offset:0
	v_lshl_add_u64 v[234:235], v[232:233], 0, s[22:23]
	v_max3_f32 v255, v255, v119, v120
	global_load_lds_dwordx4 v[234:235], off
	v_max3_f32 v254, v254, v105, v106
	v_max3_f32 v255, v255, v121, v122
	v_max3_f32 v254, v254, v107, v108
	v_max3_f32 v255, v255, v123, v124
	s_waitcnt lgkmcnt(5)
	v_mfma_f32_32x32x16_bf16 v[0:15], v[228:231], v[144:147], v[0:15]
	ds_read_b128 v[228:231], v186 offset:4096
	v_max3_f32 v254, v254, v109, v110
	v_max3_f32 v255, v255, v125, v126
	v_max3_f32 v254, v254, v111, v127
	v_max_f32_e32 v254, v254, v255
	v_mov_b32_e32 v255, v254
	s_nop 1
	v_permlane32_swap_b32_e32 v254, v255
	s_waitcnt lgkmcnt(5)
	v_mfma_f32_32x32x16_bf16 v[48:63], v[208:211], v[148:151], v[48:63]
	ds_read_b128 v[208:211], v186 offset:8192
	v_max_f32_e32 v254, v254, v255
	v_add_f32_e32 v180, 0x42800000, v175
	v_cmp_gt_f32_e32 vcc, v254, v180
	s_nop 1
	v_cndmask_b32_e32 v180, v175, v254, vcc
	v_sub_f32_e32 v255, v175, v180
	v_mul_f32_e32 v255, 0x3e38aa3b, v255
	s_waitcnt lgkmcnt(5)
	v_mfma_f32_32x32x16_bf16 v[32:47], v[212:215], v[148:151], v[32:47]
	ds_read_b128 v[212:215], v186 offset:12288
	v_exp_f32_e32 v174, v255
	v_mov_b32_e32 v175, v180
	v_mul_f32_e32 v179, 0x3e38aa3b, v180
	v_fma_f32 v96, v96, s24, -v179
	v_fma_f32 v97, v97, s24, -v179
	v_fma_f32 v98, v98, s24, -v179
	v_fma_f32 v99, v99, s24, -v179
	s_waitcnt lgkmcnt(5)
	v_mfma_f32_32x32x16_bf16 v[16:31], v[216:219], v[148:151], v[16:31]
	ds_read_b128 v[216:219], v189 offset:0
	v_fma_f32 v100, v100, s24, -v179
	v_fma_f32 v101, v101, s24, -v179
	v_fma_f32 v102, v102, s24, -v179
	v_fma_f32 v103, v103, s24, -v179
	v_exp_f32_e32 v96, v96
	v_exp_f32_e32 v97, v97
	s_waitcnt lgkmcnt(5)
	v_mfma_f32_32x32x16_bf16 v[0:15], v[220:223], v[148:151], v[0:15]
	ds_read_b128 v[220:223], v189 offset:4096
	v_exp_f32_e32 v98, v98
	v_exp_f32_e32 v99, v99
	v_exp_f32_e32 v100, v100
	v_exp_f32_e32 v101, v101
	v_exp_f32_e32 v102, v102
	v_exp_f32_e32 v103, v103
	s_waitcnt lgkmcnt(5)
	v_mfma_f32_32x32x16_bf16 v[48:63], v[224:227], v[152:155], v[48:63]
	ds_read_b128 v[224:227], v189 offset:8192
	v_add_f32_e32 v190, v96, v97
	v_add_f32_e32 v191, v98, v99
	v_add_f32_e32 v190, v190, v100
	v_add_f32_e32 v191, v191, v101
	v_add_f32_e32 v190, v190, v102
	v_add_f32_e32 v191, v191, v103
	s_waitcnt lgkmcnt(5)
	v_mfma_f32_32x32x16_bf16 v[32:47], v[228:231], v[152:155], v[32:47]
	ds_read_b128 v[228:231], v189 offset:12288
	v_cvt_pk_bf16_f32 v144, v96, v97
	v_cvt_pk_bf16_f32 v145, v98, v99
	v_cvt_pk_bf16_f32 v146, v100, v101
	v_cvt_pk_bf16_f32 v147, v102, v103
	v_fma_f32 v104, v104, s24, -v179
	v_fma_f32 v105, v105, s24, -v179
	s_waitcnt lgkmcnt(5)
	v_mfma_f32_32x32x16_bf16 v[16:31], v[208:211], v[152:155], v[16:31]
	ds_read_b128 v[208:211], v182 offset:32768
	v_fma_f32 v106, v106, s24, -v179
	v_fma_f32 v107, v107, s24, -v179
	v_fma_f32 v108, v108, s24, -v179
	v_fma_f32 v109, v109, s24, -v179
	v_fma_f32 v110, v110, s24, -v179
	v_fma_f32 v111, v111, s24, -v179
	s_waitcnt lgkmcnt(5)
	v_mfma_f32_32x32x16_bf16 v[0:15], v[212:215], v[152:155], v[0:15]
	ds_read_b128 v[212:215], v182 offset:36864
	v_exp_f32_e32 v104, v104
	v_exp_f32_e32 v105, v105
	v_exp_f32_e32 v106, v106
	v_exp_f32_e32 v107, v107
	v_exp_f32_e32 v108, v108
	v_exp_f32_e32 v109, v109
	s_waitcnt lgkmcnt(5)
	v_mfma_f32_32x32x16_bf16 v[48:63], v[216:219], v[156:159], v[48:63]
	ds_read_b128 v[216:219], v183 offset:32768
	v_exp_f32_e32 v110, v110
	v_exp_f32_e32 v111, v111
	v_add_f32_e32 v190, v190, v104
	v_add_f32_e32 v191, v191, v105
	v_add_f32_e32 v190, v190, v106
	v_add_f32_e32 v191, v191, v107
	s_waitcnt lgkmcnt(5)
	v_mfma_f32_32x32x16_bf16 v[32:47], v[220:223], v[156:159], v[32:47]
	ds_read_b128 v[220:223], v183 offset:36864
	v_add_f32_e32 v190, v190, v108
	v_add_f32_e32 v191, v191, v109
	v_add_f32_e32 v190, v190, v110
	v_add_f32_e32 v191, v191, v111
	v_cvt_pk_bf16_f32 v148, v104, v105
	v_cvt_pk_bf16_f32 v149, v106, v107
	s_waitcnt lgkmcnt(5)
	v_mfma_f32_32x32x16_bf16 v[16:31], v[224:227], v[156:159], v[16:31]
	ds_read_b128 v[224:227], v184 offset:32768
	v_cvt_pk_bf16_f32 v150, v108, v109
	v_cvt_pk_bf16_f32 v151, v110, v111
	v_fma_f32 v112, v112, s24, -v179
	v_fma_f32 v113, v113, s24, -v179
	v_fma_f32 v114, v114, s24, -v179
	v_fma_f32 v115, v115, s24, -v179
	s_waitcnt lgkmcnt(5)
	v_mfma_f32_32x32x16_bf16 v[0:15], v[228:231], v[156:159], v[0:15]
	ds_read_b128 v[228:231], v184 offset:36864
	v_fma_f32 v116, v116, s24, -v179
	v_fma_f32 v117, v117, s24, -v179
	v_fma_f32 v118, v118, s24, -v179
	v_fma_f32 v119, v119, s24, -v179
	v_exp_f32_e32 v112, v112
	v_exp_f32_e32 v113, v113
	s_waitcnt lgkmcnt(5)
	v_mfma_f32_32x32x16_bf16 v[64:79], v[208:211], v[128:131], 0
	ds_read_b128 v[208:211], v185 offset:32768
	v_exp_f32_e32 v114, v114
	v_exp_f32_e32 v115, v115
	v_exp_f32_e32 v116, v116
	v_exp_f32_e32 v117, v117
	v_exp_f32_e32 v118, v118
	v_exp_f32_e32 v119, v119
	s_waitcnt lgkmcnt(5)
	v_mfma_f32_32x32x16_bf16 v[80:95], v[212:215], v[128:131], 0
	ds_read_b128 v[212:215], v185 offset:36864
	v_add_f32_e32 v190, v190, v112
	v_add_f32_e32 v191, v191, v113
	v_add_f32_e32 v190, v190, v114
	v_add_f32_e32 v191, v191, v115
	v_add_f32_e32 v190, v190, v116
	v_add_f32_e32 v191, v191, v117
	s_waitcnt lgkmcnt(5)
	v_mfma_f32_32x32x16_bf16 v[64:79], v[216:219], v[132:135], v[64:79]
	ds_read_b128 v[216:219], v187 offset:16384
	v_add_f32_e32 v190, v190, v118
	v_add_f32_e32 v191, v191, v119
	v_cvt_pk_bf16_f32 v152, v112, v113
	v_cvt_pk_bf16_f32 v153, v114, v115
	v_cvt_pk_bf16_f32 v154, v116, v117
	v_cvt_pk_bf16_f32 v155, v118, v119
	s_waitcnt lgkmcnt(5)
	v_mfma_f32_32x32x16_bf16 v[80:95], v[220:223], v[132:135], v[80:95]
	ds_read_b128 v[220:223], v187 offset:20480
	v_fma_f32 v120, v120, s24, -v179
	v_fma_f32 v121, v121, s24, -v179
	v_fma_f32 v122, v122, s24, -v179
	v_fma_f32 v123, v123, s24, -v179
	v_fma_f32 v124, v124, s24, -v179
	v_fma_f32 v125, v125, s24, -v179
	s_waitcnt lgkmcnt(5)
	v_mfma_f32_32x32x16_bf16 v[64:79], v[224:227], v[136:139], v[64:79]
	ds_read_b128 v[224:227], v187 offset:24576
	v_fma_f32 v126, v126, s24, -v179
	v_fma_f32 v127, v127, s24, -v179
	v_exp_f32_e32 v120, v120
	v_exp_f32_e32 v121, v121
	v_exp_f32_e32 v122, v122
	v_exp_f32_e32 v123, v123
	s_waitcnt lgkmcnt(5)
	v_mfma_f32_32x32x16_bf16 v[80:95], v[228:231], v[136:139], v[80:95]
	ds_read_b128 v[228:231], v187 offset:28672
	v_exp_f32_e32 v124, v124
	v_exp_f32_e32 v125, v125
	v_exp_f32_e32 v126, v126
	v_exp_f32_e32 v127, v127
	v_add_f32_e32 v190, v190, v120
	v_add_f32_e32 v191, v191, v121
	s_waitcnt lgkmcnt(5)
	v_mfma_f32_32x32x16_bf16 v[64:79], v[208:211], v[140:143], v[64:79]
	ds_read_b128 v[208:211], v188 offset:16384
	v_add_f32_e32 v190, v190, v122
	v_add_f32_e32 v191, v191, v123
	v_add_f32_e32 v190, v190, v124
	v_add_f32_e32 v191, v191, v125
	v_add_f32_e32 v190, v190, v126
	v_add_f32_e32 v191, v191, v127
	s_waitcnt lgkmcnt(5)
	v_mfma_f32_32x32x16_bf16 v[80:95], v[212:215], v[140:143], v[80:95]
	ds_read_b128 v[212:215], v188 offset:20480
	v_cvt_pk_bf16_f32 v156, v120, v121
	v_cvt_pk_bf16_f32 v157, v122, v123
	v_cvt_pk_bf16_f32 v158, v124, v125
	v_cvt_pk_bf16_f32 v159, v126, v127
	v_add_f32_e32 v190, v190, v191
	v_fma_f32 v167, v167, v174, v190
	s_cbranch_vccz .Lattn_noresc_T29
	s_nop 7
	s_nop 7
	v_pk_mul_f32 v[0:1], v[0:1], v[174:175] op_sel_hi:[1,0]
	v_pk_mul_f32 v[2:3], v[2:3], v[174:175] op_sel_hi:[1,0]
	v_pk_mul_f32 v[4:5], v[4:5], v[174:175] op_sel_hi:[1,0]
	v_pk_mul_f32 v[6:7], v[6:7], v[174:175] op_sel_hi:[1,0]
	v_pk_mul_f32 v[8:9], v[8:9], v[174:175] op_sel_hi:[1,0]
	v_pk_mul_f32 v[10:11], v[10:11], v[174:175] op_sel_hi:[1,0]
	v_pk_mul_f32 v[12:13], v[12:13], v[174:175] op_sel_hi:[1,0]
	v_pk_mul_f32 v[14:15], v[14:15], v[174:175] op_sel_hi:[1,0]
	v_pk_mul_f32 v[16:17], v[16:17], v[174:175] op_sel_hi:[1,0]
	v_pk_mul_f32 v[18:19], v[18:19], v[174:175] op_sel_hi:[1,0]
	v_pk_mul_f32 v[20:21], v[20:21], v[174:175] op_sel_hi:[1,0]
	v_pk_mul_f32 v[22:23], v[22:23], v[174:175] op_sel_hi:[1,0]
	v_pk_mul_f32 v[24:25], v[24:25], v[174:175] op_sel_hi:[1,0]
	v_pk_mul_f32 v[26:27], v[26:27], v[174:175] op_sel_hi:[1,0]
	v_pk_mul_f32 v[28:29], v[28:29], v[174:175] op_sel_hi:[1,0]
	v_pk_mul_f32 v[30:31], v[30:31], v[174:175] op_sel_hi:[1,0]
	v_pk_mul_f32 v[32:33], v[32:33], v[174:175] op_sel_hi:[1,0]
	v_pk_mul_f32 v[34:35], v[34:35], v[174:175] op_sel_hi:[1,0]
	v_pk_mul_f32 v[36:37], v[36:37], v[174:175] op_sel_hi:[1,0]
	v_pk_mul_f32 v[38:39], v[38:39], v[174:175] op_sel_hi:[1,0]
	v_pk_mul_f32 v[40:41], v[40:41], v[174:175] op_sel_hi:[1,0]
	v_pk_mul_f32 v[42:43], v[42:43], v[174:175] op_sel_hi:[1,0]
	v_pk_mul_f32 v[44:45], v[44:45], v[174:175] op_sel_hi:[1,0]
	v_pk_mul_f32 v[46:47], v[46:47], v[174:175] op_sel_hi:[1,0]
	v_pk_mul_f32 v[48:49], v[48:49], v[174:175] op_sel_hi:[1,0]
	v_pk_mul_f32 v[50:51], v[50:51], v[174:175] op_sel_hi:[1,0]
	v_pk_mul_f32 v[52:53], v[52:53], v[174:175] op_sel_hi:[1,0]
	v_pk_mul_f32 v[54:55], v[54:55], v[174:175] op_sel_hi:[1,0]
	v_pk_mul_f32 v[56:57], v[56:57], v[174:175] op_sel_hi:[1,0]
	v_pk_mul_f32 v[58:59], v[58:59], v[174:175] op_sel_hi:[1,0]
	v_pk_mul_f32 v[60:61], v[60:61], v[174:175] op_sel_hi:[1,0]
	v_pk_mul_f32 v[62:63], v[62:63], v[174:175] op_sel_hi:[1,0]
	s_nop 1
.Lattn_noresc_T29:
	s_waitcnt vmcnt(2)
	s_barrier
	s_waitcnt lgkmcnt(5)
	v_mfma_f32_32x32x16_bf16 v[48:63], v[216:219], v[144:147], v[48:63]
	ds_read_b128 v[216:219], v188 offset:24576
	v_max3_f32 v254, v64, v65, v66
	v_max3_f32 v255, v80, v81, v82
	v_max3_f32 v254, v254, v67, v68
	v_max3_f32 v255, v255, v83, v84
	v_max3_f32 v254, v254, v69, v70
	v_max3_f32 v255, v255, v85, v86
	s_waitcnt lgkmcnt(5)
	v_mfma_f32_32x32x16_bf16 v[32:47], v[220:223], v[144:147], v[32:47]
	ds_read_b128 v[220:223], v188 offset:28672
	v_max3_f32 v254, v254, v71, v72
	v_max3_f32 v255, v255, v87, v88
	v_max3_f32 v254, v254, v73, v74
	v_max3_f32 v255, v255, v89, v90
	v_max3_f32 v254, v254, v75, v76
	v_max3_f32 v255, v255, v91, v92
	s_waitcnt lgkmcnt(5)
	v_mfma_f32_32x32x16_bf16 v[16:31], v[224:227], v[144:147], v[16:31]
	ds_read_b128 v[224:227], v186 offset:16384
	v_max3_f32 v254, v254, v77, v78
	v_max3_f32 v255, v255, v93, v94
	v_max3_f32 v254, v254, v79, v95
	v_max_f32_e32 v254, v254, v255
	v_mov_b32_e32 v255, v254
	s_nop 1
	s_waitcnt lgkmcnt(5)
	v_mfma_f32_32x32x16_bf16 v[0:15], v[228:231], v[144:147], v[0:15]
	ds_read_b128 v[228:231], v186 offset:20480
	v_permlane32_swap_b32_e32 v254, v255
	v_max_f32_e32 v254, v254, v255
	v_add_f32_e32 v180, 0x42800000, v175
	v_cmp_gt_f32_e32 vcc, v254, v180
	s_nop 1
	v_cndmask_b32_e32 v180, v175, v254, vcc
	s_waitcnt lgkmcnt(5)
	v_mfma_f32_32x32x16_bf16 v[48:63], v[208:211], v[148:151], v[48:63]
	ds_read_b128 v[208:211], v186 offset:24576
	v_sub_f32_e32 v255, v175, v180
	v_mul_f32_e32 v255, 0x3e38aa3b, v255
	v_exp_f32_e32 v174, v255
	v_mov_b32_e32 v175, v180
	v_mul_f32_e32 v179, 0x3e38aa3b, v180
	v_fma_f32 v64, v64, s24, -v179
	s_waitcnt lgkmcnt(5)
	v_mfma_f32_32x32x16_bf16 v[32:47], v[212:215], v[148:151], v[32:47]
	ds_read_b128 v[212:215], v186 offset:28672
	v_fma_f32 v65, v65, s24, -v179
	v_fma_f32 v66, v66, s24, -v179
	v_fma_f32 v67, v67, s24, -v179
	v_fma_f32 v68, v68, s24, -v179
	v_fma_f32 v69, v69, s24, -v179
	v_fma_f32 v70, v70, s24, -v179
	s_waitcnt lgkmcnt(5)
	v_mfma_f32_32x32x16_bf16 v[16:31], v[216:219], v[148:151], v[16:31]
	ds_read_b128 v[216:219], v189 offset:16384
	v_fma_f32 v71, v71, s24, -v179
	v_exp_f32_e32 v64, v64
	v_exp_f32_e32 v65, v65
	v_exp_f32_e32 v66, v66
	v_exp_f32_e32 v67, v67
	v_exp_f32_e32 v68, v68
	s_waitcnt lgkmcnt(5)
	v_mfma_f32_32x32x16_bf16 v[0:15], v[220:223], v[148:151], v[0:15]
	ds_read_b128 v[220:223], v189 offset:20480
	v_exp_f32_e32 v69, v69
	v_exp_f32_e32 v70, v70
	v_exp_f32_e32 v71, v71
	v_add_f32_e32 v190, v64, v65
	v_add_f32_e32 v191, v66, v67
	v_add_f32_e32 v190, v190, v68
	s_waitcnt lgkmcnt(5)
	v_mfma_f32_32x32x16_bf16 v[48:63], v[224:227], v[152:155], v[48:63]
	ds_read_b128 v[224:227], v189 offset:24576
	v_add_f32_e32 v191, v191, v69
	v_add_f32_e32 v190, v190, v70
	v_add_f32_e32 v191, v191, v71
	v_cvt_pk_bf16_f32 v144, v64, v65
	v_cvt_pk_bf16_f32 v145, v66, v67
	v_cvt_pk_bf16_f32 v146, v68, v69
	s_waitcnt lgkmcnt(5)
	v_mfma_f32_32x32x16_bf16 v[32:47], v[228:231], v[152:155], v[32:47]
	ds_read_b128 v[228:231], v189 offset:28672
	v_cvt_pk_bf16_f32 v147, v70, v71
	v_fma_f32 v72, v72, s24, -v179
	v_fma_f32 v73, v73, s24, -v179
	v_fma_f32 v74, v74, s24, -v179
	v_fma_f32 v75, v75, s24, -v179
	v_fma_f32 v76, v76, s24, -v179
	s_waitcnt lgkmcnt(5)
	v_mfma_f32_32x32x16_bf16 v[16:31], v[208:211], v[152:155], v[16:31]
	ds_read_b128 v[208:211], v182 offset:49152
	v_fma_f32 v77, v77, s24, -v179
	v_fma_f32 v78, v78, s24, -v179
	v_fma_f32 v79, v79, s24, -v179
	v_exp_f32_e32 v72, v72
	v_exp_f32_e32 v73, v73
	v_exp_f32_e32 v74, v74
	s_waitcnt lgkmcnt(5)
	v_mfma_f32_32x32x16_bf16 v[0:15], v[212:215], v[152:155], v[0:15]
	ds_read_b128 v[212:215], v182 offset:53248
	v_exp_f32_e32 v75, v75
	v_exp_f32_e32 v76, v76
	v_exp_f32_e32 v77, v77
	v_exp_f32_e32 v78, v78
	v_exp_f32_e32 v79, v79
	v_add_f32_e32 v190, v190, v72
	s_waitcnt lgkmcnt(5)
	v_mfma_f32_32x32x16_bf16 v[48:63], v[216:219], v[156:159], v[48:63]
	ds_read_b128 v[216:219], v183 offset:49152
	v_add_f32_e32 v191, v191, v73
	v_add_f32_e32 v190, v190, v74
	v_add_f32_e32 v191, v191, v75
	v_add_f32_e32 v190, v190, v76
	v_add_f32_e32 v191, v191, v77
	v_add_f32_e32 v190, v190, v78
	s_waitcnt lgkmcnt(5)
	v_mfma_f32_32x32x16_bf16 v[32:47], v[220:223], v[156:159], v[32:47]
	ds_read_b128 v[220:223], v183 offset:53248
	v_add_f32_e32 v191, v191, v79
	v_cvt_pk_bf16_f32 v148, v72, v73
	v_cvt_pk_bf16_f32 v149, v74, v75
	v_cvt_pk_bf16_f32 v150, v76, v77
	v_cvt_pk_bf16_f32 v151, v78, v79
	v_fma_f32 v80, v80, s24, -v179
	s_waitcnt lgkmcnt(5)
	v_mfma_f32_32x32x16_bf16 v[16:31], v[224:227], v[156:159], v[16:31]
	ds_read_b128 v[224:227], v184 offset:49152
	v_fma_f32 v81, v81, s24, -v179
	v_fma_f32 v82, v82, s24, -v179
	v_fma_f32 v83, v83, s24, -v179
	v_fma_f32 v84, v84, s24, -v179
	v_fma_f32 v85, v85, s24, -v179
	v_fma_f32 v86, v86, s24, -v179
	s_waitcnt lgkmcnt(5)
	v_mfma_f32_32x32x16_bf16 v[0:15], v[228:231], v[156:159], v[0:15]
	ds_read_b128 v[228:231], v184 offset:53248
	v_fma_f32 v87, v87, s24, -v179
	v_exp_f32_e32 v80, v80
	v_exp_f32_e32 v81, v81
	v_exp_f32_e32 v82, v82
	v_exp_f32_e32 v83, v83
	v_exp_f32_e32 v84, v84
	s_waitcnt lgkmcnt(5)
	v_mfma_f32_32x32x16_bf16 v[96:111], v[208:211], v[128:131], 0
	ds_read_b128 v[208:211], v185 offset:49152
	v_exp_f32_e32 v85, v85
	v_exp_f32_e32 v86, v86
	v_exp_f32_e32 v87, v87
	v_add_f32_e32 v190, v190, v80
	v_add_f32_e32 v191, v191, v81
	v_add_f32_e32 v190, v190, v82
	s_waitcnt lgkmcnt(5)
	v_mfma_f32_32x32x16_bf16 v[112:127], v[212:215], v[128:131], 0
	ds_read_b128 v[212:215], v185 offset:53248
	v_add_f32_e32 v191, v191, v83
	v_add_f32_e32 v190, v190, v84
	v_add_f32_e32 v191, v191, v85
	v_add_f32_e32 v190, v190, v86
	v_add_f32_e32 v191, v191, v87
	v_cvt_pk_bf16_f32 v152, v80, v81
	s_waitcnt lgkmcnt(5)
	v_mfma_f32_32x32x16_bf16 v[96:111], v[216:219], v[132:135], v[96:111]
	ds_read_b128 v[216:219], v187 offset:32768
	v_cvt_pk_bf16_f32 v153, v82, v83
	v_cvt_pk_bf16_f32 v154, v84, v85
	v_cvt_pk_bf16_f32 v155, v86, v87
	v_fma_f32 v88, v88, s24, -v179
	v_fma_f32 v89, v89, s24, -v179
	v_fma_f32 v90, v90, s24, -v179
	s_waitcnt lgkmcnt(5)
	v_mfma_f32_32x32x16_bf16 v[112:127], v[220:223], v[132:135], v[112:127]
	ds_read_b128 v[220:223], v187 offset:36864
	v_fma_f32 v91, v91, s24, -v179
	v_fma_f32 v92, v92, s24, -v179
	v_fma_f32 v93, v93, s24, -v179
	v_fma_f32 v94, v94, s24, -v179
	v_fma_f32 v95, v95, s24, -v179
	v_exp_f32_e32 v88, v88
	s_waitcnt lgkmcnt(5)
	v_mfma_f32_32x32x16_bf16 v[96:111], v[224:227], v[136:139], v[96:111]
	ds_read_b128 v[224:227], v187 offset:40960
	v_exp_f32_e32 v89, v89
	v_exp_f32_e32 v90, v90
	v_exp_f32_e32 v91, v91
	v_exp_f32_e32 v92, v92
	v_exp_f32_e32 v93, v93
	v_exp_f32_e32 v94, v94
	s_waitcnt lgkmcnt(5)
	v_mfma_f32_32x32x16_bf16 v[112:127], v[228:231], v[136:139], v[112:127]
	ds_read_b128 v[228:231], v187 offset:45056
	v_exp_f32_e32 v95, v95
	v_add_f32_e32 v190, v190, v88
	v_add_f32_e32 v191, v191, v89
	v_add_f32_e32 v190, v190, v90
	v_add_f32_e32 v191, v191, v91
	s_waitcnt lgkmcnt(5)
	v_mfma_f32_32x32x16_bf16 v[96:111], v[208:211], v[140:143], v[96:111]
	ds_read_b128 v[208:211], v188 offset:32768
	v_add_f32_e32 v190, v190, v92
	v_add_f32_e32 v191, v191, v93
	v_add_f32_e32 v190, v190, v94
	v_add_f32_e32 v191, v191, v95
	v_cvt_pk_bf16_f32 v156, v88, v89
	s_waitcnt lgkmcnt(5)
	v_mfma_f32_32x32x16_bf16 v[112:127], v[212:215], v[140:143], v[112:127]
	ds_read_b128 v[212:215], v188 offset:36864
	v_cvt_pk_bf16_f32 v157, v90, v91
	v_cvt_pk_bf16_f32 v158, v92, v93
	v_cvt_pk_bf16_f32 v159, v94, v95
	v_add_f32_e32 v190, v190, v191
	v_fma_f32 v167, v167, v174, v190
	s_cbranch_vccz .Lattn_noresc_T30
	s_nop 7
	s_nop 7
	v_pk_mul_f32 v[0:1], v[0:1], v[174:175] op_sel_hi:[1,0]
	v_pk_mul_f32 v[2:3], v[2:3], v[174:175] op_sel_hi:[1,0]
	v_pk_mul_f32 v[4:5], v[4:5], v[174:175] op_sel_hi:[1,0]
	v_pk_mul_f32 v[6:7], v[6:7], v[174:175] op_sel_hi:[1,0]
	v_pk_mul_f32 v[8:9], v[8:9], v[174:175] op_sel_hi:[1,0]
	v_pk_mul_f32 v[10:11], v[10:11], v[174:175] op_sel_hi:[1,0]
	v_pk_mul_f32 v[12:13], v[12:13], v[174:175] op_sel_hi:[1,0]
	v_pk_mul_f32 v[14:15], v[14:15], v[174:175] op_sel_hi:[1,0]
	v_pk_mul_f32 v[16:17], v[16:17], v[174:175] op_sel_hi:[1,0]
	v_pk_mul_f32 v[18:19], v[18:19], v[174:175] op_sel_hi:[1,0]
	v_pk_mul_f32 v[20:21], v[20:21], v[174:175] op_sel_hi:[1,0]
	v_pk_mul_f32 v[22:23], v[22:23], v[174:175] op_sel_hi:[1,0]
	v_pk_mul_f32 v[24:25], v[24:25], v[174:175] op_sel_hi:[1,0]
	v_pk_mul_f32 v[26:27], v[26:27], v[174:175] op_sel_hi:[1,0]
	v_pk_mul_f32 v[28:29], v[28:29], v[174:175] op_sel_hi:[1,0]
	v_pk_mul_f32 v[30:31], v[30:31], v[174:175] op_sel_hi:[1,0]
	v_pk_mul_f32 v[32:33], v[32:33], v[174:175] op_sel_hi:[1,0]
	v_pk_mul_f32 v[34:35], v[34:35], v[174:175] op_sel_hi:[1,0]
	v_pk_mul_f32 v[36:37], v[36:37], v[174:175] op_sel_hi:[1,0]
	v_pk_mul_f32 v[38:39], v[38:39], v[174:175] op_sel_hi:[1,0]
	v_pk_mul_f32 v[40:41], v[40:41], v[174:175] op_sel_hi:[1,0]
	v_pk_mul_f32 v[42:43], v[42:43], v[174:175] op_sel_hi:[1,0]
	v_pk_mul_f32 v[44:45], v[44:45], v[174:175] op_sel_hi:[1,0]
	v_pk_mul_f32 v[46:47], v[46:47], v[174:175] op_sel_hi:[1,0]
	v_pk_mul_f32 v[48:49], v[48:49], v[174:175] op_sel_hi:[1,0]
	v_pk_mul_f32 v[50:51], v[50:51], v[174:175] op_sel_hi:[1,0]
	v_pk_mul_f32 v[52:53], v[52:53], v[174:175] op_sel_hi:[1,0]
	v_pk_mul_f32 v[54:55], v[54:55], v[174:175] op_sel_hi:[1,0]
	v_pk_mul_f32 v[56:57], v[56:57], v[174:175] op_sel_hi:[1,0]
	v_pk_mul_f32 v[58:59], v[58:59], v[174:175] op_sel_hi:[1,0]
	v_pk_mul_f32 v[60:61], v[60:61], v[174:175] op_sel_hi:[1,0]
	v_pk_mul_f32 v[62:63], v[62:63], v[174:175] op_sel_hi:[1,0]
	s_nop 1
.Lattn_noresc_T30:
	s_waitcnt vmcnt(0)
	s_barrier
	s_waitcnt lgkmcnt(5)
	v_mfma_f32_32x32x16_bf16 v[48:63], v[216:219], v[144:147], v[48:63]
	ds_read_b128 v[216:219], v188 offset:40960
	v_max3_f32 v254, v96, v97, v98
	v_max3_f32 v255, v112, v113, v114
	v_max3_f32 v254, v254, v99, v100
	v_max3_f32 v255, v255, v115, v116
	v_max3_f32 v254, v254, v101, v102
	v_max3_f32 v255, v255, v117, v118
	v_max3_f32 v254, v254, v103, v104
	v_max3_f32 v255, v255, v119, v120
	v_max3_f32 v254, v254, v105, v106
	s_waitcnt lgkmcnt(5)
	v_mfma_f32_32x32x16_bf16 v[32:47], v[220:223], v[144:147], v[32:47]
	ds_read_b128 v[220:223], v188 offset:45056
	v_max3_f32 v255, v255, v121, v122
	v_max3_f32 v254, v254, v107, v108
	v_max3_f32 v255, v255, v123, v124
	v_max3_f32 v254, v254, v109, v110
	v_max3_f32 v255, v255, v125, v126
	v_max3_f32 v254, v254, v111, v127
	v_max_f32_e32 v254, v254, v255
	v_mov_b32_e32 v255, v254
	s_nop 1
	s_waitcnt lgkmcnt(5)
	v_mfma_f32_32x32x16_bf16 v[16:31], v[224:227], v[144:147], v[16:31]
	ds_read_b128 v[224:227], v186 offset:32768
	v_permlane32_swap_b32_e32 v254, v255
	v_max_f32_e32 v254, v254, v255
	v_add_f32_e32 v180, 0x42800000, v175
	v_cmp_gt_f32_e32 vcc, v254, v180
	s_nop 1
	v_cndmask_b32_e32 v180, v175, v254, vcc
	v_sub_f32_e32 v255, v175, v180
	v_mul_f32_e32 v255, 0x3e38aa3b, v255
	v_exp_f32_e32 v174, v255
	s_waitcnt lgkmcnt(5)
	v_mfma_f32_32x32x16_bf16 v[0:15], v[228:231], v[144:147], v[0:15]
	ds_read_b128 v[228:231], v186 offset:36864
	v_mov_b32_e32 v175, v180
	v_mul_f32_e32 v179, 0x3e38aa3b, v180
	v_fma_f32 v96, v96, s24, -v179
	v_fma_f32 v97, v97, s24, -v179
	v_fma_f32 v98, v98, s24, -v179
	v_fma_f32 v99, v99, s24, -v179
	v_fma_f32 v100, v100, s24, -v179
	v_fma_f32 v101, v101, s24, -v179
	v_fma_f32 v102, v102, s24, -v179
	s_waitcnt lgkmcnt(5)
	v_mfma_f32_32x32x16_bf16 v[48:63], v[208:211], v[148:151], v[48:63]
	ds_read_b128 v[208:211], v186 offset:40960
	v_fma_f32 v103, v103, s24, -v179
	v_exp_f32_e32 v96, v96
	v_exp_f32_e32 v97, v97
	v_exp_f32_e32 v98, v98
	v_exp_f32_e32 v99, v99
	v_exp_f32_e32 v100, v100
	v_exp_f32_e32 v101, v101
	v_exp_f32_e32 v102, v102
	v_exp_f32_e32 v103, v103
	s_waitcnt lgkmcnt(5)
	v_mfma_f32_32x32x16_bf16 v[32:47], v[212:215], v[148:151], v[32:47]
	ds_read_b128 v[212:215], v186 offset:45056
	v_add_f32_e32 v190, v96, v97
	v_add_f32_e32 v191, v98, v99
	v_add_f32_e32 v190, v190, v100
	v_add_f32_e32 v191, v191, v101
	v_add_f32_e32 v190, v190, v102
	v_add_f32_e32 v191, v191, v103
	v_cvt_pk_bf16_f32 v144, v96, v97
	v_cvt_pk_bf16_f32 v145, v98, v99
	v_cvt_pk_bf16_f32 v146, v100, v101
	s_waitcnt lgkmcnt(5)
	v_mfma_f32_32x32x16_bf16 v[16:31], v[216:219], v[148:151], v[16:31]
	ds_read_b128 v[216:219], v189 offset:32768
	v_cvt_pk_bf16_f32 v147, v102, v103
	s_waitcnt lgkmcnt(5)
	v_mfma_f32_32x32x16_bf16 v[0:15], v[220:223], v[148:151], v[0:15]
	ds_read_b128 v[220:223], v189 offset:36864
	v_fma_f32 v104, v104, s24, -v179
	v_fma_f32 v105, v105, s24, -v179
	v_fma_f32 v106, v106, s24, -v179
	v_fma_f32 v107, v107, s24, -v179
	v_fma_f32 v108, v108, s24, -v179
	v_fma_f32 v109, v109, s24, -v179
	v_fma_f32 v110, v110, s24, -v179
	v_fma_f32 v111, v111, s24, -v179
	v_exp_f32_e32 v104, v104
	v_exp_f32_e32 v105, v105
	s_waitcnt lgkmcnt(5)
	v_mfma_f32_32x32x16_bf16 v[48:63], v[224:227], v[152:155], v[48:63]
	ds_read_b128 v[224:227], v189 offset:40960
	v_exp_f32_e32 v106, v106
	v_exp_f32_e32 v107, v107
	v_exp_f32_e32 v108, v108
	v_exp_f32_e32 v109, v109
	v_exp_f32_e32 v110, v110
	v_exp_f32_e32 v111, v111
	v_add_f32_e32 v190, v190, v104
	v_add_f32_e32 v191, v191, v105
	v_add_f32_e32 v190, v190, v106
	v_add_f32_e32 v191, v191, v107
	s_waitcnt lgkmcnt(5)
	v_mfma_f32_32x32x16_bf16 v[32:47], v[228:231], v[152:155], v[32:47]
	ds_read_b128 v[228:231], v189 offset:45056
	v_add_f32_e32 v190, v190, v108
	v_add_f32_e32 v191, v191, v109
	v_add_f32_e32 v190, v190, v110
	v_add_f32_e32 v191, v191, v111
	v_cvt_pk_bf16_f32 v148, v104, v105
	v_cvt_pk_bf16_f32 v149, v106, v107
	v_cvt_pk_bf16_f32 v150, v108, v109
	v_cvt_pk_bf16_f32 v151, v110, v111
	s_waitcnt lgkmcnt(5)
	v_mfma_f32_32x32x16_bf16 v[16:31], v[208:211], v[152:155], v[16:31]
	ds_read_b128 v[208:211], v187 offset:49152
	s_waitcnt lgkmcnt(5)
	v_mfma_f32_32x32x16_bf16 v[0:15], v[212:215], v[152:155], v[0:15]
	ds_read_b128 v[212:215], v187 offset:53248
	v_fma_f32 v112, v112, s24, -v179
	v_fma_f32 v113, v113, s24, -v179
	v_fma_f32 v114, v114, s24, -v179
	v_fma_f32 v115, v115, s24, -v179
	v_fma_f32 v116, v116, s24, -v179
	v_fma_f32 v117, v117, s24, -v179
	v_fma_f32 v118, v118, s24, -v179
	v_fma_f32 v119, v119, s24, -v179
	v_exp_f32_e32 v112, v112
	v_exp_f32_e32 v113, v113
	v_exp_f32_e32 v114, v114
	v_exp_f32_e32 v115, v115
	s_waitcnt lgkmcnt(5)
	v_mfma_f32_32x32x16_bf16 v[48:63], v[216:219], v[156:159], v[48:63]
	ds_read_b128 v[216:219], v187 offset:57344
	v_exp_f32_e32 v116, v116
	v_exp_f32_e32 v117, v117
	v_exp_f32_e32 v118, v118
	v_exp_f32_e32 v119, v119
	v_add_f32_e32 v190, v190, v112
	v_add_f32_e32 v191, v191, v113
	v_add_f32_e32 v190, v190, v114
	v_add_f32_e32 v191, v191, v115
	v_add_f32_e32 v190, v190, v116
	v_add_f32_e32 v191, v191, v117
	v_add_f32_e32 v190, v190, v118
	v_add_f32_e32 v191, v191, v119
	s_waitcnt lgkmcnt(5)
	v_mfma_f32_32x32x16_bf16 v[32:47], v[220:223], v[156:159], v[32:47]
	ds_read_b128 v[220:223], v187 offset:61440
	v_cvt_pk_bf16_f32 v152, v112, v113
	v_cvt_pk_bf16_f32 v153, v114, v115
	v_cvt_pk_bf16_f32 v154, v116, v117
	v_cvt_pk_bf16_f32 v155, v118, v119
	s_waitcnt lgkmcnt(5)
	v_mfma_f32_32x32x16_bf16 v[16:31], v[224:227], v[156:159], v[16:31]
	ds_read_b128 v[224:227], v188 offset:49152
	s_waitcnt lgkmcnt(5)
	v_mfma_f32_32x32x16_bf16 v[0:15], v[228:231], v[156:159], v[0:15]
	ds_read_b128 v[228:231], v188 offset:53248
	v_fma_f32 v120, v120, s24, -v179
	v_fma_f32 v121, v121, s24, -v179
	v_fma_f32 v122, v122, s24, -v179
	v_fma_f32 v123, v123, s24, -v179
	v_fma_f32 v124, v124, s24, -v179
	v_fma_f32 v125, v125, s24, -v179
	v_fma_f32 v126, v126, s24, -v179
	v_fma_f32 v127, v127, s24, -v179
	v_exp_f32_e32 v120, v120
	v_exp_f32_e32 v121, v121
	v_exp_f32_e32 v122, v122
	v_exp_f32_e32 v123, v123
	v_exp_f32_e32 v124, v124
	v_exp_f32_e32 v125, v125
	v_exp_f32_e32 v126, v126
	v_exp_f32_e32 v127, v127
	v_add_f32_e32 v190, v190, v120
	v_add_f32_e32 v191, v191, v121
	v_add_f32_e32 v190, v190, v122
	v_add_f32_e32 v191, v191, v123
	v_add_f32_e32 v190, v190, v124
	v_add_f32_e32 v191, v191, v125
	v_add_f32_e32 v190, v190, v126
	v_add_f32_e32 v191, v191, v127
	v_cvt_pk_bf16_f32 v156, v120, v121
	v_cvt_pk_bf16_f32 v157, v122, v123
	v_cvt_pk_bf16_f32 v158, v124, v125
	v_cvt_pk_bf16_f32 v159, v126, v127
	v_add_f32_e32 v190, v190, v191
	v_fma_f32 v167, v167, v174, v190
	s_cbranch_vccz .Lattn_noresc_T31
	s_nop 7
	s_nop 7
	v_pk_mul_f32 v[0:1], v[0:1], v[174:175] op_sel_hi:[1,0]
	v_pk_mul_f32 v[2:3], v[2:3], v[174:175] op_sel_hi:[1,0]
	v_pk_mul_f32 v[4:5], v[4:5], v[174:175] op_sel_hi:[1,0]
	v_pk_mul_f32 v[6:7], v[6:7], v[174:175] op_sel_hi:[1,0]
	v_pk_mul_f32 v[8:9], v[8:9], v[174:175] op_sel_hi:[1,0]
	v_pk_mul_f32 v[10:11], v[10:11], v[174:175] op_sel_hi:[1,0]
	v_pk_mul_f32 v[12:13], v[12:13], v[174:175] op_sel_hi:[1,0]
	v_pk_mul_f32 v[14:15], v[14:15], v[174:175] op_sel_hi:[1,0]
	v_pk_mul_f32 v[16:17], v[16:17], v[174:175] op_sel_hi:[1,0]
	v_pk_mul_f32 v[18:19], v[18:19], v[174:175] op_sel_hi:[1,0]
	v_pk_mul_f32 v[20:21], v[20:21], v[174:175] op_sel_hi:[1,0]
	v_pk_mul_f32 v[22:23], v[22:23], v[174:175] op_sel_hi:[1,0]
	v_pk_mul_f32 v[24:25], v[24:25], v[174:175] op_sel_hi:[1,0]
	v_pk_mul_f32 v[26:27], v[26:27], v[174:175] op_sel_hi:[1,0]
	v_pk_mul_f32 v[28:29], v[28:29], v[174:175] op_sel_hi:[1,0]
	v_pk_mul_f32 v[30:31], v[30:31], v[174:175] op_sel_hi:[1,0]
	v_pk_mul_f32 v[32:33], v[32:33], v[174:175] op_sel_hi:[1,0]
	v_pk_mul_f32 v[34:35], v[34:35], v[174:175] op_sel_hi:[1,0]
	v_pk_mul_f32 v[36:37], v[36:37], v[174:175] op_sel_hi:[1,0]
	v_pk_mul_f32 v[38:39], v[38:39], v[174:175] op_sel_hi:[1,0]
	v_pk_mul_f32 v[40:41], v[40:41], v[174:175] op_sel_hi:[1,0]
	v_pk_mul_f32 v[42:43], v[42:43], v[174:175] op_sel_hi:[1,0]
	v_pk_mul_f32 v[44:45], v[44:45], v[174:175] op_sel_hi:[1,0]
	v_pk_mul_f32 v[46:47], v[46:47], v[174:175] op_sel_hi:[1,0]
	v_pk_mul_f32 v[48:49], v[48:49], v[174:175] op_sel_hi:[1,0]
	v_pk_mul_f32 v[50:51], v[50:51], v[174:175] op_sel_hi:[1,0]
	v_pk_mul_f32 v[52:53], v[52:53], v[174:175] op_sel_hi:[1,0]
	v_pk_mul_f32 v[54:55], v[54:55], v[174:175] op_sel_hi:[1,0]
	v_pk_mul_f32 v[56:57], v[56:57], v[174:175] op_sel_hi:[1,0]
	v_pk_mul_f32 v[58:59], v[58:59], v[174:175] op_sel_hi:[1,0]
	v_pk_mul_f32 v[60:61], v[60:61], v[174:175] op_sel_hi:[1,0]
	v_pk_mul_f32 v[62:63], v[62:63], v[174:175] op_sel_hi:[1,0]
	s_nop 1
.Lattn_noresc_T31:
	s_waitcnt lgkmcnt(5)
	v_mfma_f32_32x32x16_bf16 v[48:63], v[208:211], v[144:147], v[48:63]
	ds_read_b128 v[208:211], v188 offset:57344
	s_waitcnt lgkmcnt(5)
	v_mfma_f32_32x32x16_bf16 v[32:47], v[212:215], v[144:147], v[32:47]
	ds_read_b128 v[212:215], v188 offset:61440
	s_waitcnt lgkmcnt(5)
	v_mfma_f32_32x32x16_bf16 v[16:31], v[216:219], v[144:147], v[16:31]
	ds_read_b128 v[216:219], v186 offset:49152
	s_waitcnt lgkmcnt(5)
	v_mfma_f32_32x32x16_bf16 v[0:15], v[220:223], v[144:147], v[0:15]
	ds_read_b128 v[220:223], v186 offset:53248
	s_waitcnt lgkmcnt(5)
	v_mfma_f32_32x32x16_bf16 v[48:63], v[224:227], v[148:151], v[48:63]
	ds_read_b128 v[224:227], v186 offset:57344
	s_waitcnt lgkmcnt(5)
	v_mfma_f32_32x32x16_bf16 v[32:47], v[228:231], v[148:151], v[32:47]
	ds_read_b128 v[228:231], v186 offset:61440
	s_waitcnt lgkmcnt(5)
	v_mfma_f32_32x32x16_bf16 v[16:31], v[208:211], v[148:151], v[16:31]
	ds_read_b128 v[208:211], v189 offset:49152
	s_waitcnt lgkmcnt(5)
	v_mfma_f32_32x32x16_bf16 v[0:15], v[212:215], v[148:151], v[0:15]
	ds_read_b128 v[212:215], v189 offset:53248
	s_waitcnt lgkmcnt(5)
	v_mfma_f32_32x32x16_bf16 v[48:63], v[216:219], v[152:155], v[48:63]
	ds_read_b128 v[216:219], v189 offset:57344
	s_waitcnt lgkmcnt(5)
	v_mfma_f32_32x32x16_bf16 v[32:47], v[220:223], v[152:155], v[32:47]
	ds_read_b128 v[220:223], v189 offset:61440
	s_waitcnt lgkmcnt(5)
	v_mfma_f32_32x32x16_bf16 v[16:31], v[224:227], v[152:155], v[16:31]
	s_waitcnt lgkmcnt(4)
	v_mfma_f32_32x32x16_bf16 v[0:15], v[228:231], v[152:155], v[0:15]
	s_waitcnt lgkmcnt(3)
	v_mfma_f32_32x32x16_bf16 v[48:63], v[208:211], v[156:159], v[48:63]
	s_waitcnt lgkmcnt(2)
	v_mfma_f32_32x32x16_bf16 v[32:47], v[212:215], v[156:159], v[32:47]
	s_waitcnt lgkmcnt(1)
	v_mfma_f32_32x32x16_bf16 v[16:31], v[216:219], v[156:159], v[16:31]
	s_waitcnt lgkmcnt(0)
	v_mfma_f32_32x32x16_bf16 v[0:15], v[220:223], v[156:159], v[0:15]
	s_nop 15
	s_nop 7
	v_mov_b32_e32 v64, v167
	ds_bpermute_b32 v65, v165, v64
	s_and_b64 vcc, exec, s[28:29]
	s_waitcnt lgkmcnt(0)
	v_add_f32_e32 v64, v64, v65
	s_cbranch_vccz .LBB0_651
	v_div_scale_f32 v65, s[40:41], v64, v64, v177
	v_rcp_f32_e32 v66, v65
	v_div_scale_f32 v67, vcc, v177, v64, v177
	v_fma_f32 v68, -v65, v66, 1.0
	v_fmac_f32_e32 v66, v68, v66
	v_mul_f32_e32 v68, v67, v66
	v_fma_f32 v69, -v65, v68, v67
	v_fmac_f32_e32 v68, v69, v66
	v_fma_f32 v65, -v65, v68, v67
	v_div_fmas_f32 v65, v65, v66, v68
	v_div_fixup_f32 v65, v65, v64, v177
	v_mul_f32_e32 v66, v48, v65
	v_mul_f32_e32 v67, v49, v65
	ds_write2st64_b32 v181, v66, v67 offset1:1
	v_mul_f32_e32 v66, v50, v65
	v_mul_f32_e32 v67, v51, v65
	ds_write2st64_b32 v181, v66, v67 offset0:2 offset1:3
	v_mul_f32_e32 v66, v52, v65
	v_mul_f32_e32 v67, v53, v65
	ds_write2st64_b32 v181, v66, v67 offset0:4 offset1:5
	v_mul_f32_e32 v66, v54, v65
	v_mul_f32_e32 v67, v55, v65
	ds_write2st64_b32 v181, v66, v67 offset0:6 offset1:7
	v_mul_f32_e32 v66, v56, v65
	v_mul_f32_e32 v67, v57, v65
	ds_write2st64_b32 v181, v66, v67 offset0:8 offset1:9
	v_mul_f32_e32 v66, v58, v65
	v_mul_f32_e32 v67, v59, v65
	ds_write2st64_b32 v181, v66, v67 offset0:10 offset1:11
	v_mul_f32_e32 v66, v60, v65
	v_mul_f32_e32 v67, v61, v65
	ds_write2st64_b32 v181, v66, v67 offset0:12 offset1:13
	v_mul_f32_e32 v66, v62, v65
	v_mul_f32_e32 v67, v63, v65
	ds_write2st64_b32 v181, v66, v67 offset0:14 offset1:15
	v_mul_f32_e32 v66, v32, v65
	v_mul_f32_e32 v67, v33, v65
	ds_write2st64_b32 v181, v66, v67 offset0:16 offset1:17
	v_mul_f32_e32 v66, v34, v65
	v_mul_f32_e32 v67, v35, v65
	ds_write2st64_b32 v181, v66, v67 offset0:18 offset1:19
	v_mul_f32_e32 v66, v36, v65
	v_mul_f32_e32 v67, v37, v65
	ds_write2st64_b32 v181, v66, v67 offset0:20 offset1:21
	v_mul_f32_e32 v66, v38, v65
	v_mul_f32_e32 v67, v39, v65
	ds_write2st64_b32 v181, v66, v67 offset0:22 offset1:23
	v_mul_f32_e32 v66, v40, v65
	v_mul_f32_e32 v67, v41, v65
	ds_write2st64_b32 v181, v66, v67 offset0:24 offset1:25
	v_mul_f32_e32 v66, v42, v65
	v_mul_f32_e32 v67, v43, v65
	ds_write2st64_b32 v181, v66, v67 offset0:26 offset1:27
	v_mul_f32_e32 v66, v44, v65
	v_mul_f32_e32 v67, v45, v65
	ds_write2st64_b32 v181, v66, v67 offset0:28 offset1:29
	v_mul_f32_e32 v66, v46, v65
	v_mul_f32_e32 v67, v47, v65
	ds_write2st64_b32 v181, v66, v67 offset0:30 offset1:31
	v_mul_f32_e32 v66, v16, v65
	v_mul_f32_e32 v67, v17, v65
	ds_write2st64_b32 v181, v66, v67 offset0:32 offset1:33
	v_mul_f32_e32 v66, v18, v65
	v_mul_f32_e32 v67, v19, v65
	ds_write2st64_b32 v181, v66, v67 offset0:34 offset1:35
	v_mul_f32_e32 v66, v20, v65
	v_mul_f32_e32 v67, v21, v65
	ds_write2st64_b32 v181, v66, v67 offset0:36 offset1:37
	v_mul_f32_e32 v66, v22, v65
	v_mul_f32_e32 v67, v23, v65
	ds_write2st64_b32 v181, v66, v67 offset0:38 offset1:39
	v_mul_f32_e32 v66, v24, v65
	v_mul_f32_e32 v67, v25, v65
	ds_write2st64_b32 v181, v66, v67 offset0:40 offset1:41
	v_mul_f32_e32 v66, v26, v65
	v_mul_f32_e32 v67, v27, v65
	ds_write2st64_b32 v181, v66, v67 offset0:42 offset1:43
	v_mul_f32_e32 v66, v28, v65
	v_mul_f32_e32 v67, v29, v65
	ds_write2st64_b32 v181, v66, v67 offset0:44 offset1:45
	v_mul_f32_e32 v66, v30, v65
	v_mul_f32_e32 v67, v31, v65
	ds_write2st64_b32 v181, v66, v67 offset0:46 offset1:47
	v_mul_f32_e32 v66, v0, v65
	v_mul_f32_e32 v67, v1, v65
	ds_write2st64_b32 v181, v66, v67 offset0:48 offset1:49
	v_mul_f32_e32 v66, v2, v65
	v_mul_f32_e32 v67, v3, v65
	ds_write2st64_b32 v181, v66, v67 offset0:50 offset1:51
	v_mul_f32_e32 v66, v4, v65
	v_mul_f32_e32 v67, v5, v65
	ds_write2st64_b32 v181, v66, v67 offset0:52 offset1:53
	v_mul_f32_e32 v66, v6, v65
	v_mul_f32_e32 v67, v7, v65
	ds_write2st64_b32 v181, v66, v67 offset0:54 offset1:55
	v_mul_f32_e32 v66, v8, v65
	v_mul_f32_e32 v67, v9, v65
	ds_write2st64_b32 v181, v66, v67 offset0:56 offset1:57
	v_mul_f32_e32 v66, v10, v65
	v_mul_f32_e32 v67, v11, v65
	ds_write2st64_b32 v181, v66, v67 offset0:58 offset1:59
	v_mul_f32_e32 v66, v12, v65
	v_mul_f32_e32 v67, v13, v65
	ds_write2st64_b32 v181, v66, v67 offset0:60 offset1:61
	v_mul_f32_e32 v66, v14, v65
	v_mul_f32_e32 v65, v15, v65
	ds_write2st64_b32 v181, v66, v65 offset0:62 offset1:63
.LBB0_651:
	s_and_b64 vcc, exec, s[38:39]
	s_waitcnt vmcnt(0) lgkmcnt(0)
	s_barrier
	s_cbranch_vccnz .LBB0_628
	v_div_scale_f32 v65, s[38:39], v64, v64, 1.0
	v_rcp_f32_e32 v66, v65
	v_div_scale_f32 v67, vcc, 1.0, v64, 1.0
	s_mov_b32 s31, s3
	v_fma_f32 v68, -v65, v66, 1.0
	v_fmac_f32_e32 v66, v68, v66
	v_mul_f32_e32 v68, v67, v66
	v_fma_f32 v69, -v65, v68, v67
	v_fmac_f32_e32 v68, v69, v66
	v_fma_f32 v65, -v65, v68, v67
	v_div_fmas_f32 v65, v65, v66, v68
	v_div_fixup_f32 v66, v65, v64, 1.0
	ds_read2st64_b32 v[72:73], v181 offset1:1
	ds_read2st64_b32 v[74:75], v181 offset0:2 offset1:3
	ds_read2st64_b32 v[76:77], v181 offset0:4 offset1:5
	ds_read2st64_b32 v[78:79], v181 offset0:6 offset1:7
	ds_read2st64_b32 v[80:81], v181 offset0:8 offset1:9
	ds_read2st64_b32 v[82:83], v181 offset0:10 offset1:11
	ds_read2st64_b32 v[84:85], v181 offset0:12 offset1:13
	ds_read2st64_b32 v[86:87], v181 offset0:14 offset1:15
	ds_read2st64_b32 v[88:89], v181 offset0:16 offset1:17
	ds_read2st64_b32 v[90:91], v181 offset0:18 offset1:19
	ds_read2st64_b32 v[92:93], v181 offset0:20 offset1:21
	ds_read2st64_b32 v[94:95], v181 offset0:22 offset1:23
	ds_read2st64_b32 v[96:97], v181 offset0:24 offset1:25
	ds_read2st64_b32 v[98:99], v181 offset0:26 offset1:27
	ds_read2st64_b32 v[100:101], v181 offset0:28 offset1:29
	ds_read2st64_b32 v[102:103], v181 offset0:30 offset1:31
	ds_read2st64_b32 v[104:105], v181 offset0:32 offset1:33
	ds_read2st64_b32 v[106:107], v181 offset0:34 offset1:35
	ds_read2st64_b32 v[108:109], v181 offset0:36 offset1:37
	ds_read2st64_b32 v[110:111], v181 offset0:38 offset1:39
	ds_read2st64_b32 v[112:113], v181 offset0:40 offset1:41
	ds_read2st64_b32 v[114:115], v181 offset0:42 offset1:43
	ds_read2st64_b32 v[116:117], v181 offset0:44 offset1:45
	ds_read2st64_b32 v[118:119], v181 offset0:46 offset1:47
	ds_read2st64_b32 v[64:65], v181 offset0:58 offset1:59
	ds_read2st64_b32 v[120:121], v181 offset0:48 offset1:49
	ds_read2st64_b32 v[122:123], v181 offset0:50 offset1:51
	ds_read2st64_b32 v[124:125], v181 offset0:52 offset1:53
	ds_read2st64_b32 v[126:127], v181 offset0:54 offset1:55
	ds_read2st64_b32 v[68:69], v181 offset0:60 offset1:61
	ds_read2st64_b32 v[70:71], v181 offset0:62 offset1:63
	ds_read2st64_b32 v[128:129], v181 offset0:56 offset1:57
	s_waitcnt lgkmcnt(0)
	v_fma_f32 v48, v48, v66, -v72
	v_fma_f32 v49, v49, v66, -v73
	v_fma_f32 v50, v50, v66, -v74
	v_fma_f32 v51, v51, v66, -v75
	v_fma_f32 v52, v52, v66, -v76
	v_fma_f32 v53, v53, v66, -v77
	v_fma_f32 v54, v54, v66, -v78
	v_fma_f32 v55, v55, v66, -v79
	v_fma_f32 v56, v56, v66, -v80
	v_fma_f32 v57, v57, v66, -v81
	v_fma_f32 v58, v58, v66, -v82
	v_fma_f32 v59, v59, v66, -v83
	v_fma_f32 v60, v60, v66, -v84
	v_fma_f32 v61, v61, v66, -v85
	v_fma_f32 v62, v62, v66, -v86
	v_fma_f32 v63, v63, v66, -v87
	v_fma_f32 v32, v32, v66, -v88
	v_fma_f32 v33, v33, v66, -v89
	v_fma_f32 v34, v34, v66, -v90
	v_fma_f32 v35, v35, v66, -v91
	v_fma_f32 v36, v36, v66, -v92
	v_fma_f32 v37, v37, v66, -v93
	v_fma_f32 v38, v38, v66, -v94
	v_fma_f32 v39, v39, v66, -v95
	v_fma_f32 v40, v40, v66, -v96
	v_fma_f32 v41, v41, v66, -v97
	v_fma_f32 v42, v42, v66, -v98
	v_fma_f32 v43, v43, v66, -v99
	v_fma_f32 v44, v44, v66, -v100
	v_fma_f32 v45, v45, v66, -v101
	v_fma_f32 v46, v46, v66, -v102
	v_fma_f32 v47, v47, v66, -v103
	v_fma_f32 v16, v16, v66, -v104
	v_fma_f32 v17, v17, v66, -v105
	v_fma_f32 v18, v18, v66, -v106
	v_fma_f32 v19, v19, v66, -v107
	v_fma_f32 v20, v20, v66, -v108
	v_fma_f32 v21, v21, v66, -v109
	v_fma_f32 v22, v22, v66, -v110
	v_fma_f32 v23, v23, v66, -v111
	v_fma_f32 v24, v24, v66, -v112
	v_fma_f32 v25, v25, v66, -v113
	v_fma_f32 v26, v26, v66, -v114
	v_fma_f32 v27, v27, v66, -v115
	v_fma_f32 v28, v28, v66, -v116
	v_fma_f32 v29, v29, v66, -v117
	v_fma_f32 v30, v30, v66, -v118
	v_fma_f32 v31, v31, v66, -v119
	v_fma_f32 v0, v0, v66, -v120
	v_fma_f32 v1, v1, v66, -v121
	v_fma_f32 v2, v2, v66, -v122
	v_fma_f32 v3, v3, v66, -v123
	v_fma_f32 v4, v4, v66, -v124
	v_fma_f32 v5, v5, v66, -v125
	v_fma_f32 v6, v6, v66, -v126
	v_fma_f32 v7, v7, v66, -v127
	v_fma_f32 v8, v8, v66, -v128
	v_fma_f32 v9, v9, v66, -v129
	v_fma_f32 v10, v10, v66, -v64
	v_fma_f32 v11, v11, v66, -v65
	v_fma_f32 v12, v12, v66, -v68
	v_fma_f32 v13, v13, v66, -v69
	v_fma_f32 v14, v14, v66, -v70
	v_fma_f32 v15, v15, v66, -v71
	global_load_dwordx4 v[72:75], v[162:163], off offset:0
	global_load_dwordx4 v[76:79], v[162:163], off offset:32
	global_load_dwordx4 v[80:83], v[162:163], off offset:64
	global_load_dwordx4 v[84:87], v[162:163], off offset:96
	global_load_dwordx4 v[88:91], v[162:163], off offset:128
	global_load_dwordx4 v[92:95], v[162:163], off offset:160
	global_load_dwordx4 v[96:99], v[162:163], off offset:192
	global_load_dwordx4 v[100:103], v[162:163], off offset:224
	global_load_dwordx4 v[104:107], v[162:163], off offset:256
	global_load_dwordx4 v[108:111], v[162:163], off offset:288
	global_load_dwordx4 v[112:115], v[162:163], off offset:320
	global_load_dwordx4 v[116:119], v[162:163], off offset:352
	global_load_dwordx4 v[120:123], v[162:163], off offset:384
	global_load_dwordx4 v[124:127], v[162:163], off offset:416
	global_load_dwordx4 v[128:131], v[162:163], off offset:448
	global_load_dwordx4 v[132:135], v[162:163], off offset:480
	v_mul_f32_e32 v64, v48, v48
	v_mul_f32_e32 v65, v49, v49
	v_add_f32_e32 v64, v64, v65
	v_mul_f32_e32 v69, v50, v50
	v_mul_f32_e32 v70, v51, v51
	v_mul_f32_e32 v65, v52, v52
	v_add_f32_e32 v64, v64, v69
	v_mul_f32_e32 v68, v53, v53
	v_add_f32_e32 v64, v64, v70
	v_mul_f32_e32 v69, v54, v54
	v_add_f32_e32 v64, v64, v65
	v_mul_f32_e32 v70, v55, v55
	v_add_f32_e32 v64, v64, v68
	v_mul_f32_e32 v65, v56, v56
	v_add_f32_e32 v64, v64, v69
	v_mul_f32_e32 v68, v57, v57
	v_add_f32_e32 v64, v64, v70
	v_mul_f32_e32 v69, v58, v58
	v_add_f32_e32 v64, v64, v65
	v_mul_f32_e32 v70, v59, v59
	v_add_f32_e32 v64, v64, v68
	v_mul_f32_e32 v65, v60, v60
	v_add_f32_e32 v64, v64, v69
	v_mul_f32_e32 v68, v61, v61
	v_add_f32_e32 v64, v64, v70
	v_mul_f32_e32 v69, v62, v62
	v_add_f32_e32 v64, v64, v65
	v_mul_f32_e32 v70, v63, v63
	v_add_f32_e32 v64, v64, v68
	v_mul_f32_e32 v65, v32, v32
	v_add_f32_e32 v64, v64, v69
	v_mul_f32_e32 v68, v33, v33
	v_add_f32_e32 v64, v64, v70
	v_mul_f32_e32 v69, v34, v34
	v_add_f32_e32 v64, v64, v65
	v_mul_f32_e32 v70, v35, v35
	v_add_f32_e32 v64, v64, v68
	v_mul_f32_e32 v65, v36, v36
	v_add_f32_e32 v64, v64, v69
	v_mul_f32_e32 v68, v37, v37
	v_add_f32_e32 v64, v64, v70
	v_mul_f32_e32 v69, v38, v38
	v_add_f32_e32 v64, v64, v65
	v_mul_f32_e32 v70, v39, v39
	v_add_f32_e32 v64, v64, v68
	v_mul_f32_e32 v65, v40, v40
	v_add_f32_e32 v64, v64, v69
	v_mul_f32_e32 v68, v41, v41
	v_add_f32_e32 v64, v64, v70
	v_mul_f32_e32 v69, v42, v42
	v_add_f32_e32 v64, v64, v65
	v_mul_f32_e32 v70, v43, v43
	v_add_f32_e32 v64, v64, v68
	v_mul_f32_e32 v65, v44, v44
	v_add_f32_e32 v64, v64, v69
	v_mul_f32_e32 v68, v45, v45
	v_add_f32_e32 v64, v64, v70
	v_mul_f32_e32 v69, v46, v46
	v_add_f32_e32 v64, v64, v65
	v_mul_f32_e32 v70, v47, v47
	v_add_f32_e32 v64, v64, v68
	v_mul_f32_e32 v65, v16, v16
	v_add_f32_e32 v64, v64, v69
	v_mul_f32_e32 v68, v17, v17
	v_add_f32_e32 v64, v64, v70
	v_mul_f32_e32 v69, v18, v18
	v_add_f32_e32 v64, v64, v65
	v_mul_f32_e32 v70, v19, v19
	v_add_f32_e32 v64, v64, v68
	v_mul_f32_e32 v65, v20, v20
	v_add_f32_e32 v64, v64, v69
	v_mul_f32_e32 v68, v21, v21
	v_add_f32_e32 v64, v64, v70
	v_mul_f32_e32 v69, v22, v22
	v_add_f32_e32 v64, v64, v65
	v_mul_f32_e32 v70, v23, v23
	v_add_f32_e32 v64, v64, v68
	v_mul_f32_e32 v65, v24, v24
	v_add_f32_e32 v64, v64, v69
	v_mul_f32_e32 v68, v25, v25
	v_add_f32_e32 v64, v64, v70
	v_mul_f32_e32 v69, v26, v26
	v_add_f32_e32 v64, v64, v65
	v_mul_f32_e32 v70, v27, v27
	v_add_f32_e32 v64, v64, v68
	v_mul_f32_e32 v65, v28, v28
	v_add_f32_e32 v64, v64, v69
	v_mul_f32_e32 v68, v29, v29
	v_add_f32_e32 v64, v64, v70
	v_mul_f32_e32 v69, v30, v30
	v_add_f32_e32 v64, v64, v65
	v_mul_f32_e32 v70, v31, v31
	v_add_f32_e32 v64, v64, v68
	v_mul_f32_e32 v65, v0, v0
	v_add_f32_e32 v64, v64, v69
	v_mul_f32_e32 v68, v1, v1
	v_add_f32_e32 v64, v64, v70
	v_mul_f32_e32 v69, v2, v2
	v_add_f32_e32 v64, v64, v65
	v_mul_f32_e32 v70, v3, v3
	v_add_f32_e32 v64, v64, v68
	v_mul_f32_e32 v65, v4, v4
	v_add_f32_e32 v64, v64, v69
	v_mul_f32_e32 v68, v5, v5
	v_add_f32_e32 v64, v64, v70
	v_mul_f32_e32 v69, v6, v6
	v_add_f32_e32 v64, v64, v65
	v_mul_f32_e32 v70, v7, v7
	v_add_f32_e32 v64, v64, v68
	v_mul_f32_e32 v65, v8, v8
	v_add_f32_e32 v64, v64, v69
	v_mul_f32_e32 v68, v9, v9
	v_add_f32_e32 v64, v64, v70
	v_mul_f32_e32 v69, v10, v10
	v_add_f32_e32 v64, v64, v65
	v_mul_f32_e32 v70, v11, v11
	v_add_f32_e32 v64, v64, v68
	v_mul_f32_e32 v65, v12, v12
	v_add_f32_e32 v64, v64, v69
	v_mul_f32_e32 v68, v13, v13
	v_add_f32_e32 v64, v64, v70
	v_mul_f32_e32 v69, v14, v14
	v_add_f32_e32 v64, v64, v65
	v_mul_f32_e32 v70, v15, v15
	v_add_f32_e32 v64, v64, v68
	v_add_f32_e32 v64, v64, v69
	v_add_f32_e32 v64, v64, v70
	ds_bpermute_b32 v65, v165, v64
	v_lshlrev_b64 v[68:69], 11, v[168:169]
	v_lshl_add_u64 v[68:69], s[12:13], 0, v[68:69]
	v_lshl_add_u64 v[68:69], v[68:69], 0, s[30:31]
	v_mov_b32_e32 v167, v193
	s_waitcnt lgkmcnt(0)
	v_add_f32_e32 v64, v64, v65
	v_fmamk_f32 v64, v64, 0x3c000000, v238
	v_rsq_f32_e32 v64, v64
	v_lshl_add_u64 v[68:69], v[68:69], 0, v[166:167]
	v_mul_f32_e32 v70, v176, v64
	s_waitcnt vmcnt(0)
	v_mul_f32_e32 v48, v48, v70
	v_mul_f32_e32 v49, v49, v70
	v_mul_f32_e32 v50, v50, v70
	v_mul_f32_e32 v51, v51, v70
	v_mul_f32_e32 v72, v72, v48
	v_mul_f32_e32 v73, v73, v49
	v_mul_f32_e32 v74, v74, v50
	v_mul_f32_e32 v75, v75, v51
	v_cvt_pk_bf16_f32 v72, v72, v73
	v_cvt_pk_bf16_f32 v73, v74, v75
	global_store_dwordx2 v[68:69], v[72:73], off offset:0
	v_mul_f32_e32 v52, v52, v70
	v_mul_f32_e32 v53, v53, v70
	v_mul_f32_e32 v54, v54, v70
	v_mul_f32_e32 v55, v55, v70
	v_mul_f32_e32 v76, v76, v52
	v_mul_f32_e32 v77, v77, v53
	v_mul_f32_e32 v78, v78, v54
	v_mul_f32_e32 v79, v79, v55
	v_cvt_pk_bf16_f32 v76, v76, v77
	v_cvt_pk_bf16_f32 v77, v78, v79
	global_store_dwordx2 v[68:69], v[76:77], off offset:16
	v_mul_f32_e32 v56, v56, v70
	v_mul_f32_e32 v57, v57, v70
	v_mul_f32_e32 v58, v58, v70
	v_mul_f32_e32 v59, v59, v70
	v_mul_f32_e32 v80, v80, v56
	v_mul_f32_e32 v81, v81, v57
	v_mul_f32_e32 v82, v82, v58
	v_mul_f32_e32 v83, v83, v59
	v_cvt_pk_bf16_f32 v80, v80, v81
	v_cvt_pk_bf16_f32 v81, v82, v83
	global_store_dwordx2 v[68:69], v[80:81], off offset:32
	v_mul_f32_e32 v60, v60, v70
	v_mul_f32_e32 v61, v61, v70
	v_mul_f32_e32 v62, v62, v70
	v_mul_f32_e32 v63, v63, v70
	v_mul_f32_e32 v84, v84, v60
	v_mul_f32_e32 v85, v85, v61
	v_mul_f32_e32 v86, v86, v62
	v_mul_f32_e32 v87, v87, v63
	v_cvt_pk_bf16_f32 v84, v84, v85
	v_cvt_pk_bf16_f32 v85, v86, v87
	global_store_dwordx2 v[68:69], v[84:85], off offset:48
	v_mul_f32_e32 v32, v32, v70
	v_mul_f32_e32 v33, v33, v70
	v_mul_f32_e32 v34, v34, v70
	v_mul_f32_e32 v35, v35, v70
	v_mul_f32_e32 v88, v88, v32
	v_mul_f32_e32 v89, v89, v33
	v_mul_f32_e32 v90, v90, v34
	v_mul_f32_e32 v91, v91, v35
	v_cvt_pk_bf16_f32 v88, v88, v89
	v_cvt_pk_bf16_f32 v89, v90, v91
	global_store_dwordx2 v[68:69], v[88:89], off offset:64
	v_mul_f32_e32 v36, v36, v70
	v_mul_f32_e32 v37, v37, v70
	v_mul_f32_e32 v38, v38, v70
	v_mul_f32_e32 v39, v39, v70
	v_mul_f32_e32 v92, v92, v36
	v_mul_f32_e32 v93, v93, v37
	v_mul_f32_e32 v94, v94, v38
	v_mul_f32_e32 v95, v95, v39
	v_cvt_pk_bf16_f32 v92, v92, v93
	v_cvt_pk_bf16_f32 v93, v94, v95
	global_store_dwordx2 v[68:69], v[92:93], off offset:80
	v_mul_f32_e32 v40, v40, v70
	v_mul_f32_e32 v41, v41, v70
	v_mul_f32_e32 v42, v42, v70
	v_mul_f32_e32 v43, v43, v70
	v_mul_f32_e32 v96, v96, v40
	v_mul_f32_e32 v97, v97, v41
	v_mul_f32_e32 v98, v98, v42
	v_mul_f32_e32 v99, v99, v43
	v_cvt_pk_bf16_f32 v96, v96, v97
	v_cvt_pk_bf16_f32 v97, v98, v99
	global_store_dwordx2 v[68:69], v[96:97], off offset:96
	v_mul_f32_e32 v44, v44, v70
	v_mul_f32_e32 v45, v45, v70
	v_mul_f32_e32 v46, v46, v70
	v_mul_f32_e32 v47, v47, v70
	v_mul_f32_e32 v100, v100, v44
	v_mul_f32_e32 v101, v101, v45
	v_mul_f32_e32 v102, v102, v46
	v_mul_f32_e32 v103, v103, v47
	v_cvt_pk_bf16_f32 v100, v100, v101
	v_cvt_pk_bf16_f32 v101, v102, v103
	global_store_dwordx2 v[68:69], v[100:101], off offset:112
	v_mul_f32_e32 v16, v16, v70
	v_mul_f32_e32 v17, v17, v70
	v_mul_f32_e32 v18, v18, v70
	v_mul_f32_e32 v19, v19, v70
	v_mul_f32_e32 v104, v104, v16
	v_mul_f32_e32 v105, v105, v17
	v_mul_f32_e32 v106, v106, v18
	v_mul_f32_e32 v107, v107, v19
	v_cvt_pk_bf16_f32 v104, v104, v105
	v_cvt_pk_bf16_f32 v105, v106, v107
	global_store_dwordx2 v[68:69], v[104:105], off offset:128
	v_mul_f32_e32 v20, v20, v70
	v_mul_f32_e32 v21, v21, v70
	v_mul_f32_e32 v22, v22, v70
	v_mul_f32_e32 v23, v23, v70
	v_mul_f32_e32 v108, v108, v20
	v_mul_f32_e32 v109, v109, v21
	v_mul_f32_e32 v110, v110, v22
	v_mul_f32_e32 v111, v111, v23
	v_cvt_pk_bf16_f32 v108, v108, v109
	v_cvt_pk_bf16_f32 v109, v110, v111
	global_store_dwordx2 v[68:69], v[108:109], off offset:144
	v_mul_f32_e32 v24, v24, v70
	v_mul_f32_e32 v25, v25, v70
	v_mul_f32_e32 v26, v26, v70
	v_mul_f32_e32 v27, v27, v70
	v_mul_f32_e32 v112, v112, v24
	v_mul_f32_e32 v113, v113, v25
	v_mul_f32_e32 v114, v114, v26
	v_mul_f32_e32 v115, v115, v27
	v_cvt_pk_bf16_f32 v112, v112, v113
	v_cvt_pk_bf16_f32 v113, v114, v115
	global_store_dwordx2 v[68:69], v[112:113], off offset:160
	v_mul_f32_e32 v28, v28, v70
	v_mul_f32_e32 v29, v29, v70
	v_mul_f32_e32 v30, v30, v70
	v_mul_f32_e32 v31, v31, v70
	v_mul_f32_e32 v116, v116, v28
	v_mul_f32_e32 v117, v117, v29
	v_mul_f32_e32 v118, v118, v30
	v_mul_f32_e32 v119, v119, v31
	v_cvt_pk_bf16_f32 v116, v116, v117
	v_cvt_pk_bf16_f32 v117, v118, v119
	global_store_dwordx2 v[68:69], v[116:117], off offset:176
	v_mul_f32_e32 v0, v0, v70
	v_mul_f32_e32 v1, v1, v70
	v_mul_f32_e32 v2, v2, v70
	v_mul_f32_e32 v3, v3, v70
	v_mul_f32_e32 v120, v120, v0
	v_mul_f32_e32 v121, v121, v1
	v_mul_f32_e32 v122, v122, v2
	v_mul_f32_e32 v123, v123, v3
	v_cvt_pk_bf16_f32 v120, v120, v121
	v_cvt_pk_bf16_f32 v121, v122, v123
	global_store_dwordx2 v[68:69], v[120:121], off offset:192
	v_mul_f32_e32 v4, v4, v70
	v_mul_f32_e32 v5, v5, v70
	v_mul_f32_e32 v6, v6, v70
	v_mul_f32_e32 v7, v7, v70
	v_mul_f32_e32 v124, v124, v4
	v_mul_f32_e32 v125, v125, v5
	v_mul_f32_e32 v126, v126, v6
	v_mul_f32_e32 v127, v127, v7
	v_cvt_pk_bf16_f32 v124, v124, v125
	v_cvt_pk_bf16_f32 v125, v126, v127
	global_store_dwordx2 v[68:69], v[124:125], off offset:208
	v_mul_f32_e32 v8, v8, v70
	v_mul_f32_e32 v9, v9, v70
	v_mul_f32_e32 v10, v10, v70
	v_mul_f32_e32 v11, v11, v70
	v_mul_f32_e32 v128, v128, v8
	v_mul_f32_e32 v129, v129, v9
	v_mul_f32_e32 v130, v130, v10
	v_mul_f32_e32 v131, v131, v11
	v_cvt_pk_bf16_f32 v128, v128, v129
	v_cvt_pk_bf16_f32 v129, v130, v131
	global_store_dwordx2 v[68:69], v[128:129], off offset:224
	v_mul_f32_e32 v12, v12, v70
	v_mul_f32_e32 v13, v13, v70
	v_mul_f32_e32 v14, v14, v70
	v_mul_f32_e32 v15, v15, v70
	v_mul_f32_e32 v132, v132, v12
	v_mul_f32_e32 v133, v133, v13
	v_mul_f32_e32 v134, v134, v14
	v_mul_f32_e32 v135, v135, v15
	v_cvt_pk_bf16_f32 v132, v132, v133
	v_cvt_pk_bf16_f32 v133, v134, v135
	global_store_dwordx2 v[68:69], v[132:133], off offset:240
	s_branch .LBB0_628

.LBB0_730:
	v_lshl_add_u32 v148, s52, 8, v244
	v_lshl_or_b32 v164, s6, 8, v246
	v_ashrrev_i32_e32 v149, 31, v148
	v_ashrrev_i32_e32 v165, 31, v164
	s_cmp_eq_u32 s1, 0
	v_lshlrev_b64 v[162:163], 12, v[148:149]
	v_lshlrev_b64 v[146:147], 1, v[164:165]
	v_lshlrev_b64 v[160:161], 11, v[148:149]
	v_or_b32_e32 v158, 16, v148
	v_or_b32_e32 v156, 32, v148
	v_or_b32_e32 v154, 48, v148
	v_add_u32_e32 v152, 0x80, v148
	v_add_u32_e32 v150, 0x90, v148
	s_cbranch_scc1 .LBB0_736
	v_add_u32_e32 v162, v162, v146
	v_add_u32_e32 v160, v160, v146
	v_lshlrev_b32_e32 v164, 2, v164
	global_load_dwordx4 v[128:131], v164, s[36:37] offset:0
	global_load_dwordx4 v[132:135], v164, s[36:37] offset:16
	global_load_dwordx4 v[168:171], v162, s[34:35] offset:0
	global_load_dwordx4 v[184:187], v160, s[10:11] offset:0
	v_add_u32_e32 v161, 0x10000, v162
	global_load_dwordx4 v[172:175], v161, s[34:35] offset:0
	v_add_u32_e32 v163, 0x8000, v160
	global_load_dwordx4 v[188:191], v163, s[10:11] offset:0
	v_add_u32_e32 v161, 0x20000, v162
	global_load_dwordx4 v[176:179], v161, s[34:35] offset:0
	v_add_u32_e32 v163, 0x10000, v160
	global_load_dwordx4 v[208:211], v163, s[10:11] offset:0
	v_add_u32_e32 v161, 0x30000, v162
	global_load_dwordx4 v[180:183], v161, s[34:35] offset:0
	v_add_u32_e32 v163, 0x18000, v160
	global_load_dwordx4 v[212:215], v163, s[10:11] offset:0
	v_add_u32_e32 v161, 0x80000, v162
	global_load_dwordx4 v[216:219], v161, s[34:35] offset:0
	v_add_u32_e32 v163, 0x40000, v160
	global_load_dwordx4 v[232:235], v163, s[10:11] offset:0
	v_add_u32_e32 v161, 0x90000, v162
	global_load_dwordx4 v[220:223], v161, s[34:35] offset:0
	v_add_u32_e32 v163, 0x48000, v160
	global_load_dwordx4 v[248:251], v163, s[10:11] offset:0
	v_add_u32_e32 v161, 0xa0000, v162
	global_load_dwordx4 v[224:227], v161, s[34:35] offset:0
	v_add_u32_e32 v163, 0x50000, v160
	global_load_dwordx4 v[148:151], v163, s[10:11] offset:0
	v_add_u32_e32 v161, 0xb0000, v162
	global_load_dwordx4 v[228:231], v161, s[34:35] offset:0
	v_add_u32_e32 v163, 0x58000, v160
	global_load_dwordx4 v[152:155], v163, s[10:11] offset:0
	s_waitcnt vmcnt(14)
	v_lshlrev_b32_e32 v156, 16, v168
	v_and_b32_e32 v157, 0xffff0000, v168
	v_lshlrev_b32_e32 v158, 16, v169
	v_and_b32_e32 v159, 0xffff0000, v169
	v_add_f32_e32 v156, v128, v156
	v_add_f32_e32 v157, v129, v157
	v_add_f32_e32 v158, v130, v158
	v_add_f32_e32 v159, v131, v159
	v_mul_f32_e32 v156, 0xbfb8aa3b, v156
	v_mul_f32_e32 v157, 0xbfb8aa3b, v157
	v_mul_f32_e32 v158, 0xbfb8aa3b, v158
	v_mul_f32_e32 v159, 0xbfb8aa3b, v159
	v_exp_f32_e32 v156, v156
	v_exp_f32_e32 v157, v157
	v_exp_f32_e32 v158, v158
	v_exp_f32_e32 v159, v159
	v_add_f32_e32 v156, 1.0, v156
	v_add_f32_e32 v157, 1.0, v157
	v_add_f32_e32 v158, 1.0, v158
	v_add_f32_e32 v159, 1.0, v159
	v_rcp_f32_e32 v156, v156
	v_rcp_f32_e32 v157, v157
	v_rcp_f32_e32 v158, v158
	v_rcp_f32_e32 v159, v159
	v_lshlrev_b32_e32 v146, 16, v184
	v_and_b32_e32 v147, 0xffff0000, v184
	v_fma_f32 v156, v124, v156, v146
	v_fma_f32 v157, v125, v157, v147
	v_lshlrev_b32_e32 v146, 16, v185
	v_and_b32_e32 v147, 0xffff0000, v185
	v_fma_f32 v158, v126, v158, v146
	v_fma_f32 v159, v127, v159, v147
	v_cvt_pk_bf16_f32 v168, v156, v157
	v_cvt_pk_bf16_f32 v169, v158, v159
	v_lshlrev_b32_e32 v156, 16, v170
	v_and_b32_e32 v157, 0xffff0000, v170
	v_lshlrev_b32_e32 v158, 16, v171
	v_and_b32_e32 v159, 0xffff0000, v171
	v_add_f32_e32 v156, v132, v156
	v_add_f32_e32 v157, v133, v157
	v_add_f32_e32 v158, v134, v158
	v_add_f32_e32 v159, v135, v159
	v_mul_f32_e32 v156, 0xbfb8aa3b, v156
	v_mul_f32_e32 v157, 0xbfb8aa3b, v157
	v_mul_f32_e32 v158, 0xbfb8aa3b, v158
	v_mul_f32_e32 v159, 0xbfb8aa3b, v159
	v_exp_f32_e32 v156, v156
	v_exp_f32_e32 v157, v157
	v_exp_f32_e32 v158, v158
	v_exp_f32_e32 v159, v159
	v_add_f32_e32 v156, 1.0, v156
	v_add_f32_e32 v157, 1.0, v157
	v_add_f32_e32 v158, 1.0, v158
	v_add_f32_e32 v159, 1.0, v159
	v_rcp_f32_e32 v156, v156
	v_rcp_f32_e32 v157, v157
	v_rcp_f32_e32 v158, v158
	v_rcp_f32_e32 v159, v159
	v_lshlrev_b32_e32 v146, 16, v186
	v_and_b32_e32 v147, 0xffff0000, v186
	v_fma_f32 v156, v120, v156, v146
	v_fma_f32 v157, v121, v157, v147
	v_lshlrev_b32_e32 v146, 16, v187
	v_and_b32_e32 v147, 0xffff0000, v187
	v_fma_f32 v158, v122, v158, v146
	v_fma_f32 v159, v123, v159, v147
	v_cvt_pk_bf16_f32 v170, v156, v157
	v_cvt_pk_bf16_f32 v171, v158, v159
	global_store_dwordx4 v160, v[168:171], s[12:13] offset:0
	s_waitcnt vmcnt(13)
	v_lshlrev_b32_e32 v156, 16, v172
	v_and_b32_e32 v157, 0xffff0000, v172
	v_lshlrev_b32_e32 v158, 16, v173
	v_and_b32_e32 v159, 0xffff0000, v173
	v_add_f32_e32 v156, v128, v156
	v_add_f32_e32 v157, v129, v157
	v_add_f32_e32 v158, v130, v158
	v_add_f32_e32 v159, v131, v159
	v_mul_f32_e32 v156, 0xbfb8aa3b, v156
	v_mul_f32_e32 v157, 0xbfb8aa3b, v157
	v_mul_f32_e32 v158, 0xbfb8aa3b, v158
	v_mul_f32_e32 v159, 0xbfb8aa3b, v159
	v_exp_f32_e32 v156, v156
	v_exp_f32_e32 v157, v157
	v_exp_f32_e32 v158, v158
	v_exp_f32_e32 v159, v159
	v_add_f32_e32 v156, 1.0, v156
	v_add_f32_e32 v157, 1.0, v157
	v_add_f32_e32 v158, 1.0, v158
	v_add_f32_e32 v159, 1.0, v159
	v_rcp_f32_e32 v156, v156
	v_rcp_f32_e32 v157, v157
	v_rcp_f32_e32 v158, v158
	v_rcp_f32_e32 v159, v159
	v_lshlrev_b32_e32 v146, 16, v188
	v_and_b32_e32 v147, 0xffff0000, v188
	v_fma_f32 v156, v116, v156, v146
	v_fma_f32 v157, v117, v157, v147
	v_lshlrev_b32_e32 v146, 16, v189
	v_and_b32_e32 v147, 0xffff0000, v189
	v_fma_f32 v158, v118, v158, v146
	v_fma_f32 v159, v119, v159, v147
	v_cvt_pk_bf16_f32 v172, v156, v157
	v_cvt_pk_bf16_f32 v173, v158, v159
	v_lshlrev_b32_e32 v156, 16, v174
	v_and_b32_e32 v157, 0xffff0000, v174
	v_lshlrev_b32_e32 v158, 16, v175
	v_and_b32_e32 v159, 0xffff0000, v175
	v_add_f32_e32 v156, v132, v156
	v_add_f32_e32 v157, v133, v157
	v_add_f32_e32 v158, v134, v158
	v_add_f32_e32 v159, v135, v159
	v_mul_f32_e32 v156, 0xbfb8aa3b, v156
	v_mul_f32_e32 v157, 0xbfb8aa3b, v157
	v_mul_f32_e32 v158, 0xbfb8aa3b, v158
	v_mul_f32_e32 v159, 0xbfb8aa3b, v159
	v_exp_f32_e32 v156, v156
	v_exp_f32_e32 v157, v157
	v_exp_f32_e32 v158, v158
	v_exp_f32_e32 v159, v159
	v_add_f32_e32 v156, 1.0, v156
	v_add_f32_e32 v157, 1.0, v157
	v_add_f32_e32 v158, 1.0, v158
	v_add_f32_e32 v159, 1.0, v159
	v_rcp_f32_e32 v156, v156
	v_rcp_f32_e32 v157, v157
	v_rcp_f32_e32 v158, v158
	v_rcp_f32_e32 v159, v159
	v_lshlrev_b32_e32 v146, 16, v190
	v_and_b32_e32 v147, 0xffff0000, v190
	v_fma_f32 v156, v112, v156, v146
	v_fma_f32 v157, v113, v157, v147
	v_lshlrev_b32_e32 v146, 16, v191
	v_and_b32_e32 v147, 0xffff0000, v191
	v_fma_f32 v158, v114, v158, v146
	v_fma_f32 v159, v115, v159, v147
	v_cvt_pk_bf16_f32 v174, v156, v157
	v_cvt_pk_bf16_f32 v175, v158, v159
	v_add_u32_e32 v161, 0x8000, v160
	global_store_dwordx4 v161, v[172:175], s[12:13] offset:0
	s_waitcnt vmcnt(12)
	v_lshlrev_b32_e32 v156, 16, v176
	v_and_b32_e32 v157, 0xffff0000, v176
	v_lshlrev_b32_e32 v158, 16, v177
	v_and_b32_e32 v159, 0xffff0000, v177
	v_add_f32_e32 v156, v128, v156
	v_add_f32_e32 v157, v129, v157
	v_add_f32_e32 v158, v130, v158
	v_add_f32_e32 v159, v131, v159
	v_mul_f32_e32 v156, 0xbfb8aa3b, v156
	v_mul_f32_e32 v157, 0xbfb8aa3b, v157
	v_mul_f32_e32 v158, 0xbfb8aa3b, v158
	v_mul_f32_e32 v159, 0xbfb8aa3b, v159
	v_exp_f32_e32 v156, v156
	v_exp_f32_e32 v157, v157
	v_exp_f32_e32 v158, v158
	v_exp_f32_e32 v159, v159
	v_add_f32_e32 v156, 1.0, v156
	v_add_f32_e32 v157, 1.0, v157
	v_add_f32_e32 v158, 1.0, v158
	v_add_f32_e32 v159, 1.0, v159
	v_rcp_f32_e32 v156, v156
	v_rcp_f32_e32 v157, v157
	v_rcp_f32_e32 v158, v158
	v_rcp_f32_e32 v159, v159
	v_lshlrev_b32_e32 v146, 16, v208
	v_and_b32_e32 v147, 0xffff0000, v208
	v_fma_f32 v156, v108, v156, v146
	v_fma_f32 v157, v109, v157, v147
	v_lshlrev_b32_e32 v146, 16, v209
	v_and_b32_e32 v147, 0xffff0000, v209
	v_fma_f32 v158, v110, v158, v146
	v_fma_f32 v159, v111, v159, v147
	v_cvt_pk_bf16_f32 v176, v156, v157
	v_cvt_pk_bf16_f32 v177, v158, v159
	v_lshlrev_b32_e32 v156, 16, v178
	v_and_b32_e32 v157, 0xffff0000, v178
	v_lshlrev_b32_e32 v158, 16, v179
	v_and_b32_e32 v159, 0xffff0000, v179
	v_add_f32_e32 v156, v132, v156
	v_add_f32_e32 v157, v133, v157
	v_add_f32_e32 v158, v134, v158
	v_add_f32_e32 v159, v135, v159
	v_mul_f32_e32 v156, 0xbfb8aa3b, v156
	v_mul_f32_e32 v157, 0xbfb8aa3b, v157
	v_mul_f32_e32 v158, 0xbfb8aa3b, v158
	v_mul_f32_e32 v159, 0xbfb8aa3b, v159
	v_exp_f32_e32 v156, v156
	v_exp_f32_e32 v157, v157
	v_exp_f32_e32 v158, v158
	v_exp_f32_e32 v159, v159
	v_add_f32_e32 v156, 1.0, v156
	v_add_f32_e32 v157, 1.0, v157
	v_add_f32_e32 v158, 1.0, v158
	v_add_f32_e32 v159, 1.0, v159
	v_rcp_f32_e32 v156, v156
	v_rcp_f32_e32 v157, v157
	v_rcp_f32_e32 v158, v158
	v_rcp_f32_e32 v159, v159
	v_lshlrev_b32_e32 v146, 16, v210
	v_and_b32_e32 v147, 0xffff0000, v210
	v_fma_f32 v156, v104, v156, v146
	v_fma_f32 v157, v105, v157, v147
	v_lshlrev_b32_e32 v146, 16, v211
	v_and_b32_e32 v147, 0xffff0000, v211
	v_fma_f32 v158, v106, v158, v146
	v_fma_f32 v159, v107, v159, v147
	v_cvt_pk_bf16_f32 v178, v156, v157
	v_cvt_pk_bf16_f32 v179, v158, v159
	v_add_u32_e32 v161, 0x10000, v160
	global_store_dwordx4 v161, v[176:179], s[12:13] offset:0
	s_waitcnt vmcnt(11)
	v_lshlrev_b32_e32 v156, 16, v180
	v_and_b32_e32 v157, 0xffff0000, v180
	v_lshlrev_b32_e32 v158, 16, v181
	v_and_b32_e32 v159, 0xffff0000, v181
	v_add_f32_e32 v156, v128, v156
	v_add_f32_e32 v157, v129, v157
	v_add_f32_e32 v158, v130, v158
	v_add_f32_e32 v159, v131, v159
	v_mul_f32_e32 v156, 0xbfb8aa3b, v156
	v_mul_f32_e32 v157, 0xbfb8aa3b, v157
	v_mul_f32_e32 v158, 0xbfb8aa3b, v158
	v_mul_f32_e32 v159, 0xbfb8aa3b, v159
	v_exp_f32_e32 v156, v156
	v_exp_f32_e32 v157, v157
	v_exp_f32_e32 v158, v158
	v_exp_f32_e32 v159, v159
	v_add_f32_e32 v156, 1.0, v156
	v_add_f32_e32 v157, 1.0, v157
	v_add_f32_e32 v158, 1.0, v158
	v_add_f32_e32 v159, 1.0, v159
	v_rcp_f32_e32 v156, v156
	v_rcp_f32_e32 v157, v157
	v_rcp_f32_e32 v158, v158
	v_rcp_f32_e32 v159, v159
	v_lshlrev_b32_e32 v146, 16, v212
	v_and_b32_e32 v147, 0xffff0000, v212
	v_fma_f32 v156, v100, v156, v146
	v_fma_f32 v157, v101, v157, v147
	v_lshlrev_b32_e32 v146, 16, v213
	v_and_b32_e32 v147, 0xffff0000, v213
	v_fma_f32 v158, v102, v158, v146
	v_fma_f32 v159, v103, v159, v147
	v_cvt_pk_bf16_f32 v180, v156, v157
	v_cvt_pk_bf16_f32 v181, v158, v159
	v_lshlrev_b32_e32 v156, 16, v182
	v_and_b32_e32 v157, 0xffff0000, v182
	v_lshlrev_b32_e32 v158, 16, v183
	v_and_b32_e32 v159, 0xffff0000, v183
	v_add_f32_e32 v156, v132, v156
	v_add_f32_e32 v157, v133, v157
	v_add_f32_e32 v158, v134, v158
	v_add_f32_e32 v159, v135, v159
	v_mul_f32_e32 v156, 0xbfb8aa3b, v156
	v_mul_f32_e32 v157, 0xbfb8aa3b, v157
	v_mul_f32_e32 v158, 0xbfb8aa3b, v158
	v_mul_f32_e32 v159, 0xbfb8aa3b, v159
	v_exp_f32_e32 v156, v156
	v_exp_f32_e32 v157, v157
	v_exp_f32_e32 v158, v158
	v_exp_f32_e32 v159, v159
	v_add_f32_e32 v156, 1.0, v156
	v_add_f32_e32 v157, 1.0, v157
	v_add_f32_e32 v158, 1.0, v158
	v_add_f32_e32 v159, 1.0, v159
	v_rcp_f32_e32 v156, v156
	v_rcp_f32_e32 v157, v157
	v_rcp_f32_e32 v158, v158
	v_rcp_f32_e32 v159, v159
	v_lshlrev_b32_e32 v146, 16, v214
	v_and_b32_e32 v147, 0xffff0000, v214
	v_fma_f32 v156, v96, v156, v146
	v_fma_f32 v157, v97, v157, v147
	v_lshlrev_b32_e32 v146, 16, v215
	v_and_b32_e32 v147, 0xffff0000, v215
	v_fma_f32 v158, v98, v158, v146
	v_fma_f32 v159, v99, v159, v147
	v_cvt_pk_bf16_f32 v182, v156, v157
	v_cvt_pk_bf16_f32 v183, v158, v159
	v_add_u32_e32 v161, 0x18000, v160
	global_store_dwordx4 v161, v[180:183], s[12:13] offset:0
	s_nop 1
	global_load_dwordx4 v[168:171], v162, s[34:35] offset:256
	global_load_dwordx4 v[184:187], v160, s[10:11] offset:256
	v_add_u32_e32 v161, 0x10000, v162
	global_load_dwordx4 v[172:175], v161, s[34:35] offset:256
	v_add_u32_e32 v163, 0x8000, v160
	global_load_dwordx4 v[188:191], v163, s[10:11] offset:256
	v_add_u32_e32 v161, 0x20000, v162
	global_load_dwordx4 v[176:179], v161, s[34:35] offset:256
	v_add_u32_e32 v163, 0x10000, v160
	global_load_dwordx4 v[208:211], v163, s[10:11] offset:256
	v_add_u32_e32 v161, 0x30000, v162
	global_load_dwordx4 v[180:183], v161, s[34:35] offset:256
	v_add_u32_e32 v163, 0x18000, v160
	global_load_dwordx4 v[212:215], v163, s[10:11] offset:256
	global_load_dwordx4 v[96:99], v164, s[36:37] offset:512
	global_load_dwordx4 v[100:103], v164, s[36:37] offset:528
	s_waitcnt vmcnt(20)
	v_lshlrev_b32_e32 v156, 16, v216
	v_and_b32_e32 v157, 0xffff0000, v216
	v_lshlrev_b32_e32 v158, 16, v217
	v_and_b32_e32 v159, 0xffff0000, v217
	v_add_f32_e32 v156, v128, v156
	v_add_f32_e32 v157, v129, v157
	v_add_f32_e32 v158, v130, v158
	v_add_f32_e32 v159, v131, v159
	v_mul_f32_e32 v156, 0xbfb8aa3b, v156
	v_mul_f32_e32 v157, 0xbfb8aa3b, v157
	v_mul_f32_e32 v158, 0xbfb8aa3b, v158
	v_mul_f32_e32 v159, 0xbfb8aa3b, v159
	v_exp_f32_e32 v156, v156
	v_exp_f32_e32 v157, v157
	v_exp_f32_e32 v158, v158
	v_exp_f32_e32 v159, v159
	v_add_f32_e32 v156, 1.0, v156
	v_add_f32_e32 v157, 1.0, v157
	v_add_f32_e32 v158, 1.0, v158
	v_add_f32_e32 v159, 1.0, v159
	v_rcp_f32_e32 v156, v156
	v_rcp_f32_e32 v157, v157
	v_rcp_f32_e32 v158, v158
	v_rcp_f32_e32 v159, v159
	v_lshlrev_b32_e32 v146, 16, v232
	v_and_b32_e32 v147, 0xffff0000, v232
	v_fma_f32 v156, v92, v156, v146
	v_fma_f32 v157, v93, v157, v147
	v_lshlrev_b32_e32 v146, 16, v233
	v_and_b32_e32 v147, 0xffff0000, v233
	v_fma_f32 v158, v94, v158, v146
	v_fma_f32 v159, v95, v159, v147
	v_cvt_pk_bf16_f32 v216, v156, v157
	v_cvt_pk_bf16_f32 v217, v158, v159
	v_lshlrev_b32_e32 v156, 16, v218
	v_and_b32_e32 v157, 0xffff0000, v218
	v_lshlrev_b32_e32 v158, 16, v219
	v_and_b32_e32 v159, 0xffff0000, v219
	v_add_f32_e32 v156, v132, v156
	v_add_f32_e32 v157, v133, v157
	v_add_f32_e32 v158, v134, v158
	v_add_f32_e32 v159, v135, v159
	v_mul_f32_e32 v156, 0xbfb8aa3b, v156
	v_mul_f32_e32 v157, 0xbfb8aa3b, v157
	v_mul_f32_e32 v158, 0xbfb8aa3b, v158
	v_mul_f32_e32 v159, 0xbfb8aa3b, v159
	v_exp_f32_e32 v156, v156
	v_exp_f32_e32 v157, v157
	v_exp_f32_e32 v158, v158
	v_exp_f32_e32 v159, v159
	v_add_f32_e32 v156, 1.0, v156
	v_add_f32_e32 v157, 1.0, v157
	v_add_f32_e32 v158, 1.0, v158
	v_add_f32_e32 v159, 1.0, v159
	v_rcp_f32_e32 v156, v156
	v_rcp_f32_e32 v157, v157
	v_rcp_f32_e32 v158, v158
	v_rcp_f32_e32 v159, v159
	v_lshlrev_b32_e32 v146, 16, v234
	v_and_b32_e32 v147, 0xffff0000, v234
	v_fma_f32 v156, v88, v156, v146
	v_fma_f32 v157, v89, v157, v147
	v_lshlrev_b32_e32 v146, 16, v235
	v_and_b32_e32 v147, 0xffff0000, v235
	v_fma_f32 v158, v90, v158, v146
	v_fma_f32 v159, v91, v159, v147
	v_cvt_pk_bf16_f32 v218, v156, v157
	v_cvt_pk_bf16_f32 v219, v158, v159
	v_add_u32_e32 v161, 0x40000, v160
	global_store_dwordx4 v161, v[216:219], s[12:13] offset:0
	s_waitcnt vmcnt(19)
	v_lshlrev_b32_e32 v156, 16, v220
	v_and_b32_e32 v157, 0xffff0000, v220
	v_lshlrev_b32_e32 v158, 16, v221
	v_and_b32_e32 v159, 0xffff0000, v221
	v_add_f32_e32 v156, v128, v156
	v_add_f32_e32 v157, v129, v157
	v_add_f32_e32 v158, v130, v158
	v_add_f32_e32 v159, v131, v159
	v_mul_f32_e32 v156, 0xbfb8aa3b, v156
	v_mul_f32_e32 v157, 0xbfb8aa3b, v157
	v_mul_f32_e32 v158, 0xbfb8aa3b, v158
	v_mul_f32_e32 v159, 0xbfb8aa3b, v159
	v_exp_f32_e32 v156, v156
	v_exp_f32_e32 v157, v157
	v_exp_f32_e32 v158, v158
	v_exp_f32_e32 v159, v159
	v_add_f32_e32 v156, 1.0, v156
	v_add_f32_e32 v157, 1.0, v157
	v_add_f32_e32 v158, 1.0, v158
	v_add_f32_e32 v159, 1.0, v159
	v_rcp_f32_e32 v156, v156
	v_rcp_f32_e32 v157, v157
	v_rcp_f32_e32 v158, v158
	v_rcp_f32_e32 v159, v159
	v_lshlrev_b32_e32 v146, 16, v248
	v_and_b32_e32 v147, 0xffff0000, v248
	v_fma_f32 v156, v84, v156, v146
	v_fma_f32 v157, v85, v157, v147
	v_lshlrev_b32_e32 v146, 16, v249
	v_and_b32_e32 v147, 0xffff0000, v249
	v_fma_f32 v158, v86, v158, v146
	v_fma_f32 v159, v87, v159, v147
	v_cvt_pk_bf16_f32 v220, v156, v157
	v_cvt_pk_bf16_f32 v221, v158, v159
	v_lshlrev_b32_e32 v156, 16, v222
	v_and_b32_e32 v157, 0xffff0000, v222
	v_lshlrev_b32_e32 v158, 16, v223
	v_and_b32_e32 v159, 0xffff0000, v223
	v_add_f32_e32 v156, v132, v156
	v_add_f32_e32 v157, v133, v157
	v_add_f32_e32 v158, v134, v158
	v_add_f32_e32 v159, v135, v159
	v_mul_f32_e32 v156, 0xbfb8aa3b, v156
	v_mul_f32_e32 v157, 0xbfb8aa3b, v157
	v_mul_f32_e32 v158, 0xbfb8aa3b, v158
	v_mul_f32_e32 v159, 0xbfb8aa3b, v159
	v_exp_f32_e32 v156, v156
	v_exp_f32_e32 v157, v157
	v_exp_f32_e32 v158, v158
	v_exp_f32_e32 v159, v159
	v_add_f32_e32 v156, 1.0, v156
	v_add_f32_e32 v157, 1.0, v157
	v_add_f32_e32 v158, 1.0, v158
	v_add_f32_e32 v159, 1.0, v159
	v_rcp_f32_e32 v156, v156
	v_rcp_f32_e32 v157, v157
	v_rcp_f32_e32 v158, v158
	v_rcp_f32_e32 v159, v159
	v_lshlrev_b32_e32 v146, 16, v250
	v_and_b32_e32 v147, 0xffff0000, v250
	v_fma_f32 v156, v80, v156, v146
	v_fma_f32 v157, v81, v157, v147
	v_lshlrev_b32_e32 v146, 16, v251
	v_and_b32_e32 v147, 0xffff0000, v251
	v_fma_f32 v158, v82, v158, v146
	v_fma_f32 v159, v83, v159, v147
	v_cvt_pk_bf16_f32 v222, v156, v157
	v_cvt_pk_bf16_f32 v223, v158, v159
	v_add_u32_e32 v161, 0x48000, v160
	global_store_dwordx4 v161, v[220:223], s[12:13] offset:0
	s_waitcnt vmcnt(18)
	v_lshlrev_b32_e32 v156, 16, v224
	v_and_b32_e32 v157, 0xffff0000, v224
	v_lshlrev_b32_e32 v158, 16, v225
	v_and_b32_e32 v159, 0xffff0000, v225
	v_add_f32_e32 v156, v128, v156
	v_add_f32_e32 v157, v129, v157
	v_add_f32_e32 v158, v130, v158
	v_add_f32_e32 v159, v131, v159
	v_mul_f32_e32 v156, 0xbfb8aa3b, v156
	v_mul_f32_e32 v157, 0xbfb8aa3b, v157
	v_mul_f32_e32 v158, 0xbfb8aa3b, v158
	v_mul_f32_e32 v159, 0xbfb8aa3b, v159
	v_exp_f32_e32 v156, v156
	v_exp_f32_e32 v157, v157
	v_exp_f32_e32 v158, v158
	v_exp_f32_e32 v159, v159
	v_add_f32_e32 v156, 1.0, v156
	v_add_f32_e32 v157, 1.0, v157
	v_add_f32_e32 v158, 1.0, v158
	v_add_f32_e32 v159, 1.0, v159
	v_rcp_f32_e32 v156, v156
	v_rcp_f32_e32 v157, v157
	v_rcp_f32_e32 v158, v158
	v_rcp_f32_e32 v159, v159
	v_lshlrev_b32_e32 v146, 16, v148
	v_and_b32_e32 v147, 0xffff0000, v148
	v_fma_f32 v156, v76, v156, v146
	v_fma_f32 v157, v77, v157, v147
	v_lshlrev_b32_e32 v146, 16, v149
	v_and_b32_e32 v147, 0xffff0000, v149
	v_fma_f32 v158, v78, v158, v146
	v_fma_f32 v159, v79, v159, v147
	v_cvt_pk_bf16_f32 v224, v156, v157
	v_cvt_pk_bf16_f32 v225, v158, v159
	v_lshlrev_b32_e32 v156, 16, v226
	v_and_b32_e32 v157, 0xffff0000, v226
	v_lshlrev_b32_e32 v158, 16, v227
	v_and_b32_e32 v159, 0xffff0000, v227
	v_add_f32_e32 v156, v132, v156
	v_add_f32_e32 v157, v133, v157
	v_add_f32_e32 v158, v134, v158
	v_add_f32_e32 v159, v135, v159
	v_mul_f32_e32 v156, 0xbfb8aa3b, v156
	v_mul_f32_e32 v157, 0xbfb8aa3b, v157
	v_mul_f32_e32 v158, 0xbfb8aa3b, v158
	v_mul_f32_e32 v159, 0xbfb8aa3b, v159
	v_exp_f32_e32 v156, v156
	v_exp_f32_e32 v157, v157
	v_exp_f32_e32 v158, v158
	v_exp_f32_e32 v159, v159
	v_add_f32_e32 v156, 1.0, v156
	v_add_f32_e32 v157, 1.0, v157
	v_add_f32_e32 v158, 1.0, v158
	v_add_f32_e32 v159, 1.0, v159
	v_rcp_f32_e32 v156, v156
	v_rcp_f32_e32 v157, v157
	v_rcp_f32_e32 v158, v158
	v_rcp_f32_e32 v159, v159
	v_lshlrev_b32_e32 v146, 16, v150
	v_and_b32_e32 v147, 0xffff0000, v150
	v_fma_f32 v156, v72, v156, v146
	v_fma_f32 v157, v73, v157, v147
	v_lshlrev_b32_e32 v146, 16, v151
	v_and_b32_e32 v147, 0xffff0000, v151
	v_fma_f32 v158, v74, v158, v146
	v_fma_f32 v159, v75, v159, v147
	v_cvt_pk_bf16_f32 v226, v156, v157
	v_cvt_pk_bf16_f32 v227, v158, v159
	v_add_u32_e32 v161, 0x50000, v160
	global_store_dwordx4 v161, v[224:227], s[12:13] offset:0
	s_waitcnt vmcnt(17)
	v_lshlrev_b32_e32 v156, 16, v228
	v_and_b32_e32 v157, 0xffff0000, v228
	v_lshlrev_b32_e32 v158, 16, v229
	v_and_b32_e32 v159, 0xffff0000, v229
	v_add_f32_e32 v156, v128, v156
	v_add_f32_e32 v157, v129, v157
	v_add_f32_e32 v158, v130, v158
	v_add_f32_e32 v159, v131, v159
	v_mul_f32_e32 v156, 0xbfb8aa3b, v156
	v_mul_f32_e32 v157, 0xbfb8aa3b, v157
	v_mul_f32_e32 v158, 0xbfb8aa3b, v158
	v_mul_f32_e32 v159, 0xbfb8aa3b, v159
	v_exp_f32_e32 v156, v156
	v_exp_f32_e32 v157, v157
	v_exp_f32_e32 v158, v158
	v_exp_f32_e32 v159, v159
	v_add_f32_e32 v156, 1.0, v156
	v_add_f32_e32 v157, 1.0, v157
	v_add_f32_e32 v158, 1.0, v158
	v_add_f32_e32 v159, 1.0, v159
	v_rcp_f32_e32 v156, v156
	v_rcp_f32_e32 v157, v157
	v_rcp_f32_e32 v158, v158
	v_rcp_f32_e32 v159, v159
	v_lshlrev_b32_e32 v146, 16, v152
	v_and_b32_e32 v147, 0xffff0000, v152
	v_fma_f32 v156, v68, v156, v146
	v_fma_f32 v157, v69, v157, v147
	v_lshlrev_b32_e32 v146, 16, v153
	v_and_b32_e32 v147, 0xffff0000, v153
	v_fma_f32 v158, v70, v158, v146
	v_fma_f32 v159, v71, v159, v147
	v_cvt_pk_bf16_f32 v228, v156, v157
	v_cvt_pk_bf16_f32 v229, v158, v159
	v_lshlrev_b32_e32 v156, 16, v230
	v_and_b32_e32 v157, 0xffff0000, v230
	v_lshlrev_b32_e32 v158, 16, v231
	v_and_b32_e32 v159, 0xffff0000, v231
	v_add_f32_e32 v156, v132, v156
	v_add_f32_e32 v157, v133, v157
	v_add_f32_e32 v158, v134, v158
	v_add_f32_e32 v159, v135, v159
	v_mul_f32_e32 v156, 0xbfb8aa3b, v156
	v_mul_f32_e32 v157, 0xbfb8aa3b, v157
	v_mul_f32_e32 v158, 0xbfb8aa3b, v158
	v_mul_f32_e32 v159, 0xbfb8aa3b, v159
	v_exp_f32_e32 v156, v156
	v_exp_f32_e32 v157, v157
	v_exp_f32_e32 v158, v158
	v_exp_f32_e32 v159, v159
	v_add_f32_e32 v156, 1.0, v156
	v_add_f32_e32 v157, 1.0, v157
	v_add_f32_e32 v158, 1.0, v158
	v_add_f32_e32 v159, 1.0, v159
	v_rcp_f32_e32 v156, v156
	v_rcp_f32_e32 v157, v157
	v_rcp_f32_e32 v158, v158
	v_rcp_f32_e32 v159, v159
	v_lshlrev_b32_e32 v146, 16, v154
	v_and_b32_e32 v147, 0xffff0000, v154
	v_fma_f32 v156, v64, v156, v146
	v_fma_f32 v157, v65, v157, v147
	v_lshlrev_b32_e32 v146, 16, v155
	v_and_b32_e32 v147, 0xffff0000, v155
	v_fma_f32 v158, v66, v158, v146
	v_fma_f32 v159, v67, v159, v147
	v_cvt_pk_bf16_f32 v230, v156, v157
	v_cvt_pk_bf16_f32 v231, v158, v159
	v_add_u32_e32 v161, 0x58000, v160
	global_store_dwordx4 v161, v[228:231], s[12:13] offset:0
	s_nop 1
	v_add_u32_e32 v161, 0x80000, v162
	global_load_dwordx4 v[216:219], v161, s[34:35] offset:256
	v_add_u32_e32 v163, 0x40000, v160
	global_load_dwordx4 v[232:235], v163, s[10:11] offset:256
	v_add_u32_e32 v161, 0x90000, v162
	global_load_dwordx4 v[220:223], v161, s[34:35] offset:256
	v_add_u32_e32 v163, 0x48000, v160
	global_load_dwordx4 v[248:251], v163, s[10:11] offset:256
	v_add_u32_e32 v161, 0xa0000, v162
	global_load_dwordx4 v[224:227], v161, s[34:35] offset:256
	v_add_u32_e32 v163, 0x50000, v160
	global_load_dwordx4 v[148:151], v163, s[10:11] offset:256
	v_add_u32_e32 v161, 0xb0000, v162
	global_load_dwordx4 v[228:231], v161, s[34:35] offset:256
	v_add_u32_e32 v163, 0x58000, v160
	global_load_dwordx4 v[152:155], v163, s[10:11] offset:256
	s_waitcnt vmcnt(12)
	v_lshlrev_b32_e32 v156, 16, v168
	v_and_b32_e32 v157, 0xffff0000, v168
	v_lshlrev_b32_e32 v158, 16, v169
	v_and_b32_e32 v159, 0xffff0000, v169
	v_add_f32_e32 v156, v96, v156
	v_add_f32_e32 v157, v97, v157
	v_add_f32_e32 v158, v98, v158
	v_add_f32_e32 v159, v99, v159
	v_mul_f32_e32 v156, 0xbfb8aa3b, v156
	v_mul_f32_e32 v157, 0xbfb8aa3b, v157
	v_mul_f32_e32 v158, 0xbfb8aa3b, v158
	v_mul_f32_e32 v159, 0xbfb8aa3b, v159
	v_exp_f32_e32 v156, v156
	v_exp_f32_e32 v157, v157
	v_exp_f32_e32 v158, v158
	v_exp_f32_e32 v159, v159
	v_add_f32_e32 v156, 1.0, v156
	v_add_f32_e32 v157, 1.0, v157
	v_add_f32_e32 v158, 1.0, v158
	v_add_f32_e32 v159, 1.0, v159
	v_rcp_f32_e32 v156, v156
	v_rcp_f32_e32 v157, v157
	v_rcp_f32_e32 v158, v158
	v_rcp_f32_e32 v159, v159
	v_lshlrev_b32_e32 v146, 16, v184
	v_and_b32_e32 v147, 0xffff0000, v184
	v_fma_f32 v156, v60, v156, v146
	v_fma_f32 v157, v61, v157, v147
	v_lshlrev_b32_e32 v146, 16, v185
	v_and_b32_e32 v147, 0xffff0000, v185
	v_fma_f32 v158, v62, v158, v146
	v_fma_f32 v159, v63, v159, v147
	v_cvt_pk_bf16_f32 v168, v156, v157
	v_cvt_pk_bf16_f32 v169, v158, v159
	v_lshlrev_b32_e32 v156, 16, v170
	v_and_b32_e32 v157, 0xffff0000, v170
	v_lshlrev_b32_e32 v158, 16, v171
	v_and_b32_e32 v159, 0xffff0000, v171
	v_add_f32_e32 v156, v100, v156
	v_add_f32_e32 v157, v101, v157
	v_add_f32_e32 v158, v102, v158
	v_add_f32_e32 v159, v103, v159
	v_mul_f32_e32 v156, 0xbfb8aa3b, v156
	v_mul_f32_e32 v157, 0xbfb8aa3b, v157
	v_mul_f32_e32 v158, 0xbfb8aa3b, v158
	v_mul_f32_e32 v159, 0xbfb8aa3b, v159
	v_exp_f32_e32 v156, v156
	v_exp_f32_e32 v157, v157
	v_exp_f32_e32 v158, v158
	v_exp_f32_e32 v159, v159
	v_add_f32_e32 v156, 1.0, v156
	v_add_f32_e32 v157, 1.0, v157
	v_add_f32_e32 v158, 1.0, v158
	v_add_f32_e32 v159, 1.0, v159
	v_rcp_f32_e32 v156, v156
	v_rcp_f32_e32 v157, v157
	v_rcp_f32_e32 v158, v158
	v_rcp_f32_e32 v159, v159
	v_lshlrev_b32_e32 v146, 16, v186
	v_and_b32_e32 v147, 0xffff0000, v186
	v_fma_f32 v156, v56, v156, v146
	v_fma_f32 v157, v57, v157, v147
	v_lshlrev_b32_e32 v146, 16, v187
	v_and_b32_e32 v147, 0xffff0000, v187
	v_fma_f32 v158, v58, v158, v146
	v_fma_f32 v159, v59, v159, v147
	v_cvt_pk_bf16_f32 v170, v156, v157
	v_cvt_pk_bf16_f32 v171, v158, v159
	global_store_dwordx4 v160, v[168:171], s[12:13] offset:256
	v_lshlrev_b32_e32 v156, 16, v172
	v_and_b32_e32 v157, 0xffff0000, v172
	v_lshlrev_b32_e32 v158, 16, v173
	v_and_b32_e32 v159, 0xffff0000, v173
	v_add_f32_e32 v156, v96, v156
	v_add_f32_e32 v157, v97, v157
	v_add_f32_e32 v158, v98, v158
	v_add_f32_e32 v159, v99, v159
	v_mul_f32_e32 v156, 0xbfb8aa3b, v156
	v_mul_f32_e32 v157, 0xbfb8aa3b, v157
	v_mul_f32_e32 v158, 0xbfb8aa3b, v158
	v_mul_f32_e32 v159, 0xbfb8aa3b, v159
	v_exp_f32_e32 v156, v156
	v_exp_f32_e32 v157, v157
	v_exp_f32_e32 v158, v158
	v_exp_f32_e32 v159, v159
	v_add_f32_e32 v156, 1.0, v156
	v_add_f32_e32 v157, 1.0, v157
	v_add_f32_e32 v158, 1.0, v158
	v_add_f32_e32 v159, 1.0, v159
	v_rcp_f32_e32 v156, v156
	v_rcp_f32_e32 v157, v157
	v_rcp_f32_e32 v158, v158
	v_rcp_f32_e32 v159, v159
	v_lshlrev_b32_e32 v146, 16, v188
	v_and_b32_e32 v147, 0xffff0000, v188
	v_fma_f32 v156, v52, v156, v146
	v_fma_f32 v157, v53, v157, v147
	v_lshlrev_b32_e32 v146, 16, v189
	v_and_b32_e32 v147, 0xffff0000, v189
	v_fma_f32 v158, v54, v158, v146
	v_fma_f32 v159, v55, v159, v147
	v_cvt_pk_bf16_f32 v172, v156, v157
	v_cvt_pk_bf16_f32 v173, v158, v159
	v_lshlrev_b32_e32 v156, 16, v174
	v_and_b32_e32 v157, 0xffff0000, v174
	v_lshlrev_b32_e32 v158, 16, v175
	v_and_b32_e32 v159, 0xffff0000, v175
	v_add_f32_e32 v156, v100, v156
	v_add_f32_e32 v157, v101, v157
	v_add_f32_e32 v158, v102, v158
	v_add_f32_e32 v159, v103, v159
	v_mul_f32_e32 v156, 0xbfb8aa3b, v156
	v_mul_f32_e32 v157, 0xbfb8aa3b, v157
	v_mul_f32_e32 v158, 0xbfb8aa3b, v158
	v_mul_f32_e32 v159, 0xbfb8aa3b, v159
	v_exp_f32_e32 v156, v156
	v_exp_f32_e32 v157, v157
	v_exp_f32_e32 v158, v158
	v_exp_f32_e32 v159, v159
	v_add_f32_e32 v156, 1.0, v156
	v_add_f32_e32 v157, 1.0, v157
	v_add_f32_e32 v158, 1.0, v158
	v_add_f32_e32 v159, 1.0, v159
	v_rcp_f32_e32 v156, v156
	v_rcp_f32_e32 v157, v157
	v_rcp_f32_e32 v158, v158
	v_rcp_f32_e32 v159, v159
	v_lshlrev_b32_e32 v146, 16, v190
	v_and_b32_e32 v147, 0xffff0000, v190
	v_fma_f32 v156, v48, v156, v146
	v_fma_f32 v157, v49, v157, v147
	v_lshlrev_b32_e32 v146, 16, v191
	v_and_b32_e32 v147, 0xffff0000, v191
	v_fma_f32 v158, v50, v158, v146
	v_fma_f32 v159, v51, v159, v147
	v_cvt_pk_bf16_f32 v174, v156, v157
	v_cvt_pk_bf16_f32 v175, v158, v159
	v_add_u32_e32 v161, 0x8000, v160
	global_store_dwordx4 v161, v[172:175], s[12:13] offset:256
	v_lshlrev_b32_e32 v156, 16, v176
	v_and_b32_e32 v157, 0xffff0000, v176
	v_lshlrev_b32_e32 v158, 16, v177
	v_and_b32_e32 v159, 0xffff0000, v177
	v_add_f32_e32 v156, v96, v156
	v_add_f32_e32 v157, v97, v157
	v_add_f32_e32 v158, v98, v158
	v_add_f32_e32 v159, v99, v159
	v_mul_f32_e32 v156, 0xbfb8aa3b, v156
	v_mul_f32_e32 v157, 0xbfb8aa3b, v157
	v_mul_f32_e32 v158, 0xbfb8aa3b, v158
	v_mul_f32_e32 v159, 0xbfb8aa3b, v159
	v_exp_f32_e32 v156, v156
	v_exp_f32_e32 v157, v157
	v_exp_f32_e32 v158, v158
	v_exp_f32_e32 v159, v159
	v_add_f32_e32 v156, 1.0, v156
	v_add_f32_e32 v157, 1.0, v157
	v_add_f32_e32 v158, 1.0, v158
	v_add_f32_e32 v159, 1.0, v159
	v_rcp_f32_e32 v156, v156
	v_rcp_f32_e32 v157, v157
	v_rcp_f32_e32 v158, v158
	v_rcp_f32_e32 v159, v159
	v_lshlrev_b32_e32 v146, 16, v208
	v_and_b32_e32 v147, 0xffff0000, v208
	v_fma_f32 v156, v44, v156, v146
	v_fma_f32 v157, v45, v157, v147
	v_lshlrev_b32_e32 v146, 16, v209
	v_and_b32_e32 v147, 0xffff0000, v209
	v_fma_f32 v158, v46, v158, v146
	v_fma_f32 v159, v47, v159, v147
	v_cvt_pk_bf16_f32 v176, v156, v157
	v_cvt_pk_bf16_f32 v177, v158, v159
	v_lshlrev_b32_e32 v156, 16, v178
	v_and_b32_e32 v157, 0xffff0000, v178
	v_lshlrev_b32_e32 v158, 16, v179
	v_and_b32_e32 v159, 0xffff0000, v179
	v_add_f32_e32 v156, v100, v156
	v_add_f32_e32 v157, v101, v157
	v_add_f32_e32 v158, v102, v158
	v_add_f32_e32 v159, v103, v159
	v_mul_f32_e32 v156, 0xbfb8aa3b, v156
	v_mul_f32_e32 v157, 0xbfb8aa3b, v157
	v_mul_f32_e32 v158, 0xbfb8aa3b, v158
	v_mul_f32_e32 v159, 0xbfb8aa3b, v159
	v_exp_f32_e32 v156, v156
	v_exp_f32_e32 v157, v157
	v_exp_f32_e32 v158, v158
	v_exp_f32_e32 v159, v159
	v_add_f32_e32 v156, 1.0, v156
	v_add_f32_e32 v157, 1.0, v157
	v_add_f32_e32 v158, 1.0, v158
	v_add_f32_e32 v159, 1.0, v159
	v_rcp_f32_e32 v156, v156
	v_rcp_f32_e32 v157, v157
	v_rcp_f32_e32 v158, v158
	v_rcp_f32_e32 v159, v159
	v_lshlrev_b32_e32 v146, 16, v210
	v_and_b32_e32 v147, 0xffff0000, v210
	v_fma_f32 v156, v40, v156, v146
	v_fma_f32 v157, v41, v157, v147
	v_lshlrev_b32_e32 v146, 16, v211
	v_and_b32_e32 v147, 0xffff0000, v211
	v_fma_f32 v158, v42, v158, v146
	v_fma_f32 v159, v43, v159, v147
	v_cvt_pk_bf16_f32 v178, v156, v157
	v_cvt_pk_bf16_f32 v179, v158, v159
	v_add_u32_e32 v161, 0x10000, v160
	global_store_dwordx4 v161, v[176:179], s[12:13] offset:256
	v_lshlrev_b32_e32 v156, 16, v180
	v_and_b32_e32 v157, 0xffff0000, v180
	v_lshlrev_b32_e32 v158, 16, v181
	v_and_b32_e32 v159, 0xffff0000, v181
	v_add_f32_e32 v156, v96, v156
	v_add_f32_e32 v157, v97, v157
	v_add_f32_e32 v158, v98, v158
	v_add_f32_e32 v159, v99, v159
	v_mul_f32_e32 v156, 0xbfb8aa3b, v156
	v_mul_f32_e32 v157, 0xbfb8aa3b, v157
	v_mul_f32_e32 v158, 0xbfb8aa3b, v158
	v_mul_f32_e32 v159, 0xbfb8aa3b, v159
	v_exp_f32_e32 v156, v156
	v_exp_f32_e32 v157, v157
	v_exp_f32_e32 v158, v158
	v_exp_f32_e32 v159, v159
	v_add_f32_e32 v156, 1.0, v156
	v_add_f32_e32 v157, 1.0, v157
	v_add_f32_e32 v158, 1.0, v158
	v_add_f32_e32 v159, 1.0, v159
	v_rcp_f32_e32 v156, v156
	v_rcp_f32_e32 v157, v157
	v_rcp_f32_e32 v158, v158
	v_rcp_f32_e32 v159, v159
	v_lshlrev_b32_e32 v146, 16, v212
	v_and_b32_e32 v147, 0xffff0000, v212
	v_fma_f32 v156, v36, v156, v146
	v_fma_f32 v157, v37, v157, v147
	v_lshlrev_b32_e32 v146, 16, v213
	v_and_b32_e32 v147, 0xffff0000, v213
	v_fma_f32 v158, v38, v158, v146
	v_fma_f32 v159, v39, v159, v147
	v_cvt_pk_bf16_f32 v180, v156, v157
	v_cvt_pk_bf16_f32 v181, v158, v159
	v_lshlrev_b32_e32 v156, 16, v182
	v_and_b32_e32 v157, 0xffff0000, v182
	v_lshlrev_b32_e32 v158, 16, v183
	v_and_b32_e32 v159, 0xffff0000, v183
	v_add_f32_e32 v156, v100, v156
	v_add_f32_e32 v157, v101, v157
	v_add_f32_e32 v158, v102, v158
	v_add_f32_e32 v159, v103, v159
	v_mul_f32_e32 v156, 0xbfb8aa3b, v156
	v_mul_f32_e32 v157, 0xbfb8aa3b, v157
	v_mul_f32_e32 v158, 0xbfb8aa3b, v158
	v_mul_f32_e32 v159, 0xbfb8aa3b, v159
	v_exp_f32_e32 v156, v156
	v_exp_f32_e32 v157, v157
	v_exp_f32_e32 v158, v158
	v_exp_f32_e32 v159, v159
	v_add_f32_e32 v156, 1.0, v156
	v_add_f32_e32 v157, 1.0, v157
	v_add_f32_e32 v158, 1.0, v158
	v_add_f32_e32 v159, 1.0, v159
	v_rcp_f32_e32 v156, v156
	v_rcp_f32_e32 v157, v157
	v_rcp_f32_e32 v158, v158
	v_rcp_f32_e32 v159, v159
	v_lshlrev_b32_e32 v146, 16, v214
	v_and_b32_e32 v147, 0xffff0000, v214
	v_fma_f32 v156, v32, v156, v146
	v_fma_f32 v157, v33, v157, v147
	v_lshlrev_b32_e32 v146, 16, v215
	v_and_b32_e32 v147, 0xffff0000, v215
	v_fma_f32 v158, v34, v158, v146
	v_fma_f32 v159, v35, v159, v147
	v_cvt_pk_bf16_f32 v182, v156, v157
	v_cvt_pk_bf16_f32 v183, v158, v159
	v_add_u32_e32 v161, 0x18000, v160
	global_store_dwordx4 v161, v[180:183], s[12:13] offset:256
	s_waitcnt vmcnt(10)
	v_lshlrev_b32_e32 v156, 16, v216
	v_and_b32_e32 v157, 0xffff0000, v216
	v_lshlrev_b32_e32 v158, 16, v217
	v_and_b32_e32 v159, 0xffff0000, v217
	v_add_f32_e32 v156, v96, v156
	v_add_f32_e32 v157, v97, v157
	v_add_f32_e32 v158, v98, v158
	v_add_f32_e32 v159, v99, v159
	v_mul_f32_e32 v156, 0xbfb8aa3b, v156
	v_mul_f32_e32 v157, 0xbfb8aa3b, v157
	v_mul_f32_e32 v158, 0xbfb8aa3b, v158
	v_mul_f32_e32 v159, 0xbfb8aa3b, v159
	v_exp_f32_e32 v156, v156
	v_exp_f32_e32 v157, v157
	v_exp_f32_e32 v158, v158
	v_exp_f32_e32 v159, v159
	v_add_f32_e32 v156, 1.0, v156
	v_add_f32_e32 v157, 1.0, v157
	v_add_f32_e32 v158, 1.0, v158
	v_add_f32_e32 v159, 1.0, v159
	v_rcp_f32_e32 v156, v156
	v_rcp_f32_e32 v157, v157
	v_rcp_f32_e32 v158, v158
	v_rcp_f32_e32 v159, v159
	v_lshlrev_b32_e32 v146, 16, v232
	v_and_b32_e32 v147, 0xffff0000, v232
	v_fma_f32 v156, v28, v156, v146
	v_fma_f32 v157, v29, v157, v147
	v_lshlrev_b32_e32 v146, 16, v233
	v_and_b32_e32 v147, 0xffff0000, v233
	v_fma_f32 v158, v30, v158, v146
	v_fma_f32 v159, v31, v159, v147
	v_cvt_pk_bf16_f32 v216, v156, v157
	v_cvt_pk_bf16_f32 v217, v158, v159
	v_lshlrev_b32_e32 v156, 16, v218
	v_and_b32_e32 v157, 0xffff0000, v218
	v_lshlrev_b32_e32 v158, 16, v219
	v_and_b32_e32 v159, 0xffff0000, v219
	v_add_f32_e32 v156, v100, v156
	v_add_f32_e32 v157, v101, v157
	v_add_f32_e32 v158, v102, v158
	v_add_f32_e32 v159, v103, v159
	v_mul_f32_e32 v156, 0xbfb8aa3b, v156
	v_mul_f32_e32 v157, 0xbfb8aa3b, v157
	v_mul_f32_e32 v158, 0xbfb8aa3b, v158
	v_mul_f32_e32 v159, 0xbfb8aa3b, v159
	v_exp_f32_e32 v156, v156
	v_exp_f32_e32 v157, v157
	v_exp_f32_e32 v158, v158
	v_exp_f32_e32 v159, v159
	v_add_f32_e32 v156, 1.0, v156
	v_add_f32_e32 v157, 1.0, v157
	v_add_f32_e32 v158, 1.0, v158
	v_add_f32_e32 v159, 1.0, v159
	v_rcp_f32_e32 v156, v156
	v_rcp_f32_e32 v157, v157
	v_rcp_f32_e32 v158, v158
	v_rcp_f32_e32 v159, v159
	v_lshlrev_b32_e32 v146, 16, v234
	v_and_b32_e32 v147, 0xffff0000, v234
	v_fma_f32 v156, v24, v156, v146
	v_fma_f32 v157, v25, v157, v147
	v_lshlrev_b32_e32 v146, 16, v235
	v_and_b32_e32 v147, 0xffff0000, v235
	v_fma_f32 v158, v26, v158, v146
	v_fma_f32 v159, v27, v159, v147
	v_cvt_pk_bf16_f32 v218, v156, v157
	v_cvt_pk_bf16_f32 v219, v158, v159
	v_add_u32_e32 v161, 0x40000, v160
	global_store_dwordx4 v161, v[216:219], s[12:13] offset:256
	s_waitcnt vmcnt(9)
	v_lshlrev_b32_e32 v156, 16, v220
	v_and_b32_e32 v157, 0xffff0000, v220
	v_lshlrev_b32_e32 v158, 16, v221
	v_and_b32_e32 v159, 0xffff0000, v221
	v_add_f32_e32 v156, v96, v156
	v_add_f32_e32 v157, v97, v157
	v_add_f32_e32 v158, v98, v158
	v_add_f32_e32 v159, v99, v159
	v_mul_f32_e32 v156, 0xbfb8aa3b, v156
	v_mul_f32_e32 v157, 0xbfb8aa3b, v157
	v_mul_f32_e32 v158, 0xbfb8aa3b, v158
	v_mul_f32_e32 v159, 0xbfb8aa3b, v159
	v_exp_f32_e32 v156, v156
	v_exp_f32_e32 v157, v157
	v_exp_f32_e32 v158, v158
	v_exp_f32_e32 v159, v159
	v_add_f32_e32 v156, 1.0, v156
	v_add_f32_e32 v157, 1.0, v157
	v_add_f32_e32 v158, 1.0, v158
	v_add_f32_e32 v159, 1.0, v159
	v_rcp_f32_e32 v156, v156
	v_rcp_f32_e32 v157, v157
	v_rcp_f32_e32 v158, v158
	v_rcp_f32_e32 v159, v159
	v_lshlrev_b32_e32 v146, 16, v248
	v_and_b32_e32 v147, 0xffff0000, v248
	v_fma_f32 v156, v20, v156, v146
	v_fma_f32 v157, v21, v157, v147
	v_lshlrev_b32_e32 v146, 16, v249
	v_and_b32_e32 v147, 0xffff0000, v249
	v_fma_f32 v158, v22, v158, v146
	v_fma_f32 v159, v23, v159, v147
	v_cvt_pk_bf16_f32 v220, v156, v157
	v_cvt_pk_bf16_f32 v221, v158, v159
	v_lshlrev_b32_e32 v156, 16, v222
	v_and_b32_e32 v157, 0xffff0000, v222
	v_lshlrev_b32_e32 v158, 16, v223
	v_and_b32_e32 v159, 0xffff0000, v223
	v_add_f32_e32 v156, v100, v156
	v_add_f32_e32 v157, v101, v157
	v_add_f32_e32 v158, v102, v158
	v_add_f32_e32 v159, v103, v159
	v_mul_f32_e32 v156, 0xbfb8aa3b, v156
	v_mul_f32_e32 v157, 0xbfb8aa3b, v157
	v_mul_f32_e32 v158, 0xbfb8aa3b, v158
	v_mul_f32_e32 v159, 0xbfb8aa3b, v159
	v_exp_f32_e32 v156, v156
	v_exp_f32_e32 v157, v157
	v_exp_f32_e32 v158, v158
	v_exp_f32_e32 v159, v159
	v_add_f32_e32 v156, 1.0, v156
	v_add_f32_e32 v157, 1.0, v157
	v_add_f32_e32 v158, 1.0, v158
	v_add_f32_e32 v159, 1.0, v159
	v_rcp_f32_e32 v156, v156
	v_rcp_f32_e32 v157, v157
	v_rcp_f32_e32 v158, v158
	v_rcp_f32_e32 v159, v159
	v_lshlrev_b32_e32 v146, 16, v250
	v_and_b32_e32 v147, 0xffff0000, v250
	v_fma_f32 v156, v16, v156, v146
	v_fma_f32 v157, v17, v157, v147
	v_lshlrev_b32_e32 v146, 16, v251
	v_and_b32_e32 v147, 0xffff0000, v251
	v_fma_f32 v158, v18, v158, v146
	v_fma_f32 v159, v19, v159, v147
	v_cvt_pk_bf16_f32 v222, v156, v157
	v_cvt_pk_bf16_f32 v223, v158, v159
	v_add_u32_e32 v161, 0x48000, v160
	global_store_dwordx4 v161, v[220:223], s[12:13] offset:256
	s_waitcnt vmcnt(8)
	v_lshlrev_b32_e32 v156, 16, v224
	v_and_b32_e32 v157, 0xffff0000, v224
	v_lshlrev_b32_e32 v158, 16, v225
	v_and_b32_e32 v159, 0xffff0000, v225
	v_add_f32_e32 v156, v96, v156
	v_add_f32_e32 v157, v97, v157
	v_add_f32_e32 v158, v98, v158
	v_add_f32_e32 v159, v99, v159
	v_mul_f32_e32 v156, 0xbfb8aa3b, v156
	v_mul_f32_e32 v157, 0xbfb8aa3b, v157
	v_mul_f32_e32 v158, 0xbfb8aa3b, v158
	v_mul_f32_e32 v159, 0xbfb8aa3b, v159
	v_exp_f32_e32 v156, v156
	v_exp_f32_e32 v157, v157
	v_exp_f32_e32 v158, v158
	v_exp_f32_e32 v159, v159
	v_add_f32_e32 v156, 1.0, v156
	v_add_f32_e32 v157, 1.0, v157
	v_add_f32_e32 v158, 1.0, v158
	v_add_f32_e32 v159, 1.0, v159
	v_rcp_f32_e32 v156, v156
	v_rcp_f32_e32 v157, v157
	v_rcp_f32_e32 v158, v158
	v_rcp_f32_e32 v159, v159
	v_lshlrev_b32_e32 v146, 16, v148
	v_and_b32_e32 v147, 0xffff0000, v148
	v_fma_f32 v156, v12, v156, v146
	v_fma_f32 v157, v13, v157, v147
	v_lshlrev_b32_e32 v146, 16, v149
	v_and_b32_e32 v147, 0xffff0000, v149
	v_fma_f32 v158, v14, v158, v146
	v_fma_f32 v159, v15, v159, v147
	v_cvt_pk_bf16_f32 v224, v156, v157
	v_cvt_pk_bf16_f32 v225, v158, v159
	v_lshlrev_b32_e32 v156, 16, v226
	v_and_b32_e32 v157, 0xffff0000, v226
	v_lshlrev_b32_e32 v158, 16, v227
	v_and_b32_e32 v159, 0xffff0000, v227
	v_add_f32_e32 v156, v100, v156
	v_add_f32_e32 v157, v101, v157
	v_add_f32_e32 v158, v102, v158
	v_add_f32_e32 v159, v103, v159
	v_mul_f32_e32 v156, 0xbfb8aa3b, v156
	v_mul_f32_e32 v157, 0xbfb8aa3b, v157
	v_mul_f32_e32 v158, 0xbfb8aa3b, v158
	v_mul_f32_e32 v159, 0xbfb8aa3b, v159
	v_exp_f32_e32 v156, v156
	v_exp_f32_e32 v157, v157
	v_exp_f32_e32 v158, v158
	v_exp_f32_e32 v159, v159
	v_add_f32_e32 v156, 1.0, v156
	v_add_f32_e32 v157, 1.0, v157
	v_add_f32_e32 v158, 1.0, v158
	v_add_f32_e32 v159, 1.0, v159
	v_rcp_f32_e32 v156, v156
	v_rcp_f32_e32 v157, v157
	v_rcp_f32_e32 v158, v158
	v_rcp_f32_e32 v159, v159
	v_lshlrev_b32_e32 v146, 16, v150
	v_and_b32_e32 v147, 0xffff0000, v150
	v_fma_f32 v156, v8, v156, v146
	v_fma_f32 v157, v9, v157, v147
	v_lshlrev_b32_e32 v146, 16, v151
	v_and_b32_e32 v147, 0xffff0000, v151
	v_fma_f32 v158, v10, v158, v146
	v_fma_f32 v159, v11, v159, v147
	v_cvt_pk_bf16_f32 v226, v156, v157
	v_cvt_pk_bf16_f32 v227, v158, v159
	v_add_u32_e32 v161, 0x50000, v160
	global_store_dwordx4 v161, v[224:227], s[12:13] offset:256
	s_waitcnt vmcnt(7)
	v_lshlrev_b32_e32 v156, 16, v228
	v_and_b32_e32 v157, 0xffff0000, v228
	v_lshlrev_b32_e32 v158, 16, v229
	v_and_b32_e32 v159, 0xffff0000, v229
	v_add_f32_e32 v156, v96, v156
	v_add_f32_e32 v157, v97, v157
	v_add_f32_e32 v158, v98, v158
	v_add_f32_e32 v159, v99, v159
	v_mul_f32_e32 v156, 0xbfb8aa3b, v156
	v_mul_f32_e32 v157, 0xbfb8aa3b, v157
	v_mul_f32_e32 v158, 0xbfb8aa3b, v158
	v_mul_f32_e32 v159, 0xbfb8aa3b, v159
	v_exp_f32_e32 v156, v156
	v_exp_f32_e32 v157, v157
	v_exp_f32_e32 v158, v158
	v_exp_f32_e32 v159, v159
	v_add_f32_e32 v156, 1.0, v156
	v_add_f32_e32 v157, 1.0, v157
	v_add_f32_e32 v158, 1.0, v158
	v_add_f32_e32 v159, 1.0, v159
	v_rcp_f32_e32 v156, v156
	v_rcp_f32_e32 v157, v157
	v_rcp_f32_e32 v158, v158
	v_rcp_f32_e32 v159, v159
	v_lshlrev_b32_e32 v146, 16, v152
	v_and_b32_e32 v147, 0xffff0000, v152
	v_fma_f32 v156, v4, v156, v146
	v_fma_f32 v157, v5, v157, v147
	v_lshlrev_b32_e32 v146, 16, v153
	v_and_b32_e32 v147, 0xffff0000, v153
	v_fma_f32 v158, v6, v158, v146
	v_fma_f32 v159, v7, v159, v147
	v_cvt_pk_bf16_f32 v228, v156, v157
	v_cvt_pk_bf16_f32 v229, v158, v159
	v_lshlrev_b32_e32 v156, 16, v230
	v_and_b32_e32 v157, 0xffff0000, v230
	v_lshlrev_b32_e32 v158, 16, v231
	v_and_b32_e32 v159, 0xffff0000, v231
	v_add_f32_e32 v156, v100, v156
	v_add_f32_e32 v157, v101, v157
	v_add_f32_e32 v158, v102, v158
	v_add_f32_e32 v159, v103, v159
	v_mul_f32_e32 v156, 0xbfb8aa3b, v156
	v_mul_f32_e32 v157, 0xbfb8aa3b, v157
	v_mul_f32_e32 v158, 0xbfb8aa3b, v158
	v_mul_f32_e32 v159, 0xbfb8aa3b, v159
	v_exp_f32_e32 v156, v156
	v_exp_f32_e32 v157, v157
	v_exp_f32_e32 v158, v158
	v_exp_f32_e32 v159, v159
	v_add_f32_e32 v156, 1.0, v156
	v_add_f32_e32 v157, 1.0, v157
	v_add_f32_e32 v158, 1.0, v158
	v_add_f32_e32 v159, 1.0, v159
	v_rcp_f32_e32 v156, v156
	v_rcp_f32_e32 v157, v157
	v_rcp_f32_e32 v158, v158
	v_rcp_f32_e32 v159, v159
	v_lshlrev_b32_e32 v146, 16, v154
	v_and_b32_e32 v147, 0xffff0000, v154
	v_fma_f32 v156, v0, v156, v146
	v_fma_f32 v157, v1, v157, v147
	v_lshlrev_b32_e32 v146, 16, v155
	v_and_b32_e32 v147, 0xffff0000, v155
	v_fma_f32 v158, v2, v158, v146
	v_fma_f32 v159, v3, v159, v147
	v_cvt_pk_bf16_f32 v230, v156, v157
	v_cvt_pk_bf16_f32 v231, v158, v159
	v_add_u32_e32 v161, 0x58000, v160
	global_store_dwordx4 v161, v[228:231], s[12:13] offset:256
	s_branch .LBB0_733
.LBB0_732:
	v_add_u32_e32 v162, v162, v146
	v_add_u32_e32 v160, v160, v146
	v_lshlrev_b32_e32 v164, 2, v164
	global_load_dwordx4 v[128:131], v164, s[70:71] offset:0
	global_load_dwordx4 v[132:135], v164, s[70:71] offset:16
	global_load_dwordx4 v[168:171], v162, s[28:29] offset:0
	v_add_u32_e32 v161, 0x10000, v162
	global_load_dwordx4 v[172:175], v161, s[28:29] offset:0
	v_add_u32_e32 v161, 0x20000, v162
	global_load_dwordx4 v[176:179], v161, s[28:29] offset:0
	v_add_u32_e32 v161, 0x30000, v162
	global_load_dwordx4 v[180:183], v161, s[28:29] offset:0
	v_add_u32_e32 v161, 0x80000, v162
	global_load_dwordx4 v[184:187], v161, s[28:29] offset:0
	v_add_u32_e32 v161, 0x90000, v162
	global_load_dwordx4 v[188:191], v161, s[28:29] offset:0
	v_add_u32_e32 v161, 0xa0000, v162
	global_load_dwordx4 v[208:211], v161, s[28:29] offset:0
	v_add_u32_e32 v161, 0xb0000, v162
	global_load_dwordx4 v[212:215], v161, s[28:29] offset:0
	global_load_dwordx4 v[216:219], v162, s[28:29] offset:256
	v_add_u32_e32 v161, 0x10000, v162
	global_load_dwordx4 v[220:223], v161, s[28:29] offset:256
	v_add_u32_e32 v161, 0x20000, v162
	global_load_dwordx4 v[224:227], v161, s[28:29] offset:256
	v_add_u32_e32 v161, 0x30000, v162
	global_load_dwordx4 v[228:231], v161, s[28:29] offset:256
	v_add_u32_e32 v161, 0x80000, v162
	global_load_dwordx4 v[232:235], v161, s[28:29] offset:256
	v_add_u32_e32 v161, 0x90000, v162
	global_load_dwordx4 v[248:251], v161, s[28:29] offset:256
	v_add_u32_e32 v161, 0xa0000, v162
	global_load_dwordx4 v[148:151], v161, s[28:29] offset:256
	v_add_u32_e32 v161, 0xb0000, v162
	global_load_dwordx4 v[152:155], v161, s[28:29] offset:256
	s_waitcnt vmcnt(15)
	v_lshlrev_b32_e32 v156, 16, v168
	v_and_b32_e32 v157, 0xffff0000, v168
	v_lshlrev_b32_e32 v158, 16, v169
	v_and_b32_e32 v159, 0xffff0000, v169
	v_add_f32_e32 v156, v128, v156
	v_add_f32_e32 v157, v129, v157
	v_add_f32_e32 v158, v130, v158
	v_add_f32_e32 v159, v131, v159
	v_mul_f32_e32 v156, 0xbfb8aa3b, v156
	v_mul_f32_e32 v157, 0xbfb8aa3b, v157
	v_mul_f32_e32 v158, 0xbfb8aa3b, v158
	v_mul_f32_e32 v159, 0xbfb8aa3b, v159
	v_exp_f32_e32 v156, v156
	v_exp_f32_e32 v157, v157
	v_exp_f32_e32 v158, v158
	v_exp_f32_e32 v159, v159
	v_add_f32_e32 v156, 1.0, v156
	v_add_f32_e32 v157, 1.0, v157
	v_add_f32_e32 v158, 1.0, v158
	v_add_f32_e32 v159, 1.0, v159
	v_rcp_f32_e32 v156, v156
	v_rcp_f32_e32 v157, v157
	v_rcp_f32_e32 v158, v158
	v_rcp_f32_e32 v159, v159
	s_nop 0
	v_mul_f32_e32 v156, v124, v156
	v_mul_f32_e32 v157, v125, v157
	v_mul_f32_e32 v158, v126, v158
	v_mul_f32_e32 v159, v127, v159
	v_cvt_pk_bf16_f32 v168, v156, v157
	v_cvt_pk_bf16_f32 v169, v158, v159
	v_lshlrev_b32_e32 v156, 16, v170
	v_and_b32_e32 v157, 0xffff0000, v170
	v_lshlrev_b32_e32 v158, 16, v171
	v_and_b32_e32 v159, 0xffff0000, v171
	v_add_f32_e32 v156, v132, v156
	v_add_f32_e32 v157, v133, v157
	v_add_f32_e32 v158, v134, v158
	v_add_f32_e32 v159, v135, v159
	v_mul_f32_e32 v156, 0xbfb8aa3b, v156
	v_mul_f32_e32 v157, 0xbfb8aa3b, v157
	v_mul_f32_e32 v158, 0xbfb8aa3b, v158
	v_mul_f32_e32 v159, 0xbfb8aa3b, v159
	v_exp_f32_e32 v156, v156
	v_exp_f32_e32 v157, v157
	v_exp_f32_e32 v158, v158
	v_exp_f32_e32 v159, v159
	v_add_f32_e32 v156, 1.0, v156
	v_add_f32_e32 v157, 1.0, v157
	v_add_f32_e32 v158, 1.0, v158
	v_add_f32_e32 v159, 1.0, v159
	v_rcp_f32_e32 v156, v156
	v_rcp_f32_e32 v157, v157
	v_rcp_f32_e32 v158, v158
	v_rcp_f32_e32 v159, v159
	s_nop 0
	v_mul_f32_e32 v156, v120, v156
	v_mul_f32_e32 v157, v121, v157
	v_mul_f32_e32 v158, v122, v158
	v_mul_f32_e32 v159, v123, v159
	v_cvt_pk_bf16_f32 v170, v156, v157
	v_cvt_pk_bf16_f32 v171, v158, v159
	global_store_dwordx4 v160, v[168:171], s[30:31] offset:0
	s_waitcnt vmcnt(15)
	v_lshlrev_b32_e32 v156, 16, v172
	v_and_b32_e32 v157, 0xffff0000, v172
	v_lshlrev_b32_e32 v158, 16, v173
	v_and_b32_e32 v159, 0xffff0000, v173
	v_add_f32_e32 v156, v128, v156
	v_add_f32_e32 v157, v129, v157
	v_add_f32_e32 v158, v130, v158
	v_add_f32_e32 v159, v131, v159
	v_mul_f32_e32 v156, 0xbfb8aa3b, v156
	v_mul_f32_e32 v157, 0xbfb8aa3b, v157
	v_mul_f32_e32 v158, 0xbfb8aa3b, v158
	v_mul_f32_e32 v159, 0xbfb8aa3b, v159
	v_exp_f32_e32 v156, v156
	v_exp_f32_e32 v157, v157
	v_exp_f32_e32 v158, v158
	v_exp_f32_e32 v159, v159
	v_add_f32_e32 v156, 1.0, v156
	v_add_f32_e32 v157, 1.0, v157
	v_add_f32_e32 v158, 1.0, v158
	v_add_f32_e32 v159, 1.0, v159
	v_rcp_f32_e32 v156, v156
	v_rcp_f32_e32 v157, v157
	v_rcp_f32_e32 v158, v158
	v_rcp_f32_e32 v159, v159
	s_nop 0
	v_mul_f32_e32 v156, v116, v156
	v_mul_f32_e32 v157, v117, v157
	v_mul_f32_e32 v158, v118, v158
	v_mul_f32_e32 v159, v119, v159
	v_cvt_pk_bf16_f32 v172, v156, v157
	v_cvt_pk_bf16_f32 v173, v158, v159
	v_lshlrev_b32_e32 v156, 16, v174
	v_and_b32_e32 v157, 0xffff0000, v174
	v_lshlrev_b32_e32 v158, 16, v175
	v_and_b32_e32 v159, 0xffff0000, v175
	v_add_f32_e32 v156, v132, v156
	v_add_f32_e32 v157, v133, v157
	v_add_f32_e32 v158, v134, v158
	v_add_f32_e32 v159, v135, v159
	v_mul_f32_e32 v156, 0xbfb8aa3b, v156
	v_mul_f32_e32 v157, 0xbfb8aa3b, v157
	v_mul_f32_e32 v158, 0xbfb8aa3b, v158
	v_mul_f32_e32 v159, 0xbfb8aa3b, v159
	v_exp_f32_e32 v156, v156
	v_exp_f32_e32 v157, v157
	v_exp_f32_e32 v158, v158
	v_exp_f32_e32 v159, v159
	v_add_f32_e32 v156, 1.0, v156
	v_add_f32_e32 v157, 1.0, v157
	v_add_f32_e32 v158, 1.0, v158
	v_add_f32_e32 v159, 1.0, v159
	v_rcp_f32_e32 v156, v156
	v_rcp_f32_e32 v157, v157
	v_rcp_f32_e32 v158, v158
	v_rcp_f32_e32 v159, v159
	s_nop 0
	v_mul_f32_e32 v156, v112, v156
	v_mul_f32_e32 v157, v113, v157
	v_mul_f32_e32 v158, v114, v158
	v_mul_f32_e32 v159, v115, v159
	v_cvt_pk_bf16_f32 v174, v156, v157
	v_cvt_pk_bf16_f32 v175, v158, v159
	v_add_u32_e32 v161, 0x8000, v160
	global_store_dwordx4 v161, v[172:175], s[30:31] offset:0
	s_waitcnt vmcnt(15)
	v_lshlrev_b32_e32 v156, 16, v176
	v_and_b32_e32 v157, 0xffff0000, v176
	v_lshlrev_b32_e32 v158, 16, v177
	v_and_b32_e32 v159, 0xffff0000, v177
	v_add_f32_e32 v156, v128, v156
	v_add_f32_e32 v157, v129, v157
	v_add_f32_e32 v158, v130, v158
	v_add_f32_e32 v159, v131, v159
	v_mul_f32_e32 v156, 0xbfb8aa3b, v156
	v_mul_f32_e32 v157, 0xbfb8aa3b, v157
	v_mul_f32_e32 v158, 0xbfb8aa3b, v158
	v_mul_f32_e32 v159, 0xbfb8aa3b, v159
	v_exp_f32_e32 v156, v156
	v_exp_f32_e32 v157, v157
	v_exp_f32_e32 v158, v158
	v_exp_f32_e32 v159, v159
	v_add_f32_e32 v156, 1.0, v156
	v_add_f32_e32 v157, 1.0, v157
	v_add_f32_e32 v158, 1.0, v158
	v_add_f32_e32 v159, 1.0, v159
	v_rcp_f32_e32 v156, v156
	v_rcp_f32_e32 v157, v157
	v_rcp_f32_e32 v158, v158
	v_rcp_f32_e32 v159, v159
	s_nop 0
	v_mul_f32_e32 v156, v108, v156
	v_mul_f32_e32 v157, v109, v157
	v_mul_f32_e32 v158, v110, v158
	v_mul_f32_e32 v159, v111, v159
	v_cvt_pk_bf16_f32 v176, v156, v157
	v_cvt_pk_bf16_f32 v177, v158, v159
	v_lshlrev_b32_e32 v156, 16, v178
	v_and_b32_e32 v157, 0xffff0000, v178
	v_lshlrev_b32_e32 v158, 16, v179
	v_and_b32_e32 v159, 0xffff0000, v179
	v_add_f32_e32 v156, v132, v156
	v_add_f32_e32 v157, v133, v157
	v_add_f32_e32 v158, v134, v158
	v_add_f32_e32 v159, v135, v159
	v_mul_f32_e32 v156, 0xbfb8aa3b, v156
	v_mul_f32_e32 v157, 0xbfb8aa3b, v157
	v_mul_f32_e32 v158, 0xbfb8aa3b, v158
	v_mul_f32_e32 v159, 0xbfb8aa3b, v159
	v_exp_f32_e32 v156, v156
	v_exp_f32_e32 v157, v157
	v_exp_f32_e32 v158, v158
	v_exp_f32_e32 v159, v159
	v_add_f32_e32 v156, 1.0, v156
	v_add_f32_e32 v157, 1.0, v157
	v_add_f32_e32 v158, 1.0, v158
	v_add_f32_e32 v159, 1.0, v159
	v_rcp_f32_e32 v156, v156
	v_rcp_f32_e32 v157, v157
	v_rcp_f32_e32 v158, v158
	v_rcp_f32_e32 v159, v159
	s_nop 0
	v_mul_f32_e32 v156, v104, v156
	v_mul_f32_e32 v157, v105, v157
	v_mul_f32_e32 v158, v106, v158
	v_mul_f32_e32 v159, v107, v159
	v_cvt_pk_bf16_f32 v178, v156, v157
	v_cvt_pk_bf16_f32 v179, v158, v159
	v_add_u32_e32 v161, 0x10000, v160
	global_store_dwordx4 v161, v[176:179], s[30:31] offset:0
	s_waitcnt vmcnt(15)
	v_lshlrev_b32_e32 v156, 16, v180
	v_and_b32_e32 v157, 0xffff0000, v180
	v_lshlrev_b32_e32 v158, 16, v181
	v_and_b32_e32 v159, 0xffff0000, v181
	v_add_f32_e32 v156, v128, v156
	v_add_f32_e32 v157, v129, v157
	v_add_f32_e32 v158, v130, v158
	v_add_f32_e32 v159, v131, v159
	v_mul_f32_e32 v156, 0xbfb8aa3b, v156
	v_mul_f32_e32 v157, 0xbfb8aa3b, v157
	v_mul_f32_e32 v158, 0xbfb8aa3b, v158
	v_mul_f32_e32 v159, 0xbfb8aa3b, v159
	v_exp_f32_e32 v156, v156
	v_exp_f32_e32 v157, v157
	v_exp_f32_e32 v158, v158
	v_exp_f32_e32 v159, v159
	v_add_f32_e32 v156, 1.0, v156
	v_add_f32_e32 v157, 1.0, v157
	v_add_f32_e32 v158, 1.0, v158
	v_add_f32_e32 v159, 1.0, v159
	v_rcp_f32_e32 v156, v156
	v_rcp_f32_e32 v157, v157
	v_rcp_f32_e32 v158, v158
	v_rcp_f32_e32 v159, v159
	s_nop 0
	v_mul_f32_e32 v156, v100, v156
	v_mul_f32_e32 v157, v101, v157
	v_mul_f32_e32 v158, v102, v158
	v_mul_f32_e32 v159, v103, v159
	v_cvt_pk_bf16_f32 v180, v156, v157
	v_cvt_pk_bf16_f32 v181, v158, v159
	v_lshlrev_b32_e32 v156, 16, v182
	v_and_b32_e32 v157, 0xffff0000, v182
	v_lshlrev_b32_e32 v158, 16, v183
	v_and_b32_e32 v159, 0xffff0000, v183
	v_add_f32_e32 v156, v132, v156
	v_add_f32_e32 v157, v133, v157
	v_add_f32_e32 v158, v134, v158
	v_add_f32_e32 v159, v135, v159
	v_mul_f32_e32 v156, 0xbfb8aa3b, v156
	v_mul_f32_e32 v157, 0xbfb8aa3b, v157
	v_mul_f32_e32 v158, 0xbfb8aa3b, v158
	v_mul_f32_e32 v159, 0xbfb8aa3b, v159
	v_exp_f32_e32 v156, v156
	v_exp_f32_e32 v157, v157
	v_exp_f32_e32 v158, v158
	v_exp_f32_e32 v159, v159
	v_add_f32_e32 v156, 1.0, v156
	v_add_f32_e32 v157, 1.0, v157
	v_add_f32_e32 v158, 1.0, v158
	v_add_f32_e32 v159, 1.0, v159
	v_rcp_f32_e32 v156, v156
	v_rcp_f32_e32 v157, v157
	v_rcp_f32_e32 v158, v158
	v_rcp_f32_e32 v159, v159
	s_nop 0
	v_mul_f32_e32 v156, v96, v156
	v_mul_f32_e32 v157, v97, v157
	v_mul_f32_e32 v158, v98, v158
	v_mul_f32_e32 v159, v99, v159
	v_cvt_pk_bf16_f32 v182, v156, v157
	v_cvt_pk_bf16_f32 v183, v158, v159
	v_add_u32_e32 v161, 0x18000, v160
	global_store_dwordx4 v161, v[180:183], s[30:31] offset:0
	global_load_dwordx4 v[96:99], v164, s[70:71] offset:512
	global_load_dwordx4 v[100:103], v164, s[70:71] offset:528
	s_waitcnt vmcnt(17)
	v_lshlrev_b32_e32 v156, 16, v184
	v_and_b32_e32 v157, 0xffff0000, v184
	v_lshlrev_b32_e32 v158, 16, v185
	v_and_b32_e32 v159, 0xffff0000, v185
	v_add_f32_e32 v156, v128, v156
	v_add_f32_e32 v157, v129, v157
	v_add_f32_e32 v158, v130, v158
	v_add_f32_e32 v159, v131, v159
	v_mul_f32_e32 v156, 0xbfb8aa3b, v156
	v_mul_f32_e32 v157, 0xbfb8aa3b, v157
	v_mul_f32_e32 v158, 0xbfb8aa3b, v158
	v_mul_f32_e32 v159, 0xbfb8aa3b, v159
	v_exp_f32_e32 v156, v156
	v_exp_f32_e32 v157, v157
	v_exp_f32_e32 v158, v158
	v_exp_f32_e32 v159, v159
	v_add_f32_e32 v156, 1.0, v156
	v_add_f32_e32 v157, 1.0, v157
	v_add_f32_e32 v158, 1.0, v158
	v_add_f32_e32 v159, 1.0, v159
	v_rcp_f32_e32 v156, v156
	v_rcp_f32_e32 v157, v157
	v_rcp_f32_e32 v158, v158
	v_rcp_f32_e32 v159, v159
	s_nop 0
	v_mul_f32_e32 v156, v92, v156
	v_mul_f32_e32 v157, v93, v157
	v_mul_f32_e32 v158, v94, v158
	v_mul_f32_e32 v159, v95, v159
	v_cvt_pk_bf16_f32 v184, v156, v157
	v_cvt_pk_bf16_f32 v185, v158, v159
	v_lshlrev_b32_e32 v156, 16, v186
	v_and_b32_e32 v157, 0xffff0000, v186
	v_lshlrev_b32_e32 v158, 16, v187
	v_and_b32_e32 v159, 0xffff0000, v187
	v_add_f32_e32 v156, v132, v156
	v_add_f32_e32 v157, v133, v157
	v_add_f32_e32 v158, v134, v158
	v_add_f32_e32 v159, v135, v159
	v_mul_f32_e32 v156, 0xbfb8aa3b, v156
	v_mul_f32_e32 v157, 0xbfb8aa3b, v157
	v_mul_f32_e32 v158, 0xbfb8aa3b, v158
	v_mul_f32_e32 v159, 0xbfb8aa3b, v159
	v_exp_f32_e32 v156, v156
	v_exp_f32_e32 v157, v157
	v_exp_f32_e32 v158, v158
	v_exp_f32_e32 v159, v159
	v_add_f32_e32 v156, 1.0, v156
	v_add_f32_e32 v157, 1.0, v157
	v_add_f32_e32 v158, 1.0, v158
	v_add_f32_e32 v159, 1.0, v159
	v_rcp_f32_e32 v156, v156
	v_rcp_f32_e32 v157, v157
	v_rcp_f32_e32 v158, v158
	v_rcp_f32_e32 v159, v159
	s_nop 0
	v_mul_f32_e32 v156, v88, v156
	v_mul_f32_e32 v157, v89, v157
	v_mul_f32_e32 v158, v90, v158
	v_mul_f32_e32 v159, v91, v159
	v_cvt_pk_bf16_f32 v186, v156, v157
	v_cvt_pk_bf16_f32 v187, v158, v159
	v_add_u32_e32 v161, 0x40000, v160
	global_store_dwordx4 v161, v[184:187], s[30:31] offset:0
	s_waitcnt vmcnt(17)
	v_lshlrev_b32_e32 v156, 16, v188
	v_and_b32_e32 v157, 0xffff0000, v188
	v_lshlrev_b32_e32 v158, 16, v189
	v_and_b32_e32 v159, 0xffff0000, v189
	v_add_f32_e32 v156, v128, v156
	v_add_f32_e32 v157, v129, v157
	v_add_f32_e32 v158, v130, v158
	v_add_f32_e32 v159, v131, v159
	v_mul_f32_e32 v156, 0xbfb8aa3b, v156
	v_mul_f32_e32 v157, 0xbfb8aa3b, v157
	v_mul_f32_e32 v158, 0xbfb8aa3b, v158
	v_mul_f32_e32 v159, 0xbfb8aa3b, v159
	v_exp_f32_e32 v156, v156
	v_exp_f32_e32 v157, v157
	v_exp_f32_e32 v158, v158
	v_exp_f32_e32 v159, v159
	v_add_f32_e32 v156, 1.0, v156
	v_add_f32_e32 v157, 1.0, v157
	v_add_f32_e32 v158, 1.0, v158
	v_add_f32_e32 v159, 1.0, v159
	v_rcp_f32_e32 v156, v156
	v_rcp_f32_e32 v157, v157
	v_rcp_f32_e32 v158, v158
	v_rcp_f32_e32 v159, v159
	s_nop 0
	v_mul_f32_e32 v156, v84, v156
	v_mul_f32_e32 v157, v85, v157
	v_mul_f32_e32 v158, v86, v158
	v_mul_f32_e32 v159, v87, v159
	v_cvt_pk_bf16_f32 v188, v156, v157
	v_cvt_pk_bf16_f32 v189, v158, v159
	v_lshlrev_b32_e32 v156, 16, v190
	v_and_b32_e32 v157, 0xffff0000, v190
	v_lshlrev_b32_e32 v158, 16, v191
	v_and_b32_e32 v159, 0xffff0000, v191
	v_add_f32_e32 v156, v132, v156
	v_add_f32_e32 v157, v133, v157
	v_add_f32_e32 v158, v134, v158
	v_add_f32_e32 v159, v135, v159
	v_mul_f32_e32 v156, 0xbfb8aa3b, v156
	v_mul_f32_e32 v157, 0xbfb8aa3b, v157
	v_mul_f32_e32 v158, 0xbfb8aa3b, v158
	v_mul_f32_e32 v159, 0xbfb8aa3b, v159
	v_exp_f32_e32 v156, v156
	v_exp_f32_e32 v157, v157
	v_exp_f32_e32 v158, v158
	v_exp_f32_e32 v159, v159
	v_add_f32_e32 v156, 1.0, v156
	v_add_f32_e32 v157, 1.0, v157
	v_add_f32_e32 v158, 1.0, v158
	v_add_f32_e32 v159, 1.0, v159
	v_rcp_f32_e32 v156, v156
	v_rcp_f32_e32 v157, v157
	v_rcp_f32_e32 v158, v158
	v_rcp_f32_e32 v159, v159
	s_nop 0
	v_mul_f32_e32 v156, v80, v156
	v_mul_f32_e32 v157, v81, v157
	v_mul_f32_e32 v158, v82, v158
	v_mul_f32_e32 v159, v83, v159
	v_cvt_pk_bf16_f32 v190, v156, v157
	v_cvt_pk_bf16_f32 v191, v158, v159
	v_add_u32_e32 v161, 0x48000, v160
	global_store_dwordx4 v161, v[188:191], s[30:31] offset:0
	s_waitcnt vmcnt(17)
	v_lshlrev_b32_e32 v156, 16, v208
	v_and_b32_e32 v157, 0xffff0000, v208
	v_lshlrev_b32_e32 v158, 16, v209
	v_and_b32_e32 v159, 0xffff0000, v209
	v_add_f32_e32 v156, v128, v156
	v_add_f32_e32 v157, v129, v157
	v_add_f32_e32 v158, v130, v158
	v_add_f32_e32 v159, v131, v159
	v_mul_f32_e32 v156, 0xbfb8aa3b, v156
	v_mul_f32_e32 v157, 0xbfb8aa3b, v157
	v_mul_f32_e32 v158, 0xbfb8aa3b, v158
	v_mul_f32_e32 v159, 0xbfb8aa3b, v159
	v_exp_f32_e32 v156, v156
	v_exp_f32_e32 v157, v157
	v_exp_f32_e32 v158, v158
	v_exp_f32_e32 v159, v159
	v_add_f32_e32 v156, 1.0, v156
	v_add_f32_e32 v157, 1.0, v157
	v_add_f32_e32 v158, 1.0, v158
	v_add_f32_e32 v159, 1.0, v159
	v_rcp_f32_e32 v156, v156
	v_rcp_f32_e32 v157, v157
	v_rcp_f32_e32 v158, v158
	v_rcp_f32_e32 v159, v159
	s_nop 0
	v_mul_f32_e32 v156, v76, v156
	v_mul_f32_e32 v157, v77, v157
	v_mul_f32_e32 v158, v78, v158
	v_mul_f32_e32 v159, v79, v159
	v_cvt_pk_bf16_f32 v208, v156, v157
	v_cvt_pk_bf16_f32 v209, v158, v159
	v_lshlrev_b32_e32 v156, 16, v210
	v_and_b32_e32 v157, 0xffff0000, v210
	v_lshlrev_b32_e32 v158, 16, v211
	v_and_b32_e32 v159, 0xffff0000, v211
	v_add_f32_e32 v156, v132, v156
	v_add_f32_e32 v157, v133, v157
	v_add_f32_e32 v158, v134, v158
	v_add_f32_e32 v159, v135, v159
	v_mul_f32_e32 v156, 0xbfb8aa3b, v156
	v_mul_f32_e32 v157, 0xbfb8aa3b, v157
	v_mul_f32_e32 v158, 0xbfb8aa3b, v158
	v_mul_f32_e32 v159, 0xbfb8aa3b, v159
	v_exp_f32_e32 v156, v156
	v_exp_f32_e32 v157, v157
	v_exp_f32_e32 v158, v158
	v_exp_f32_e32 v159, v159
	v_add_f32_e32 v156, 1.0, v156
	v_add_f32_e32 v157, 1.0, v157
	v_add_f32_e32 v158, 1.0, v158
	v_add_f32_e32 v159, 1.0, v159
	v_rcp_f32_e32 v156, v156
	v_rcp_f32_e32 v157, v157
	v_rcp_f32_e32 v158, v158
	v_rcp_f32_e32 v159, v159
	s_nop 0
	v_mul_f32_e32 v156, v72, v156
	v_mul_f32_e32 v157, v73, v157
	v_mul_f32_e32 v158, v74, v158
	v_mul_f32_e32 v159, v75, v159
	v_cvt_pk_bf16_f32 v210, v156, v157
	v_cvt_pk_bf16_f32 v211, v158, v159
	v_add_u32_e32 v161, 0x50000, v160
	global_store_dwordx4 v161, v[208:211], s[30:31] offset:0
	s_waitcnt vmcnt(17)
	v_lshlrev_b32_e32 v156, 16, v212
	v_and_b32_e32 v157, 0xffff0000, v212
	v_lshlrev_b32_e32 v158, 16, v213
	v_and_b32_e32 v159, 0xffff0000, v213
	v_add_f32_e32 v156, v128, v156
	v_add_f32_e32 v157, v129, v157
	v_add_f32_e32 v158, v130, v158
	v_add_f32_e32 v159, v131, v159
	v_mul_f32_e32 v156, 0xbfb8aa3b, v156
	v_mul_f32_e32 v157, 0xbfb8aa3b, v157
	v_mul_f32_e32 v158, 0xbfb8aa3b, v158
	v_mul_f32_e32 v159, 0xbfb8aa3b, v159
	v_exp_f32_e32 v156, v156
	v_exp_f32_e32 v157, v157
	v_exp_f32_e32 v158, v158
	v_exp_f32_e32 v159, v159
	v_add_f32_e32 v156, 1.0, v156
	v_add_f32_e32 v157, 1.0, v157
	v_add_f32_e32 v158, 1.0, v158
	v_add_f32_e32 v159, 1.0, v159
	v_rcp_f32_e32 v156, v156
	v_rcp_f32_e32 v157, v157
	v_rcp_f32_e32 v158, v158
	v_rcp_f32_e32 v159, v159
	s_nop 0
	v_mul_f32_e32 v156, v68, v156
	v_mul_f32_e32 v157, v69, v157
	v_mul_f32_e32 v158, v70, v158
	v_mul_f32_e32 v159, v71, v159
	v_cvt_pk_bf16_f32 v212, v156, v157
	v_cvt_pk_bf16_f32 v213, v158, v159
	v_lshlrev_b32_e32 v156, 16, v214
	v_and_b32_e32 v157, 0xffff0000, v214
	v_lshlrev_b32_e32 v158, 16, v215
	v_and_b32_e32 v159, 0xffff0000, v215
	v_add_f32_e32 v156, v132, v156
	v_add_f32_e32 v157, v133, v157
	v_add_f32_e32 v158, v134, v158
	v_add_f32_e32 v159, v135, v159
	v_mul_f32_e32 v156, 0xbfb8aa3b, v156
	v_mul_f32_e32 v157, 0xbfb8aa3b, v157
	v_mul_f32_e32 v158, 0xbfb8aa3b, v158
	v_mul_f32_e32 v159, 0xbfb8aa3b, v159
	v_exp_f32_e32 v156, v156
	v_exp_f32_e32 v157, v157
	v_exp_f32_e32 v158, v158
	v_exp_f32_e32 v159, v159
	v_add_f32_e32 v156, 1.0, v156
	v_add_f32_e32 v157, 1.0, v157
	v_add_f32_e32 v158, 1.0, v158
	v_add_f32_e32 v159, 1.0, v159
	v_rcp_f32_e32 v156, v156
	v_rcp_f32_e32 v157, v157
	v_rcp_f32_e32 v158, v158
	v_rcp_f32_e32 v159, v159
	s_nop 0
	v_mul_f32_e32 v156, v64, v156
	v_mul_f32_e32 v157, v65, v157
	v_mul_f32_e32 v158, v66, v158
	v_mul_f32_e32 v159, v67, v159
	v_cvt_pk_bf16_f32 v214, v156, v157
	v_cvt_pk_bf16_f32 v215, v158, v159
	v_add_u32_e32 v161, 0x58000, v160
	global_store_dwordx4 v161, v[212:215], s[30:31] offset:0
	s_waitcnt vmcnt(4)
	v_lshlrev_b32_e32 v156, 16, v216
	v_and_b32_e32 v157, 0xffff0000, v216
	v_lshlrev_b32_e32 v158, 16, v217
	v_and_b32_e32 v159, 0xffff0000, v217
	v_add_f32_e32 v156, v96, v156
	v_add_f32_e32 v157, v97, v157
	v_add_f32_e32 v158, v98, v158
	v_add_f32_e32 v159, v99, v159
	v_mul_f32_e32 v156, 0xbfb8aa3b, v156
	v_mul_f32_e32 v157, 0xbfb8aa3b, v157
	v_mul_f32_e32 v158, 0xbfb8aa3b, v158
	v_mul_f32_e32 v159, 0xbfb8aa3b, v159
	v_exp_f32_e32 v156, v156
	v_exp_f32_e32 v157, v157
	v_exp_f32_e32 v158, v158
	v_exp_f32_e32 v159, v159
	v_add_f32_e32 v156, 1.0, v156
	v_add_f32_e32 v157, 1.0, v157
	v_add_f32_e32 v158, 1.0, v158
	v_add_f32_e32 v159, 1.0, v159
	v_rcp_f32_e32 v156, v156
	v_rcp_f32_e32 v157, v157
	v_rcp_f32_e32 v158, v158
	v_rcp_f32_e32 v159, v159
	s_nop 0
	v_mul_f32_e32 v156, v60, v156
	v_mul_f32_e32 v157, v61, v157
	v_mul_f32_e32 v158, v62, v158
	v_mul_f32_e32 v159, v63, v159
	v_cvt_pk_bf16_f32 v216, v156, v157
	v_cvt_pk_bf16_f32 v217, v158, v159
	v_lshlrev_b32_e32 v156, 16, v218
	v_and_b32_e32 v157, 0xffff0000, v218
	v_lshlrev_b32_e32 v158, 16, v219
	v_and_b32_e32 v159, 0xffff0000, v219
	v_add_f32_e32 v156, v100, v156
	v_add_f32_e32 v157, v101, v157
	v_add_f32_e32 v158, v102, v158
	v_add_f32_e32 v159, v103, v159
	v_mul_f32_e32 v156, 0xbfb8aa3b, v156
	v_mul_f32_e32 v157, 0xbfb8aa3b, v157
	v_mul_f32_e32 v158, 0xbfb8aa3b, v158
	v_mul_f32_e32 v159, 0xbfb8aa3b, v159
	v_exp_f32_e32 v156, v156
	v_exp_f32_e32 v157, v157
	v_exp_f32_e32 v158, v158
	v_exp_f32_e32 v159, v159
	v_add_f32_e32 v156, 1.0, v156
	v_add_f32_e32 v157, 1.0, v157
	v_add_f32_e32 v158, 1.0, v158
	v_add_f32_e32 v159, 1.0, v159
	v_rcp_f32_e32 v156, v156
	v_rcp_f32_e32 v157, v157
	v_rcp_f32_e32 v158, v158
	v_rcp_f32_e32 v159, v159
	s_nop 0
	v_mul_f32_e32 v156, v56, v156
	v_mul_f32_e32 v157, v57, v157
	v_mul_f32_e32 v158, v58, v158
	v_mul_f32_e32 v159, v59, v159
	v_cvt_pk_bf16_f32 v218, v156, v157
	v_cvt_pk_bf16_f32 v219, v158, v159
	global_store_dwordx4 v160, v[216:219], s[30:31] offset:256
	v_lshlrev_b32_e32 v156, 16, v220
	v_and_b32_e32 v157, 0xffff0000, v220
	v_lshlrev_b32_e32 v158, 16, v221
	v_and_b32_e32 v159, 0xffff0000, v221
	v_add_f32_e32 v156, v96, v156
	v_add_f32_e32 v157, v97, v157
	v_add_f32_e32 v158, v98, v158
	v_add_f32_e32 v159, v99, v159
	v_mul_f32_e32 v156, 0xbfb8aa3b, v156
	v_mul_f32_e32 v157, 0xbfb8aa3b, v157
	v_mul_f32_e32 v158, 0xbfb8aa3b, v158
	v_mul_f32_e32 v159, 0xbfb8aa3b, v159
	v_exp_f32_e32 v156, v156
	v_exp_f32_e32 v157, v157
	v_exp_f32_e32 v158, v158
	v_exp_f32_e32 v159, v159
	v_add_f32_e32 v156, 1.0, v156
	v_add_f32_e32 v157, 1.0, v157
	v_add_f32_e32 v158, 1.0, v158
	v_add_f32_e32 v159, 1.0, v159
	v_rcp_f32_e32 v156, v156
	v_rcp_f32_e32 v157, v157
	v_rcp_f32_e32 v158, v158
	v_rcp_f32_e32 v159, v159
	s_nop 0
	v_mul_f32_e32 v156, v52, v156
	v_mul_f32_e32 v157, v53, v157
	v_mul_f32_e32 v158, v54, v158
	v_mul_f32_e32 v159, v55, v159
	v_cvt_pk_bf16_f32 v220, v156, v157
	v_cvt_pk_bf16_f32 v221, v158, v159
	v_lshlrev_b32_e32 v156, 16, v222
	v_and_b32_e32 v157, 0xffff0000, v222
	v_lshlrev_b32_e32 v158, 16, v223
	v_and_b32_e32 v159, 0xffff0000, v223
	v_add_f32_e32 v156, v100, v156
	v_add_f32_e32 v157, v101, v157
	v_add_f32_e32 v158, v102, v158
	v_add_f32_e32 v159, v103, v159
	v_mul_f32_e32 v156, 0xbfb8aa3b, v156
	v_mul_f32_e32 v157, 0xbfb8aa3b, v157
	v_mul_f32_e32 v158, 0xbfb8aa3b, v158
	v_mul_f32_e32 v159, 0xbfb8aa3b, v159
	v_exp_f32_e32 v156, v156
	v_exp_f32_e32 v157, v157
	v_exp_f32_e32 v158, v158
	v_exp_f32_e32 v159, v159
	v_add_f32_e32 v156, 1.0, v156
	v_add_f32_e32 v157, 1.0, v157
	v_add_f32_e32 v158, 1.0, v158
	v_add_f32_e32 v159, 1.0, v159
	v_rcp_f32_e32 v156, v156
	v_rcp_f32_e32 v157, v157
	v_rcp_f32_e32 v158, v158
	v_rcp_f32_e32 v159, v159
	s_nop 0
	v_mul_f32_e32 v156, v48, v156
	v_mul_f32_e32 v157, v49, v157
	v_mul_f32_e32 v158, v50, v158
	v_mul_f32_e32 v159, v51, v159
	v_cvt_pk_bf16_f32 v222, v156, v157
	v_cvt_pk_bf16_f32 v223, v158, v159
	v_add_u32_e32 v161, 0x8000, v160
	global_store_dwordx4 v161, v[220:223], s[30:31] offset:256
	v_lshlrev_b32_e32 v156, 16, v224
	v_and_b32_e32 v157, 0xffff0000, v224
	v_lshlrev_b32_e32 v158, 16, v225
	v_and_b32_e32 v159, 0xffff0000, v225
	v_add_f32_e32 v156, v96, v156
	v_add_f32_e32 v157, v97, v157
	v_add_f32_e32 v158, v98, v158
	v_add_f32_e32 v159, v99, v159
	v_mul_f32_e32 v156, 0xbfb8aa3b, v156
	v_mul_f32_e32 v157, 0xbfb8aa3b, v157
	v_mul_f32_e32 v158, 0xbfb8aa3b, v158
	v_mul_f32_e32 v159, 0xbfb8aa3b, v159
	v_exp_f32_e32 v156, v156
	v_exp_f32_e32 v157, v157
	v_exp_f32_e32 v158, v158
	v_exp_f32_e32 v159, v159
	v_add_f32_e32 v156, 1.0, v156
	v_add_f32_e32 v157, 1.0, v157
	v_add_f32_e32 v158, 1.0, v158
	v_add_f32_e32 v159, 1.0, v159
	v_rcp_f32_e32 v156, v156
	v_rcp_f32_e32 v157, v157
	v_rcp_f32_e32 v158, v158
	v_rcp_f32_e32 v159, v159
	s_nop 0
	v_mul_f32_e32 v156, v44, v156
	v_mul_f32_e32 v157, v45, v157
	v_mul_f32_e32 v158, v46, v158
	v_mul_f32_e32 v159, v47, v159
	v_cvt_pk_bf16_f32 v224, v156, v157
	v_cvt_pk_bf16_f32 v225, v158, v159
	v_lshlrev_b32_e32 v156, 16, v226
	v_and_b32_e32 v157, 0xffff0000, v226
	v_lshlrev_b32_e32 v158, 16, v227
	v_and_b32_e32 v159, 0xffff0000, v227
	v_add_f32_e32 v156, v100, v156
	v_add_f32_e32 v157, v101, v157
	v_add_f32_e32 v158, v102, v158
	v_add_f32_e32 v159, v103, v159
	v_mul_f32_e32 v156, 0xbfb8aa3b, v156
	v_mul_f32_e32 v157, 0xbfb8aa3b, v157
	v_mul_f32_e32 v158, 0xbfb8aa3b, v158
	v_mul_f32_e32 v159, 0xbfb8aa3b, v159
	v_exp_f32_e32 v156, v156
	v_exp_f32_e32 v157, v157
	v_exp_f32_e32 v158, v158
	v_exp_f32_e32 v159, v159
	v_add_f32_e32 v156, 1.0, v156
	v_add_f32_e32 v157, 1.0, v157
	v_add_f32_e32 v158, 1.0, v158
	v_add_f32_e32 v159, 1.0, v159
	v_rcp_f32_e32 v156, v156
	v_rcp_f32_e32 v157, v157
	v_rcp_f32_e32 v158, v158
	v_rcp_f32_e32 v159, v159
	s_nop 0
	v_mul_f32_e32 v156, v40, v156
	v_mul_f32_e32 v157, v41, v157
	v_mul_f32_e32 v158, v42, v158
	v_mul_f32_e32 v159, v43, v159
	v_cvt_pk_bf16_f32 v226, v156, v157
	v_cvt_pk_bf16_f32 v227, v158, v159
	v_add_u32_e32 v161, 0x10000, v160
	global_store_dwordx4 v161, v[224:227], s[30:31] offset:256
	v_lshlrev_b32_e32 v156, 16, v228
	v_and_b32_e32 v157, 0xffff0000, v228
	v_lshlrev_b32_e32 v158, 16, v229
	v_and_b32_e32 v159, 0xffff0000, v229
	v_add_f32_e32 v156, v96, v156
	v_add_f32_e32 v157, v97, v157
	v_add_f32_e32 v158, v98, v158
	v_add_f32_e32 v159, v99, v159
	v_mul_f32_e32 v156, 0xbfb8aa3b, v156
	v_mul_f32_e32 v157, 0xbfb8aa3b, v157
	v_mul_f32_e32 v158, 0xbfb8aa3b, v158
	v_mul_f32_e32 v159, 0xbfb8aa3b, v159
	v_exp_f32_e32 v156, v156
	v_exp_f32_e32 v157, v157
	v_exp_f32_e32 v158, v158
	v_exp_f32_e32 v159, v159
	v_add_f32_e32 v156, 1.0, v156
	v_add_f32_e32 v157, 1.0, v157
	v_add_f32_e32 v158, 1.0, v158
	v_add_f32_e32 v159, 1.0, v159
	v_rcp_f32_e32 v156, v156
	v_rcp_f32_e32 v157, v157
	v_rcp_f32_e32 v158, v158
	v_rcp_f32_e32 v159, v159
	s_nop 0
	v_mul_f32_e32 v156, v36, v156
	v_mul_f32_e32 v157, v37, v157
	v_mul_f32_e32 v158, v38, v158
	v_mul_f32_e32 v159, v39, v159
	v_cvt_pk_bf16_f32 v228, v156, v157
	v_cvt_pk_bf16_f32 v229, v158, v159
	v_lshlrev_b32_e32 v156, 16, v230
	v_and_b32_e32 v157, 0xffff0000, v230
	v_lshlrev_b32_e32 v158, 16, v231
	v_and_b32_e32 v159, 0xffff0000, v231
	v_add_f32_e32 v156, v100, v156
	v_add_f32_e32 v157, v101, v157
	v_add_f32_e32 v158, v102, v158
	v_add_f32_e32 v159, v103, v159
	v_mul_f32_e32 v156, 0xbfb8aa3b, v156
	v_mul_f32_e32 v157, 0xbfb8aa3b, v157
	v_mul_f32_e32 v158, 0xbfb8aa3b, v158
	v_mul_f32_e32 v159, 0xbfb8aa3b, v159
	v_exp_f32_e32 v156, v156
	v_exp_f32_e32 v157, v157
	v_exp_f32_e32 v158, v158
	v_exp_f32_e32 v159, v159
	v_add_f32_e32 v156, 1.0, v156
	v_add_f32_e32 v157, 1.0, v157
	v_add_f32_e32 v158, 1.0, v158
	v_add_f32_e32 v159, 1.0, v159
	v_rcp_f32_e32 v156, v156
	v_rcp_f32_e32 v157, v157
	v_rcp_f32_e32 v158, v158
	v_rcp_f32_e32 v159, v159
	s_nop 0
	v_mul_f32_e32 v156, v32, v156
	v_mul_f32_e32 v157, v33, v157
	v_mul_f32_e32 v158, v34, v158
	v_mul_f32_e32 v159, v35, v159
	v_cvt_pk_bf16_f32 v230, v156, v157
	v_cvt_pk_bf16_f32 v231, v158, v159
	v_add_u32_e32 v161, 0x18000, v160
	global_store_dwordx4 v161, v[228:231], s[30:31] offset:256
	v_lshlrev_b32_e32 v156, 16, v232
	v_and_b32_e32 v157, 0xffff0000, v232
	v_lshlrev_b32_e32 v158, 16, v233
	v_and_b32_e32 v159, 0xffff0000, v233
	v_add_f32_e32 v156, v96, v156
	v_add_f32_e32 v157, v97, v157
	v_add_f32_e32 v158, v98, v158
	v_add_f32_e32 v159, v99, v159
	v_mul_f32_e32 v156, 0xbfb8aa3b, v156
	v_mul_f32_e32 v157, 0xbfb8aa3b, v157
	v_mul_f32_e32 v158, 0xbfb8aa3b, v158
	v_mul_f32_e32 v159, 0xbfb8aa3b, v159
	v_exp_f32_e32 v156, v156
	v_exp_f32_e32 v157, v157
	v_exp_f32_e32 v158, v158
	v_exp_f32_e32 v159, v159
	v_add_f32_e32 v156, 1.0, v156
	v_add_f32_e32 v157, 1.0, v157
	v_add_f32_e32 v158, 1.0, v158
	v_add_f32_e32 v159, 1.0, v159
	v_rcp_f32_e32 v156, v156
	v_rcp_f32_e32 v157, v157
	v_rcp_f32_e32 v158, v158
	v_rcp_f32_e32 v159, v159
	s_nop 0
	v_mul_f32_e32 v156, v28, v156
	v_mul_f32_e32 v157, v29, v157
	v_mul_f32_e32 v158, v30, v158
	v_mul_f32_e32 v159, v31, v159
	v_cvt_pk_bf16_f32 v232, v156, v157
	v_cvt_pk_bf16_f32 v233, v158, v159
	v_lshlrev_b32_e32 v156, 16, v234
	v_and_b32_e32 v157, 0xffff0000, v234
	v_lshlrev_b32_e32 v158, 16, v235
	v_and_b32_e32 v159, 0xffff0000, v235
	v_add_f32_e32 v156, v100, v156
	v_add_f32_e32 v157, v101, v157
	v_add_f32_e32 v158, v102, v158
	v_add_f32_e32 v159, v103, v159
	v_mul_f32_e32 v156, 0xbfb8aa3b, v156
	v_mul_f32_e32 v157, 0xbfb8aa3b, v157
	v_mul_f32_e32 v158, 0xbfb8aa3b, v158
	v_mul_f32_e32 v159, 0xbfb8aa3b, v159
	v_exp_f32_e32 v156, v156
	v_exp_f32_e32 v157, v157
	v_exp_f32_e32 v158, v158
	v_exp_f32_e32 v159, v159
	v_add_f32_e32 v156, 1.0, v156
	v_add_f32_e32 v157, 1.0, v157
	v_add_f32_e32 v158, 1.0, v158
	v_add_f32_e32 v159, 1.0, v159
	v_rcp_f32_e32 v156, v156
	v_rcp_f32_e32 v157, v157
	v_rcp_f32_e32 v158, v158
	v_rcp_f32_e32 v159, v159
	s_nop 0
	v_mul_f32_e32 v156, v24, v156
	v_mul_f32_e32 v157, v25, v157
	v_mul_f32_e32 v158, v26, v158
	v_mul_f32_e32 v159, v27, v159
	v_cvt_pk_bf16_f32 v234, v156, v157
	v_cvt_pk_bf16_f32 v235, v158, v159
	v_add_u32_e32 v161, 0x40000, v160
	global_store_dwordx4 v161, v[232:235], s[30:31] offset:256
	v_lshlrev_b32_e32 v156, 16, v248
	v_and_b32_e32 v157, 0xffff0000, v248
	v_lshlrev_b32_e32 v158, 16, v249
	v_and_b32_e32 v159, 0xffff0000, v249
	v_add_f32_e32 v156, v96, v156
	v_add_f32_e32 v157, v97, v157
	v_add_f32_e32 v158, v98, v158
	v_add_f32_e32 v159, v99, v159
	v_mul_f32_e32 v156, 0xbfb8aa3b, v156
	v_mul_f32_e32 v157, 0xbfb8aa3b, v157
	v_mul_f32_e32 v158, 0xbfb8aa3b, v158
	v_mul_f32_e32 v159, 0xbfb8aa3b, v159
	v_exp_f32_e32 v156, v156
	v_exp_f32_e32 v157, v157
	v_exp_f32_e32 v158, v158
	v_exp_f32_e32 v159, v159
	v_add_f32_e32 v156, 1.0, v156
	v_add_f32_e32 v157, 1.0, v157
	v_add_f32_e32 v158, 1.0, v158
	v_add_f32_e32 v159, 1.0, v159
	v_rcp_f32_e32 v156, v156
	v_rcp_f32_e32 v157, v157
	v_rcp_f32_e32 v158, v158
	v_rcp_f32_e32 v159, v159
	s_nop 0
	v_mul_f32_e32 v156, v20, v156
	v_mul_f32_e32 v157, v21, v157
	v_mul_f32_e32 v158, v22, v158
	v_mul_f32_e32 v159, v23, v159
	v_cvt_pk_bf16_f32 v248, v156, v157
	v_cvt_pk_bf16_f32 v249, v158, v159
	v_lshlrev_b32_e32 v156, 16, v250
	v_and_b32_e32 v157, 0xffff0000, v250
	v_lshlrev_b32_e32 v158, 16, v251
	v_and_b32_e32 v159, 0xffff0000, v251
	v_add_f32_e32 v156, v100, v156
	v_add_f32_e32 v157, v101, v157
	v_add_f32_e32 v158, v102, v158
	v_add_f32_e32 v159, v103, v159
	v_mul_f32_e32 v156, 0xbfb8aa3b, v156
	v_mul_f32_e32 v157, 0xbfb8aa3b, v157
	v_mul_f32_e32 v158, 0xbfb8aa3b, v158
	v_mul_f32_e32 v159, 0xbfb8aa3b, v159
	v_exp_f32_e32 v156, v156
	v_exp_f32_e32 v157, v157
	v_exp_f32_e32 v158, v158
	v_exp_f32_e32 v159, v159
	v_add_f32_e32 v156, 1.0, v156
	v_add_f32_e32 v157, 1.0, v157
	v_add_f32_e32 v158, 1.0, v158
	v_add_f32_e32 v159, 1.0, v159
	v_rcp_f32_e32 v156, v156
	v_rcp_f32_e32 v157, v157
	v_rcp_f32_e32 v158, v158
	v_rcp_f32_e32 v159, v159
	s_nop 0
	v_mul_f32_e32 v156, v16, v156
	v_mul_f32_e32 v157, v17, v157
	v_mul_f32_e32 v158, v18, v158
	v_mul_f32_e32 v159, v19, v159
	v_cvt_pk_bf16_f32 v250, v156, v157
	v_cvt_pk_bf16_f32 v251, v158, v159
	v_add_u32_e32 v161, 0x48000, v160
	global_store_dwordx4 v161, v[248:251], s[30:31] offset:256
	v_lshlrev_b32_e32 v156, 16, v148
	v_and_b32_e32 v157, 0xffff0000, v148
	v_lshlrev_b32_e32 v158, 16, v149
	v_and_b32_e32 v159, 0xffff0000, v149
	v_add_f32_e32 v156, v96, v156
	v_add_f32_e32 v157, v97, v157
	v_add_f32_e32 v158, v98, v158
	v_add_f32_e32 v159, v99, v159
	v_mul_f32_e32 v156, 0xbfb8aa3b, v156
	v_mul_f32_e32 v157, 0xbfb8aa3b, v157
	v_mul_f32_e32 v158, 0xbfb8aa3b, v158
	v_mul_f32_e32 v159, 0xbfb8aa3b, v159
	v_exp_f32_e32 v156, v156
	v_exp_f32_e32 v157, v157
	v_exp_f32_e32 v158, v158
	v_exp_f32_e32 v159, v159
	v_add_f32_e32 v156, 1.0, v156
	v_add_f32_e32 v157, 1.0, v157
	v_add_f32_e32 v158, 1.0, v158
	v_add_f32_e32 v159, 1.0, v159
	v_rcp_f32_e32 v156, v156
	v_rcp_f32_e32 v157, v157
	v_rcp_f32_e32 v158, v158
	v_rcp_f32_e32 v159, v159
	s_nop 0
	v_mul_f32_e32 v156, v12, v156
	v_mul_f32_e32 v157, v13, v157
	v_mul_f32_e32 v158, v14, v158
	v_mul_f32_e32 v159, v15, v159
	v_cvt_pk_bf16_f32 v148, v156, v157
	v_cvt_pk_bf16_f32 v149, v158, v159
	v_lshlrev_b32_e32 v156, 16, v150
	v_and_b32_e32 v157, 0xffff0000, v150
	v_lshlrev_b32_e32 v158, 16, v151
	v_and_b32_e32 v159, 0xffff0000, v151
	v_add_f32_e32 v156, v100, v156
	v_add_f32_e32 v157, v101, v157
	v_add_f32_e32 v158, v102, v158
	v_add_f32_e32 v159, v103, v159
	v_mul_f32_e32 v156, 0xbfb8aa3b, v156
	v_mul_f32_e32 v157, 0xbfb8aa3b, v157
	v_mul_f32_e32 v158, 0xbfb8aa3b, v158
	v_mul_f32_e32 v159, 0xbfb8aa3b, v159
	v_exp_f32_e32 v156, v156
	v_exp_f32_e32 v157, v157
	v_exp_f32_e32 v158, v158
	v_exp_f32_e32 v159, v159
	v_add_f32_e32 v156, 1.0, v156
	v_add_f32_e32 v157, 1.0, v157
	v_add_f32_e32 v158, 1.0, v158
	v_add_f32_e32 v159, 1.0, v159
	v_rcp_f32_e32 v156, v156
	v_rcp_f32_e32 v157, v157
	v_rcp_f32_e32 v158, v158
	v_rcp_f32_e32 v159, v159
	s_nop 0
	v_mul_f32_e32 v156, v8, v156
	v_mul_f32_e32 v157, v9, v157
	v_mul_f32_e32 v158, v10, v158
	v_mul_f32_e32 v159, v11, v159
	v_cvt_pk_bf16_f32 v150, v156, v157
	v_cvt_pk_bf16_f32 v151, v158, v159
	v_add_u32_e32 v161, 0x50000, v160
	global_store_dwordx4 v161, v[148:151], s[30:31] offset:256
	v_lshlrev_b32_e32 v156, 16, v152
	v_and_b32_e32 v157, 0xffff0000, v152
	v_lshlrev_b32_e32 v158, 16, v153
	v_and_b32_e32 v159, 0xffff0000, v153
	v_add_f32_e32 v156, v96, v156
	v_add_f32_e32 v157, v97, v157
	v_add_f32_e32 v158, v98, v158
	v_add_f32_e32 v159, v99, v159
	v_mul_f32_e32 v156, 0xbfb8aa3b, v156
	v_mul_f32_e32 v157, 0xbfb8aa3b, v157
	v_mul_f32_e32 v158, 0xbfb8aa3b, v158
	v_mul_f32_e32 v159, 0xbfb8aa3b, v159
	v_exp_f32_e32 v156, v156
	v_exp_f32_e32 v157, v157
	v_exp_f32_e32 v158, v158
	v_exp_f32_e32 v159, v159
	v_add_f32_e32 v156, 1.0, v156
	v_add_f32_e32 v157, 1.0, v157
	v_add_f32_e32 v158, 1.0, v158
	v_add_f32_e32 v159, 1.0, v159
	v_rcp_f32_e32 v156, v156
	v_rcp_f32_e32 v157, v157
	v_rcp_f32_e32 v158, v158
	v_rcp_f32_e32 v159, v159
	s_nop 0
	v_mul_f32_e32 v156, v4, v156
	v_mul_f32_e32 v157, v5, v157
	v_mul_f32_e32 v158, v6, v158
	v_mul_f32_e32 v159, v7, v159
	v_cvt_pk_bf16_f32 v152, v156, v157
	v_cvt_pk_bf16_f32 v153, v158, v159
	v_lshlrev_b32_e32 v156, 16, v154
	v_and_b32_e32 v157, 0xffff0000, v154
	v_lshlrev_b32_e32 v158, 16, v155
	v_and_b32_e32 v159, 0xffff0000, v155
	v_add_f32_e32 v156, v100, v156
	v_add_f32_e32 v157, v101, v157
	v_add_f32_e32 v158, v102, v158
	v_add_f32_e32 v159, v103, v159
	v_mul_f32_e32 v156, 0xbfb8aa3b, v156
	v_mul_f32_e32 v157, 0xbfb8aa3b, v157
	v_mul_f32_e32 v158, 0xbfb8aa3b, v158
	v_mul_f32_e32 v159, 0xbfb8aa3b, v159
	v_exp_f32_e32 v156, v156
	v_exp_f32_e32 v157, v157
	v_exp_f32_e32 v158, v158
	v_exp_f32_e32 v159, v159
	v_add_f32_e32 v156, 1.0, v156
	v_add_f32_e32 v157, 1.0, v157
	v_add_f32_e32 v158, 1.0, v158
	v_add_f32_e32 v159, 1.0, v159
	v_rcp_f32_e32 v156, v156
	v_rcp_f32_e32 v157, v157
	v_rcp_f32_e32 v158, v158
	v_rcp_f32_e32 v159, v159
	s_nop 0
	v_mul_f32_e32 v156, v0, v156
	v_mul_f32_e32 v157, v1, v157
	v_mul_f32_e32 v158, v2, v158
	v_mul_f32_e32 v159, v3, v159
	v_cvt_pk_bf16_f32 v154, v156, v157
	v_cvt_pk_bf16_f32 v155, v158, v159
	v_add_u32_e32 v161, 0x58000, v160
	global_store_dwordx4 v161, v[152:155], s[30:31] offset:256
	s_branch .LBB0_733
